# prompt attention: all 8 K/V staging loads issued before the LDS writes; QK tiles regenerated with next-tile K-fragment prefetch and the 4 bias LDS reads of a tile issued together; generic fallback for
# speedup vs baseline: 1.0180x; 1.0057x over previous
.LBB0_115:
	s_bfe_u32 s24, s22, 0x60001
	s_lshl_b32 s25, s24, 7
	s_and_b32 s23, s22, 1
	s_add_i32 s26, s25, 0xffffff80
	s_ashr_i32 s2, s22, 7
	s_lshl_b32 s88, s23, 7
	v_add_u32_e32 v3, s26, v67
	s_lshl_b32 s3, s2, 13
	v_lshl_add_u64 v[16:17], v[20:21], 0, s[88:89]
	v_cmp_lt_i32_e32 vcc, -1, v3
	v_mov_b32_e32 v6, 0
	v_mov_b32_e32 v2, 0
	v_mov_b32_e32 v8, 0
	v_mov_b32_e32 v9, 0
	v_mov_b32_e32 v10, 0
	v_mov_b32_e32 v11, 0
	v_mov_b32_e32 v12, 0
	v_mov_b32_e32 v13, 0
	v_mov_b32_e32 v14, 0
	v_mov_b32_e32 v15, 0
	s_barrier
	v_add_u32_e32 v238, s26, v67
	v_cmp_lt_i32_e32 vcc, -1, v238
	v_mov_b32_e32 v206, 0
	v_mov_b32_e32 v207, 0
	v_mov_b32_e32 v208, 0
	v_mov_b32_e32 v209, 0
	v_mov_b32_e32 v210, 0
	v_mov_b32_e32 v211, 0
	v_mov_b32_e32 v212, 0
	v_mov_b32_e32 v213, 0
	v_add_u32_e32 v240, s3, v238
	v_ashrrev_i32_e32 v241, 31, v240
	v_lshlrev_b64 v[240:241], 9, v[240:241]
	v_lshl_add_u64 v[240:241], v[16:17], 0, v[240:241]
	s_and_saveexec_b64 s[8:9], vcc
	global_load_dwordx4 v[206:209], v[240:241], off
	global_load_dwordx4 v[210:213], v[240:241], off offset:256
	s_or_b64 exec, exec, s[8:9]
	v_add_u32_e32 v238, s26, v70
	v_cmp_lt_i32_e32 vcc, -1, v238
	v_mov_b32_e32 v214, 0
	v_mov_b32_e32 v215, 0
	v_mov_b32_e32 v216, 0
	v_mov_b32_e32 v217, 0
	v_mov_b32_e32 v218, 0
	v_mov_b32_e32 v219, 0
	v_mov_b32_e32 v220, 0
	v_mov_b32_e32 v221, 0
	v_add_u32_e32 v240, s3, v238
	v_ashrrev_i32_e32 v241, 31, v240
	v_lshlrev_b64 v[240:241], 9, v[240:241]
	v_lshl_add_u64 v[240:241], v[16:17], 0, v[240:241]
	s_and_saveexec_b64 s[8:9], vcc
	global_load_dwordx4 v[214:217], v[240:241], off
	global_load_dwordx4 v[218:221], v[240:241], off offset:256
	s_or_b64 exec, exec, s[8:9]
	v_add_u32_e32 v238, s26, v72
	v_cmp_lt_i32_e32 vcc, -1, v238
	v_mov_b32_e32 v222, 0
	v_mov_b32_e32 v223, 0
	v_mov_b32_e32 v224, 0
	v_mov_b32_e32 v225, 0
	v_mov_b32_e32 v226, 0
	v_mov_b32_e32 v227, 0
	v_mov_b32_e32 v228, 0
	v_mov_b32_e32 v229, 0
	v_add_u32_e32 v240, s3, v238
	v_ashrrev_i32_e32 v241, 31, v240
	v_lshlrev_b64 v[240:241], 9, v[240:241]
	v_lshl_add_u64 v[240:241], v[16:17], 0, v[240:241]
	s_and_saveexec_b64 s[8:9], vcc
	global_load_dwordx4 v[222:225], v[240:241], off
	global_load_dwordx4 v[226:229], v[240:241], off offset:256
	s_or_b64 exec, exec, s[8:9]
	v_add_u32_e32 v238, s26, v74
	v_cmp_lt_i32_e32 vcc, -1, v238
	v_mov_b32_e32 v6, 0
	v_mov_b32_e32 v7, 0
	v_mov_b32_e32 v8, 0
	v_mov_b32_e32 v9, 0
	v_mov_b32_e32 v2, 0
	v_mov_b32_e32 v3, 0
	v_mov_b32_e32 v4, 0
	v_mov_b32_e32 v5, 0
	v_add_u32_e32 v240, s3, v238
	v_ashrrev_i32_e32 v241, 31, v240
	v_lshlrev_b64 v[240:241], 9, v[240:241]
	v_lshl_add_u64 v[240:241], v[16:17], 0, v[240:241]
	s_and_saveexec_b64 s[8:9], vcc
	global_load_dwordx4 v[6:9], v[240:241], off
	global_load_dwordx4 v[2:5], v[240:241], off offset:256
	s_or_b64 exec, exec, s[8:9]
	s_mov_b32 s28, 0
	s_waitcnt vmcnt(7)
	ds_write_b128 v128, v[206:209]
	s_waitcnt vmcnt(6)
	ds_write_b16 v68, v210 offset:36864
	ds_write_b16_d16_hi v68, v210 offset:37392
	ds_write_b16 v68, v211 offset:37920
	ds_write_b16_d16_hi v68, v211 offset:38448
	ds_write_b16 v68, v212 offset:38976
	ds_write_b16_d16_hi v68, v212 offset:39504
	ds_write_b16 v68, v213 offset:40032
	ds_write_b16_d16_hi v68, v213 offset:40560
	s_waitcnt vmcnt(5)
	ds_write_b128 v129, v[214:217]
	s_waitcnt vmcnt(4)
	ds_write_b16 v71, v218 offset:36864
	ds_write_b16_d16_hi v71, v218 offset:37392
	ds_write_b16 v71, v219 offset:37920
	ds_write_b16_d16_hi v71, v219 offset:38448
	ds_write_b16 v71, v220 offset:38976
	ds_write_b16_d16_hi v71, v220 offset:39504
	ds_write_b16 v71, v221 offset:40032
	ds_write_b16_d16_hi v71, v221 offset:40560
	s_waitcnt vmcnt(3)
	ds_write_b128 v130, v[222:225]
	s_waitcnt vmcnt(2)
	ds_write_b16 v73, v226 offset:36864
	ds_write_b16_d16_hi v73, v226 offset:37392
	ds_write_b16 v73, v227 offset:37920
	ds_write_b16_d16_hi v73, v227 offset:38448
	ds_write_b16 v73, v228 offset:38976
	ds_write_b16_d16_hi v73, v228 offset:39504
	ds_write_b16 v73, v229 offset:40032
	ds_write_b16_d16_hi v73, v229 offset:40560
	v_cndmask_b32_e64 v14, 0, 1, s[42:43]
	s_nop 0
	v_readfirstlane_b32 s3, v14
	s_lshl_b32 s3, s3, 3
	s_add_i32 s88, s19, s3
	s_lshl_b64 s[46:47], s[88:89], 2
	s_lshl_b32 s88, s23, 10
	v_add_u32_e32 v10, s88, v204
	v_ashrrev_i32_e32 v11, 31, v10
	v_add_u32_e32 v12, s88, v69
	v_lshl_add_u64 v[10:11], v[10:11], 2, s[0:1]
	v_ashrrev_i32_e32 v13, 31, v12
	v_lshl_add_u64 v[12:13], v[12:13], 2, s[0:1]
	global_load_dword v10, v[10:11], off
	s_nop 0
	global_load_dword v11, v[12:13], off
	s_ashr_i32 s3, s2, 31
	s_lshl_b64 s[2:3], s[2:3], 13
	s_or_b32 s8, s2, s25
	s_mov_b32 s9, s3
	s_waitcnt vmcnt(3)
	ds_write_b128 v131, v[6:9]
	s_waitcnt vmcnt(2)
	ds_write_b16 v75, v2 offset:36864
	ds_write_b16_d16_hi v75, v2 offset:37392
	ds_write_b16 v75, v3 offset:37920
	ds_write_b16_d16_hi v75, v3 offset:38448
	ds_write_b16 v75, v4 offset:38976
	ds_write_b16_d16_hi v75, v4 offset:39504
	ds_write_b16 v75, v5 offset:40032
	ds_write_b16_d16_hi v75, v5 offset:40560
	v_lshl_add_u64 v[6:7], s[8:9], 0, v[22:23]
	v_lshlrev_b64 v[2:3], 11, v[6:7]
	v_lshl_add_u64 v[2:3], s[14:15], 0, v[2:3]
	v_lshl_add_u64 v[2:3], v[2:3], 0, s[88:89]
	v_lshl_add_u64 v[8:9], v[2:3], 0, v[0:1]
	s_lshr_b32 s8, s22, 1
	s_and_b32 s8, s8, 63
	s_lshl_b32 s8, s8, 7
	s_cmp_eq_u32 s24, 0
	s_cselect_b64 s[38:39], -1, 0
	s_or_b32 s2, s2, s8
	v_lshlrev_b64 v[30:31], 10, v[6:7]
	v_lshl_add_u64 v[6:7], s[2:3], 0, v[22:23]
	v_lshlrev_b64 v[6:7], 11, v[6:7]
	v_lshl_or_b32 v6, v14, 10, v6
	v_lshl_add_u64 v[32:33], v[26:27], 0, v[6:7]
	v_lshl_add_u64 v[34:35], v[28:29], 0, v[6:7]
	s_waitcnt vmcnt(1)
	ds_write_b32 v76, v10
	s_waitcnt vmcnt(0)
	ds_write_b32 v77, v11
	s_waitcnt lgkmcnt(0)
	s_barrier
	global_load_dwordx4 v[2:5], v[8:9], off
	global_load_dwordx4 v[10:13], v[8:9], off offset:64
.LBB0_124:
	s_waitcnt vmcnt(1)
	v_mov_b64_e32 v[16:17], v[4:5]
	v_mov_b32_e32 v36, v22
	v_mov_b64_e32 v[14:15], v[2:3]
	global_load_dwordx4 v[2:5], v[32:33], off offset:-64
	global_load_dwordx4 v[6:9], v[32:33], off
	s_load_dwordx2 s[48:49], s[80:81], 0xd0
	v_cndmask_b32_e64 v41, v195, v36, s[38:39]
	v_add_u32_e32 v46, 0x80, v36
	v_lshl_add_u64 v[32:33], v[32:33], 0, s[94:95]
	s_waitcnt lgkmcnt(0)
	s_add_u32 s2, s48, s46
	s_addc_u32 s3, s49, s47
	global_load_dword v40, v1, s[2:3]
	s_add_i32 s2, s28, 0
	s_add_i32 s2, s2, 0x11400
	s_addk_i32 s28, 0x200
	s_add_u32 s46, s46, 4
	s_addc_u32 s47, s47, 0
	s_cmpk_eq_i32 s28, 0xe00
	ds_read_b128 v[214:217], v78
	ds_read_b128 v[218:221], v78 offset:64
	v_sub_u32_e32 v206, v46, v79
	v_sub_u32_e32 v210, v41, v206
	v_or_b32_e32 v210, v210, v206
	v_and_b32_e32 v206, 0x7f, v206
	v_lshl_add_u32 v206, v206, 2, s2
	ds_read_b32 v206, v206
	v_sub_u32_e32 v207, v46, v80
	v_sub_u32_e32 v211, v41, v207
	v_or_b32_e32 v211, v211, v207
	v_and_b32_e32 v207, 0x7f, v207
	v_lshl_add_u32 v207, v207, 2, s2
	ds_read_b32 v207, v207
	v_sub_u32_e32 v208, v46, v81
	v_sub_u32_e32 v212, v41, v208
	v_or_b32_e32 v212, v212, v208
	v_and_b32_e32 v208, 0x7f, v208
	v_lshl_add_u32 v208, v208, 2, s2
	ds_read_b32 v208, v208
	v_sub_u32_e32 v209, v46, v82
	v_sub_u32_e32 v213, v41, v209
	v_or_b32_e32 v213, v213, v209
	v_and_b32_e32 v209, 0x7f, v209
	v_lshl_add_u32 v209, v209, 2, s2
	ds_read_b32 v209, v209
	ds_read_b128 v[222:225], v83
	ds_read_b128 v[226:229], v83 offset:64
	s_waitcnt vmcnt(3) lgkmcnt(6)
	v_mfma_f32_16x16x32_bf16 v[230:233], v[214:217], v[14:17], 0
	v_mfma_f32_16x16x32_bf16 v[230:233], v[218:221], v[10:13], v[230:233]
	v_ashrrev_i32_e32 v210, 31, v210
	v_and_b32_e32 v210, 0xff800000, v210
	v_ashrrev_i32_e32 v211, 31, v211
	v_and_b32_e32 v211, 0xff800000, v211
	v_ashrrev_i32_e32 v212, 31, v212
	v_and_b32_e32 v212, 0xff800000, v212
	v_ashrrev_i32_e32 v213, 31, v213
	v_and_b32_e32 v213, 0xff800000, v213
	s_nop 1
	s_waitcnt lgkmcnt(2)
	v_add_f32_e32 v234, v230, v206
	v_add_f32_e32 v47, v234, v210
	v_add_f32_e32 v234, v231, v207
	v_add_f32_e32 v48, v234, v211
	v_add_f32_e32 v234, v232, v208
	v_add_f32_e32 v49, v234, v212
	v_add_f32_e32 v234, v233, v209
	v_add_f32_e32 v50, v234, v213
	v_max3_f32 v36, v47, s96, v48
	v_max3_f32 v51, v36, v49, v50
	v_sub_u32_e32 v206, v46, v84
	v_sub_u32_e32 v210, v41, v206
	v_or_b32_e32 v210, v210, v206
	v_and_b32_e32 v206, 0x7f, v206
	v_lshl_add_u32 v206, v206, 2, s2
	ds_read_b32 v206, v206
	v_sub_u32_e32 v207, v46, v85
	v_sub_u32_e32 v211, v41, v207
	v_or_b32_e32 v211, v211, v207
	v_and_b32_e32 v207, 0x7f, v207
	v_lshl_add_u32 v207, v207, 2, s2
	ds_read_b32 v207, v207
	v_sub_u32_e32 v208, v46, v86
	v_sub_u32_e32 v212, v41, v208
	v_or_b32_e32 v212, v212, v208
	v_and_b32_e32 v208, 0x7f, v208
	v_lshl_add_u32 v208, v208, 2, s2
	ds_read_b32 v208, v208
	v_sub_u32_e32 v209, v46, v87
	v_sub_u32_e32 v213, v41, v209
	v_or_b32_e32 v213, v213, v209
	v_and_b32_e32 v209, 0x7f, v209
	v_lshl_add_u32 v209, v209, 2, s2
	ds_read_b32 v209, v209
	ds_read_b128 v[214:217], v88
	ds_read_b128 v[218:221], v88 offset:64
	s_waitcnt lgkmcnt(6)
	v_mfma_f32_16x16x32_bf16 v[230:233], v[222:225], v[14:17], 0
	v_mfma_f32_16x16x32_bf16 v[230:233], v[226:229], v[10:13], v[230:233]
	v_ashrrev_i32_e32 v210, 31, v210
	v_and_b32_e32 v210, 0xff800000, v210
	v_ashrrev_i32_e32 v211, 31, v211
	v_and_b32_e32 v211, 0xff800000, v211
	v_ashrrev_i32_e32 v212, 31, v212
	v_and_b32_e32 v212, 0xff800000, v212
	v_ashrrev_i32_e32 v213, 31, v213
	v_and_b32_e32 v213, 0xff800000, v213
	s_nop 1
	s_waitcnt lgkmcnt(2)
	v_add_f32_e32 v234, v230, v206
	v_add_f32_e32 v52, v234, v210
	v_add_f32_e32 v234, v231, v207
	v_add_f32_e32 v53, v234, v211
	v_add_f32_e32 v234, v232, v208
	v_add_f32_e32 v51, v234, v212
	v_add_f32_e32 v234, v233, v209
	v_add_f32_e32 v54, v234, v213
	v_max3_f32 v36, v51, v52, v53
	v_max3_f32 v55, v36, v51, v54
	v_sub_u32_e32 v206, v46, v89
	v_sub_u32_e32 v210, v41, v206
	v_or_b32_e32 v210, v210, v206
	v_and_b32_e32 v206, 0x7f, v206
	v_lshl_add_u32 v206, v206, 2, s2
	ds_read_b32 v206, v206
	v_sub_u32_e32 v207, v46, v90
	v_sub_u32_e32 v211, v41, v207
	v_or_b32_e32 v211, v211, v207
	v_and_b32_e32 v207, 0x7f, v207
	v_lshl_add_u32 v207, v207, 2, s2
	ds_read_b32 v207, v207
	v_sub_u32_e32 v208, v46, v91
	v_sub_u32_e32 v212, v41, v208
	v_or_b32_e32 v212, v212, v208
	v_and_b32_e32 v208, 0x7f, v208
	v_lshl_add_u32 v208, v208, 2, s2
	ds_read_b32 v208, v208
	v_sub_u32_e32 v209, v46, v92
	v_sub_u32_e32 v213, v41, v209
	v_or_b32_e32 v213, v213, v209
	v_and_b32_e32 v209, 0x7f, v209
	v_lshl_add_u32 v209, v209, 2, s2
	ds_read_b32 v209, v209
	ds_read_b128 v[222:225], v93
	ds_read_b128 v[226:229], v93 offset:64
	s_waitcnt lgkmcnt(6)
	v_mfma_f32_16x16x32_bf16 v[230:233], v[214:217], v[14:17], 0
	v_mfma_f32_16x16x32_bf16 v[230:233], v[218:221], v[10:13], v[230:233]
	v_ashrrev_i32_e32 v210, 31, v210
	v_and_b32_e32 v210, 0xff800000, v210
	v_ashrrev_i32_e32 v211, 31, v211
	v_and_b32_e32 v211, 0xff800000, v211
	v_ashrrev_i32_e32 v212, 31, v212
	v_and_b32_e32 v212, 0xff800000, v212
	v_ashrrev_i32_e32 v213, 31, v213
	v_and_b32_e32 v213, 0xff800000, v213
	s_nop 1
	s_waitcnt lgkmcnt(2)
	v_add_f32_e32 v234, v230, v206
	v_add_f32_e32 v56, v234, v210
	v_add_f32_e32 v234, v231, v207
	v_add_f32_e32 v57, v234, v211
	v_add_f32_e32 v234, v232, v208
	v_add_f32_e32 v55, v234, v212
	v_add_f32_e32 v234, v233, v209
	v_add_f32_e32 v61, v234, v213
	v_max3_f32 v36, v55, v56, v57
	v_max3_f32 v58, v36, v55, v61
	v_sub_u32_e32 v206, v46, v94
	v_sub_u32_e32 v210, v41, v206
	v_or_b32_e32 v210, v210, v206
	v_and_b32_e32 v206, 0x7f, v206
	v_lshl_add_u32 v206, v206, 2, s2
	ds_read_b32 v206, v206
	v_sub_u32_e32 v207, v46, v95
	v_sub_u32_e32 v211, v41, v207
	v_or_b32_e32 v211, v211, v207
	v_and_b32_e32 v207, 0x7f, v207
	v_lshl_add_u32 v207, v207, 2, s2
	ds_read_b32 v207, v207
	v_sub_u32_e32 v208, v46, v96
	v_sub_u32_e32 v212, v41, v208
	v_or_b32_e32 v212, v212, v208
	v_and_b32_e32 v208, 0x7f, v208
	v_lshl_add_u32 v208, v208, 2, s2
	ds_read_b32 v208, v208
	v_sub_u32_e32 v209, v46, v97
	v_sub_u32_e32 v213, v41, v209
	v_or_b32_e32 v213, v213, v209
	v_and_b32_e32 v209, 0x7f, v209
	v_lshl_add_u32 v209, v209, 2, s2
	ds_read_b32 v209, v209
	ds_read_b128 v[214:217], v98
	ds_read_b128 v[218:221], v98 offset:64
	s_waitcnt lgkmcnt(6)
	v_mfma_f32_16x16x32_bf16 v[230:233], v[222:225], v[14:17], 0
	v_mfma_f32_16x16x32_bf16 v[230:233], v[226:229], v[10:13], v[230:233]
	v_ashrrev_i32_e32 v210, 31, v210
	v_and_b32_e32 v210, 0xff800000, v210
	v_ashrrev_i32_e32 v211, 31, v211
	v_and_b32_e32 v211, 0xff800000, v211
	v_ashrrev_i32_e32 v212, 31, v212
	v_and_b32_e32 v212, 0xff800000, v212
	v_ashrrev_i32_e32 v213, 31, v213
	v_and_b32_e32 v213, 0xff800000, v213
	s_nop 1
	s_waitcnt lgkmcnt(2)
	v_add_f32_e32 v234, v230, v206
	v_add_f32_e32 v62, v234, v210
	v_add_f32_e32 v234, v231, v207
	v_add_f32_e32 v63, v234, v211
	v_add_f32_e32 v234, v232, v208
	v_add_f32_e32 v64, v234, v212
	v_add_f32_e32 v234, v233, v209
	v_add_f32_e32 v65, v234, v213
	v_max3_f32 v36, v58, v62, v63
	v_max3_f32 v58, v36, v64, v65
	v_sub_u32_e32 v206, v46, v99
	v_sub_u32_e32 v210, v41, v206
	v_or_b32_e32 v210, v210, v206
	v_and_b32_e32 v206, 0x7f, v206
	v_lshl_add_u32 v206, v206, 2, s2
	ds_read_b32 v206, v206
	v_sub_u32_e32 v207, v46, v100
	v_sub_u32_e32 v211, v41, v207
	v_or_b32_e32 v211, v211, v207
	v_and_b32_e32 v207, 0x7f, v207
	v_lshl_add_u32 v207, v207, 2, s2
	ds_read_b32 v207, v207
	v_sub_u32_e32 v208, v46, v101
	v_sub_u32_e32 v212, v41, v208
	v_or_b32_e32 v212, v212, v208
	v_and_b32_e32 v208, 0x7f, v208
	v_lshl_add_u32 v208, v208, 2, s2
	ds_read_b32 v208, v208
	v_sub_u32_e32 v209, v46, v102
	v_sub_u32_e32 v213, v41, v209
	v_or_b32_e32 v213, v213, v209
	v_and_b32_e32 v209, 0x7f, v209
	v_lshl_add_u32 v209, v209, 2, s2
	ds_read_b32 v209, v209
	ds_read_b128 v[222:225], v103
	ds_read_b128 v[226:229], v103 offset:64
	s_waitcnt lgkmcnt(6)
	v_mfma_f32_16x16x32_bf16 v[230:233], v[214:217], v[14:17], 0
	v_mfma_f32_16x16x32_bf16 v[230:233], v[218:221], v[10:13], v[230:233]
	v_ashrrev_i32_e32 v210, 31, v210
	v_and_b32_e32 v210, 0xff800000, v210
	v_ashrrev_i32_e32 v211, 31, v211
	v_and_b32_e32 v211, 0xff800000, v211
	v_ashrrev_i32_e32 v212, 31, v212
	v_and_b32_e32 v212, 0xff800000, v212
	v_ashrrev_i32_e32 v213, 31, v213
	v_and_b32_e32 v213, 0xff800000, v213
	s_nop 1
	s_waitcnt lgkmcnt(2)
	v_add_f32_e32 v234, v230, v206
	v_add_f32_e32 v137, v234, v210
	v_add_f32_e32 v234, v231, v207
	v_add_f32_e32 v142, v234, v211
	v_add_f32_e32 v234, v232, v208
	v_add_f32_e32 v143, v234, v212
	v_add_f32_e32 v234, v233, v209
	v_add_f32_e32 v144, v234, v213
	v_max3_f32 v36, v58, v137, v142
	v_max3_f32 v58, v36, v143, v144
	v_sub_u32_e32 v206, v46, v104
	v_sub_u32_e32 v210, v41, v206
	v_or_b32_e32 v210, v210, v206
	v_and_b32_e32 v206, 0x7f, v206
	v_lshl_add_u32 v206, v206, 2, s2
	ds_read_b32 v206, v206
	v_sub_u32_e32 v207, v46, v105
	v_sub_u32_e32 v211, v41, v207
	v_or_b32_e32 v211, v211, v207
	v_and_b32_e32 v207, 0x7f, v207
	v_lshl_add_u32 v207, v207, 2, s2
	ds_read_b32 v207, v207
	v_sub_u32_e32 v208, v46, v106
	v_sub_u32_e32 v212, v41, v208
	v_or_b32_e32 v212, v212, v208
	v_and_b32_e32 v208, 0x7f, v208
	v_lshl_add_u32 v208, v208, 2, s2
	ds_read_b32 v208, v208
	v_sub_u32_e32 v209, v46, v107
	v_sub_u32_e32 v213, v41, v209
	v_or_b32_e32 v213, v213, v209
	v_and_b32_e32 v209, 0x7f, v209
	v_lshl_add_u32 v209, v209, 2, s2
	ds_read_b32 v209, v209
	ds_read_b128 v[214:217], v108
	ds_read_b128 v[218:221], v108 offset:64
	s_waitcnt lgkmcnt(6)
	v_mfma_f32_16x16x32_bf16 v[230:233], v[222:225], v[14:17], 0
	v_mfma_f32_16x16x32_bf16 v[230:233], v[226:229], v[10:13], v[230:233]
	v_ashrrev_i32_e32 v210, 31, v210
	v_and_b32_e32 v210, 0xff800000, v210
	v_ashrrev_i32_e32 v211, 31, v211
	v_and_b32_e32 v211, 0xff800000, v211
	v_ashrrev_i32_e32 v212, 31, v212
	v_and_b32_e32 v212, 0xff800000, v212
	v_ashrrev_i32_e32 v213, 31, v213
	v_and_b32_e32 v213, 0xff800000, v213
	s_nop 1
	s_waitcnt lgkmcnt(2)
	v_add_f32_e32 v234, v230, v206
	v_add_f32_e32 v145, v234, v210
	v_add_f32_e32 v234, v231, v207
	v_add_f32_e32 v162, v234, v211
	v_add_f32_e32 v234, v232, v208
	v_add_f32_e32 v163, v234, v212
	v_add_f32_e32 v234, v233, v209
	v_add_f32_e32 v164, v234, v213
	v_max3_f32 v36, v58, v145, v162
	v_max3_f32 v58, v36, v163, v164
	v_sub_u32_e32 v206, v46, v109
	v_sub_u32_e32 v210, v41, v206
	v_or_b32_e32 v210, v210, v206
	v_and_b32_e32 v206, 0x7f, v206
	v_lshl_add_u32 v206, v206, 2, s2
	ds_read_b32 v206, v206
	v_sub_u32_e32 v207, v46, v110
	v_sub_u32_e32 v211, v41, v207
	v_or_b32_e32 v211, v211, v207
	v_and_b32_e32 v207, 0x7f, v207
	v_lshl_add_u32 v207, v207, 2, s2
	ds_read_b32 v207, v207
	v_sub_u32_e32 v208, v46, v111
	v_sub_u32_e32 v212, v41, v208
	v_or_b32_e32 v212, v212, v208
	v_and_b32_e32 v208, 0x7f, v208
	v_lshl_add_u32 v208, v208, 2, s2
	ds_read_b32 v208, v208
	v_sub_u32_e32 v209, v46, v112
	v_sub_u32_e32 v213, v41, v209
	v_or_b32_e32 v213, v213, v209
	v_and_b32_e32 v209, 0x7f, v209
	v_lshl_add_u32 v209, v209, 2, s2
	ds_read_b32 v209, v209
	ds_read_b128 v[222:225], v113
	ds_read_b128 v[226:229], v113 offset:64
	s_waitcnt lgkmcnt(6)
	v_mfma_f32_16x16x32_bf16 v[230:233], v[214:217], v[14:17], 0
	v_mfma_f32_16x16x32_bf16 v[230:233], v[218:221], v[10:13], v[230:233]
	v_ashrrev_i32_e32 v210, 31, v210
	v_and_b32_e32 v210, 0xff800000, v210
	v_ashrrev_i32_e32 v211, 31, v211
	v_and_b32_e32 v211, 0xff800000, v211
	v_ashrrev_i32_e32 v212, 31, v212
	v_and_b32_e32 v212, 0xff800000, v212
	v_ashrrev_i32_e32 v213, 31, v213
	v_and_b32_e32 v213, 0xff800000, v213
	s_nop 1
	s_waitcnt lgkmcnt(2)
	v_add_f32_e32 v234, v230, v206
	v_add_f32_e32 v165, v234, v210
	v_add_f32_e32 v234, v231, v207
	v_add_f32_e32 v166, v234, v211
	v_add_f32_e32 v234, v232, v208
	v_add_f32_e32 v167, v234, v212
	v_add_f32_e32 v234, v233, v209
	v_add_f32_e32 v168, v234, v213
	v_max3_f32 v36, v58, v165, v166
	v_max3_f32 v58, v36, v167, v168
	v_sub_u32_e32 v206, v46, v114
	v_sub_u32_e32 v210, v41, v206
	v_or_b32_e32 v210, v210, v206
	v_and_b32_e32 v206, 0x7f, v206
	v_lshl_add_u32 v206, v206, 2, s2
	ds_read_b32 v206, v206
	v_sub_u32_e32 v207, v46, v115
	v_sub_u32_e32 v211, v41, v207
	v_or_b32_e32 v211, v211, v207
	v_and_b32_e32 v207, 0x7f, v207
	v_lshl_add_u32 v207, v207, 2, s2
	ds_read_b32 v207, v207
	v_sub_u32_e32 v208, v46, v116
	v_sub_u32_e32 v212, v41, v208
	v_or_b32_e32 v212, v212, v208
	v_and_b32_e32 v208, 0x7f, v208
	v_lshl_add_u32 v208, v208, 2, s2
	ds_read_b32 v208, v208
	v_sub_u32_e32 v209, v46, v117
	v_sub_u32_e32 v213, v41, v209
	v_or_b32_e32 v213, v213, v209
	v_and_b32_e32 v209, 0x7f, v209
	v_lshl_add_u32 v209, v209, 2, s2
	ds_read_b32 v209, v209
	ds_read_b128 v[214:217], v118
	ds_read_b128 v[218:221], v118 offset:64
	s_waitcnt lgkmcnt(6)
	v_mfma_f32_16x16x32_bf16 v[230:233], v[222:225], v[14:17], 0
	v_mfma_f32_16x16x32_bf16 v[230:233], v[226:229], v[10:13], v[230:233]
	v_ashrrev_i32_e32 v210, 31, v210
	v_and_b32_e32 v210, 0xff800000, v210
	v_ashrrev_i32_e32 v211, 31, v211
	v_and_b32_e32 v211, 0xff800000, v211
	v_ashrrev_i32_e32 v212, 31, v212
	v_and_b32_e32 v212, 0xff800000, v212
	v_ashrrev_i32_e32 v213, 31, v213
	v_and_b32_e32 v213, 0xff800000, v213
	s_nop 1
	s_waitcnt lgkmcnt(2)
	v_add_f32_e32 v234, v230, v206
	v_add_f32_e32 v169, v234, v210
	v_add_f32_e32 v234, v231, v207
	v_add_f32_e32 v170, v234, v211
	v_add_f32_e32 v234, v232, v208
	v_add_f32_e32 v171, v234, v212
	v_add_f32_e32 v234, v233, v209
	v_add_f32_e32 v172, v234, v213
	v_max3_f32 v36, v58, v169, v170
	v_max3_f32 v58, v36, v171, v172
	v_sub_u32_e32 v206, v46, v119
	v_sub_u32_e32 v210, v41, v206
	v_or_b32_e32 v210, v210, v206
	v_and_b32_e32 v206, 0x7f, v206
	v_lshl_add_u32 v206, v206, 2, s2
	ds_read_b32 v206, v206
	v_sub_u32_e32 v207, v46, v120
	v_sub_u32_e32 v211, v41, v207
	v_or_b32_e32 v211, v211, v207
	v_and_b32_e32 v207, 0x7f, v207
	v_lshl_add_u32 v207, v207, 2, s2
	ds_read_b32 v207, v207
	v_sub_u32_e32 v208, v46, v121
	v_sub_u32_e32 v212, v41, v208
	v_or_b32_e32 v212, v212, v208
	v_and_b32_e32 v208, 0x7f, v208
	v_lshl_add_u32 v208, v208, 2, s2
	ds_read_b32 v208, v208
	v_sub_u32_e32 v209, v46, v122
	v_sub_u32_e32 v213, v41, v209
	v_or_b32_e32 v213, v213, v209
	v_and_b32_e32 v209, 0x7f, v209
	v_lshl_add_u32 v209, v209, 2, s2
	ds_read_b32 v209, v209
	ds_read_b128 v[222:225], v123
	ds_read_b128 v[226:229], v123 offset:64
	s_waitcnt lgkmcnt(6)
	v_mfma_f32_16x16x32_bf16 v[230:233], v[214:217], v[14:17], 0
	v_mfma_f32_16x16x32_bf16 v[230:233], v[218:221], v[10:13], v[230:233]
	v_ashrrev_i32_e32 v210, 31, v210
	v_and_b32_e32 v210, 0xff800000, v210
	v_ashrrev_i32_e32 v211, 31, v211
	v_and_b32_e32 v211, 0xff800000, v211
	v_ashrrev_i32_e32 v212, 31, v212
	v_and_b32_e32 v212, 0xff800000, v212
	v_ashrrev_i32_e32 v213, 31, v213
	v_and_b32_e32 v213, 0xff800000, v213
	s_nop 1
	s_waitcnt lgkmcnt(2)
	v_add_f32_e32 v234, v230, v206
	v_add_f32_e32 v173, v234, v210
	v_add_f32_e32 v234, v231, v207
	v_add_f32_e32 v174, v234, v211
	v_add_f32_e32 v234, v232, v208
	v_add_f32_e32 v175, v234, v212
	v_add_f32_e32 v234, v233, v209
	v_add_f32_e32 v176, v234, v213
	v_max3_f32 v36, v58, v173, v174
	v_max3_f32 v58, v36, v175, v176
	v_sub_u32_e32 v206, v46, v124
	v_sub_u32_e32 v210, v41, v206
	v_or_b32_e32 v210, v210, v206
	v_and_b32_e32 v206, 0x7f, v206
	v_lshl_add_u32 v206, v206, 2, s2
	ds_read_b32 v206, v206
	v_sub_u32_e32 v207, v46, v125
	v_sub_u32_e32 v211, v41, v207
	v_or_b32_e32 v211, v211, v207
	v_and_b32_e32 v207, 0x7f, v207
	v_lshl_add_u32 v207, v207, 2, s2
	ds_read_b32 v207, v207
	v_sub_u32_e32 v208, v46, v126
	v_sub_u32_e32 v212, v41, v208
	v_or_b32_e32 v212, v212, v208
	v_and_b32_e32 v208, 0x7f, v208
	v_lshl_add_u32 v208, v208, 2, s2
	ds_read_b32 v208, v208
	v_sub_u32_e32 v209, v46, v127
	v_sub_u32_e32 v213, v41, v209
	v_or_b32_e32 v213, v213, v209
	v_and_b32_e32 v209, 0x7f, v209
	v_lshl_add_u32 v209, v209, 2, s2
	ds_read_b32 v209, v209
	s_waitcnt lgkmcnt(4)
	v_mfma_f32_16x16x32_bf16 v[230:233], v[222:225], v[14:17], 0
	v_mfma_f32_16x16x32_bf16 v[230:233], v[226:229], v[10:13], v[230:233]
	v_ashrrev_i32_e32 v210, 31, v210
	v_and_b32_e32 v210, 0xff800000, v210
	v_ashrrev_i32_e32 v211, 31, v211
	v_and_b32_e32 v211, 0xff800000, v211
	v_ashrrev_i32_e32 v212, 31, v212
	v_and_b32_e32 v212, 0xff800000, v212
	v_ashrrev_i32_e32 v213, 31, v213
	v_and_b32_e32 v213, 0xff800000, v213
	s_nop 1
	s_waitcnt lgkmcnt(0)
	v_add_f32_e32 v234, v230, v206
	v_add_f32_e32 v36, v234, v210
	v_add_f32_e32 v234, v231, v207
	v_add_f32_e32 v37, v234, v211
	v_add_f32_e32 v234, v232, v208
	v_add_f32_e32 v38, v234, v212
	v_add_f32_e32 v234, v233, v209
	v_add_f32_e32 v39, v234, v213
	v_max3_f32 v10, v58, v36, v37
	v_max3_f32 v10, v10, v38, v39
	ds_swizzle_b32 v11, v10 offset:swizzle(SWAP,16)
	s_waitcnt lgkmcnt(0)
	v_max_f32_e32 v11, v11, v11
	v_max_f32_e32 v10, v10, v11
	ds_bpermute_b32 v11, v19, v10
	s_waitcnt vmcnt(0) lgkmcnt(0)
	v_max3_f32 v41, v10, v11, v40
	v_sub_f32_e32 v15, v52, v41
	v_mul_f32_e32 v15, 0x3fb8aa3b, v15
	v_exp_f32_e32 v138, v15
	v_sub_f32_e32 v15, v53, v41
	v_mul_f32_e32 v15, 0x3fb8aa3b, v15
	v_exp_f32_e32 v139, v15
	v_sub_f32_e32 v15, v51, v41
	v_mul_f32_e32 v15, 0x3fb8aa3b, v15
	v_exp_f32_e32 v140, v15
	v_sub_f32_e32 v15, v54, v41
	v_mul_f32_e32 v15, 0x3fb8aa3b, v15
	v_exp_f32_e32 v141, v15
	v_sub_f32_e32 v15, v56, v41
	v_mul_f32_e32 v15, 0x3fb8aa3b, v15
	v_exp_f32_e32 v58, v15
	v_sub_f32_e32 v15, v57, v41
	v_mul_f32_e32 v15, 0x3fb8aa3b, v15
	v_exp_f32_e32 v59, v15
	v_sub_f32_e32 v15, v55, v41
	v_sub_f32_e32 v10, v47, v41
	v_mul_f32_e32 v15, 0x3fb8aa3b, v15
	v_mul_f32_e32 v10, 0x3fb8aa3b, v10
	v_sub_f32_e32 v11, v48, v41
	v_exp_f32_e32 v60, v15
	v_sub_f32_e32 v15, v61, v41
	v_exp_f32_e32 v10, v10
	v_mul_f32_e32 v11, 0x3fb8aa3b, v11
	v_mul_f32_e32 v15, 0x3fb8aa3b, v15
	v_exp_f32_e32 v11, v11
	v_exp_f32_e32 v61, v15
	v_sub_f32_e32 v15, v62, v41
	v_mul_f32_e32 v15, 0x3fb8aa3b, v15
	v_exp_f32_e32 v62, v15
	v_sub_f32_e32 v15, v63, v41
	v_add_f32_e32 v12, 0, v10
	v_mul_f32_e32 v15, 0x3fb8aa3b, v15
	v_add_f32_e32 v13, v11, v12
	v_sub_f32_e32 v12, v49, v41
	v_exp_f32_e32 v63, v15
	v_sub_f32_e32 v15, v64, v41
	v_mul_f32_e32 v12, 0x3fb8aa3b, v12
	v_mul_f32_e32 v15, 0x3fb8aa3b, v15
	v_exp_f32_e32 v12, v12
	v_exp_f32_e32 v64, v15
	v_sub_f32_e32 v15, v65, v41
	v_mul_f32_e32 v15, 0x3fb8aa3b, v15
	v_exp_f32_e32 v65, v15
	v_sub_f32_e32 v15, v137, v41
	v_mul_f32_e32 v15, 0x3fb8aa3b, v15
	v_add_f32_e32 v14, v12, v13
	v_sub_f32_e32 v13, v50, v41
	v_exp_f32_e32 v50, v15
	v_sub_f32_e32 v15, v142, v41
	v_mul_f32_e32 v13, 0x3fb8aa3b, v13
	v_mul_f32_e32 v15, 0x3fb8aa3b, v15
	v_exp_f32_e32 v13, v13
	v_exp_f32_e32 v51, v15
	v_sub_f32_e32 v15, v143, v41
	v_mul_f32_e32 v15, 0x3fb8aa3b, v15
	v_exp_f32_e32 v52, v15
	v_sub_f32_e32 v15, v144, v41
	v_mul_f32_e32 v15, 0x3fb8aa3b, v15
	v_add_f32_e32 v14, v13, v14
	v_exp_f32_e32 v53, v15
	v_sub_f32_e32 v15, v145, v41
	v_add_f32_e32 v14, v138, v14
	v_mul_f32_e32 v15, 0x3fb8aa3b, v15
	v_add_f32_e32 v14, v139, v14
	v_exp_f32_e32 v54, v15
	v_sub_f32_e32 v15, v162, v41
	v_add_f32_e32 v14, v140, v14
	v_mul_f32_e32 v15, 0x3fb8aa3b, v15
	v_add_f32_e32 v14, v141, v14
	v_exp_f32_e32 v55, v15
	v_sub_f32_e32 v15, v163, v41
	v_add_f32_e32 v14, v58, v14
	v_mul_f32_e32 v15, 0x3fb8aa3b, v15
	v_add_f32_e32 v14, v59, v14
	v_exp_f32_e32 v56, v15
	v_sub_f32_e32 v15, v164, v41
	v_add_f32_e32 v14, v60, v14
	v_mul_f32_e32 v15, 0x3fb8aa3b, v15
	v_add_f32_e32 v14, v61, v14
	v_exp_f32_e32 v57, v15
	v_sub_f32_e32 v15, v165, v41
	v_add_f32_e32 v14, v62, v14
	v_mul_f32_e32 v15, 0x3fb8aa3b, v15
	v_add_f32_e32 v14, v63, v14
	v_exp_f32_e32 v42, v15
	v_sub_f32_e32 v15, v166, v41
	v_add_f32_e32 v14, v64, v14
	v_mul_f32_e32 v15, 0x3fb8aa3b, v15
	v_add_f32_e32 v14, v65, v14
	v_exp_f32_e32 v43, v15
	v_sub_f32_e32 v15, v167, v41
	v_add_f32_e32 v14, v50, v14
	v_mul_f32_e32 v15, 0x3fb8aa3b, v15
	v_add_f32_e32 v14, v51, v14
	v_exp_f32_e32 v44, v15
	v_sub_f32_e32 v15, v168, v41
	v_add_f32_e32 v14, v52, v14
	v_mul_f32_e32 v15, 0x3fb8aa3b, v15
	v_add_f32_e32 v14, v53, v14
	v_exp_f32_e32 v45, v15
	v_sub_f32_e32 v15, v169, v41
	v_add_f32_e32 v14, v54, v14
	v_mul_f32_e32 v15, 0x3fb8aa3b, v15
	v_add_f32_e32 v14, v55, v14
	v_exp_f32_e32 v46, v15
	v_sub_f32_e32 v15, v170, v41
	v_add_f32_e32 v14, v56, v14
	v_mul_f32_e32 v15, 0x3fb8aa3b, v15
	v_add_f32_e32 v14, v57, v14
	v_exp_f32_e32 v47, v15
	v_sub_f32_e32 v15, v171, v41
	v_add_f32_e32 v14, v42, v14
	v_mul_f32_e32 v15, 0x3fb8aa3b, v15
	v_add_f32_e32 v14, v43, v14
	v_exp_f32_e32 v48, v15
	v_sub_f32_e32 v15, v172, v41
	v_add_f32_e32 v14, v44, v14
	v_mul_f32_e32 v15, 0x3fb8aa3b, v15
	v_add_f32_e32 v14, v45, v14
	v_exp_f32_e32 v49, v15
	v_add_f32_e32 v14, v46, v14
	v_add_f32_e32 v14, v47, v14
	v_add_f32_e32 v14, v48, v14
	v_add_f32_e32 v15, v49, v14
	v_sub_f32_e32 v14, v173, v41
	v_mul_f32_e32 v14, 0x3fb8aa3b, v14
	v_exp_f32_e32 v14, v14
	v_sub_f32_e32 v36, v36, v41
	v_mul_f32_e32 v36, 0x3fb8aa3b, v36
	v_sub_f32_e32 v37, v37, v41
	v_add_f32_e32 v16, v14, v15
	v_sub_f32_e32 v15, v174, v41
	v_mul_f32_e32 v15, 0x3fb8aa3b, v15
	v_exp_f32_e32 v15, v15
	v_exp_f32_e32 v36, v36
	v_mul_f32_e32 v37, 0x3fb8aa3b, v37
	v_sub_f32_e32 v38, v38, v41
	v_add_f32_e32 v17, v15, v16
	v_sub_f32_e32 v16, v175, v41
	v_mul_f32_e32 v16, 0x3fb8aa3b, v16
	v_exp_f32_e32 v16, v16
	v_exp_f32_e32 v37, v37
	v_mul_f32_e32 v38, 0x3fb8aa3b, v38
	v_sub_f32_e32 v39, v39, v41
	v_add_f32_e32 v137, v16, v17
	v_sub_f32_e32 v17, v176, v41
	v_mul_f32_e32 v17, 0x3fb8aa3b, v17
	v_exp_f32_e32 v17, v17
	v_exp_f32_e32 v38, v38
	v_mul_f32_e32 v39, 0x3fb8aa3b, v39
	v_exp_f32_e32 v39, v39
	v_add_f32_e32 v137, v17, v137
	v_add_f32_e32 v137, v36, v137
	v_add_f32_e32 v137, v37, v137
	v_add_f32_e32 v137, v38, v137
	v_add_f32_e32 v137, v39, v137
	ds_swizzle_b32 v142, v137 offset:swizzle(SWAP,16)
	v_sub_f32_e32 v40, v40, v41
	v_mul_f32_e32 v40, 0x3fb8aa3b, v40
	v_exp_f32_e32 v40, v40
	s_waitcnt lgkmcnt(0)
	v_add_f32_e32 v137, v137, v142
	ds_bpermute_b32 v142, v19, v137
	s_waitcnt lgkmcnt(0)
	v_add_f32_e32 v137, v137, v142
	v_add_f32_e32 v40, v40, v137
	v_div_scale_f32 v41, s[2:3], v40, v40, 1.0
	v_rcp_f32_e32 v137, v41
	s_nop 0
	v_fma_f32 v142, -v41, v137, 1.0
	v_fmac_f32_e32 v137, v142, v137
	v_div_scale_f32 v142, vcc, 1.0, v40, 1.0
	v_mul_f32_e32 v143, v142, v137
	v_fma_f32 v144, -v41, v143, v142
	v_fmac_f32_e32 v143, v144, v137
	v_fma_f32 v41, -v41, v143, v142
	v_div_fmas_f32 v41, v41, v137, v143
	v_div_fixup_f32 v40, v41, v40, 1.0
	v_pk_mul_f32 v[12:13], v[12:13], v[40:41] op_sel_hi:[1,0]
	v_pk_mul_f32 v[10:11], v[10:11], v[40:41] op_sel_hi:[1,0]
	v_pk_mul_f32 v[140:141], v[140:141], v[40:41] op_sel_hi:[1,0]
	v_pk_mul_f32 v[138:139], v[138:139], v[40:41] op_sel_hi:[1,0]
	v_add_u32_e32 v137, 0x9000, v132
	v_cvt_pk_bf16_f32 v10, v10, v11
	v_cvt_pk_bf16_f32 v11, v12, v13
	v_cvt_pk_bf16_f32 v12, v138, v139
	v_cvt_pk_bf16_f32 v13, v140, v141
	ds_read2_b64 v[138:141], v137 offset1:4
	s_waitcnt lgkmcnt(0)
	v_mfma_f32_16x16x32_bf16 v[142:145], v[138:141], v[10:13], 0
	v_add_u32_e32 v138, 0xb000, v132
	v_add_u32_e32 v139, 0xd000, v132
	v_add_u32_e32 v140, 0xf000, v132
	ds_read2_b64 v[162:165], v138 offset0:32 offset1:36
	ds_read2_b64 v[166:169], v139 offset0:64 offset1:68
	ds_read2_b64 v[170:173], v140 offset0:96 offset1:100
	v_pk_mul_f32 v[58:59], v[58:59], v[40:41] op_sel_hi:[1,0]
	s_waitcnt lgkmcnt(2)
	v_mfma_f32_16x16x32_bf16 v[162:165], v[162:165], v[10:13], 0
	v_mul_f32_e64 v60, v60, v40
	v_mul_f32_e64 v61, v61, v40
	v_pk_mul_f32 v[52:53], v[52:53], v[40:41] op_sel_hi:[1,0]
	v_pk_mul_f32 v[50:51], v[50:51], v[40:41] op_sel_hi:[1,0]
	s_waitcnt lgkmcnt(1)
	v_mfma_f32_16x16x32_bf16 v[166:169], v[166:169], v[10:13], 0
	v_mul_f32_e64 v56, v56, v40
	v_mul_f32_e64 v57, v57, v40
	v_pk_mul_f32 v[54:55], v[54:55], v[40:41] op_sel_hi:[1,0]
	v_pk_mul_f32 v[44:45], v[44:45], v[40:41] op_sel_hi:[1,0]
	s_waitcnt lgkmcnt(0)
	v_mfma_f32_16x16x32_bf16 v[10:13], v[170:173], v[10:13], 0
	v_mul_f32_e64 v170, v64, v40
	v_mul_f32_e64 v171, v65, v40
	v_pk_mul_f32 v[64:65], v[62:63], v[40:41] op_sel_hi:[1,0]
	v_cvt_pk_bf16_f32 v62, v58, v59
	v_add_u32_e32 v58, 0x9000, v133
	v_cvt_pk_bf16_f32 v63, v60, v61
	v_cvt_pk_bf16_f32 v64, v64, v65
	v_cvt_pk_bf16_f32 v65, v170, v171
	ds_read2_b64 v[170:173], v58 offset1:4
	v_add_u32_e32 v59, 0xb000, v133
	s_waitcnt lgkmcnt(0)
	v_mfma_f32_16x16x32_bf16 v[142:145], v[170:173], v[62:65], v[142:145]
	ds_read2_b64 v[170:173], v59 offset0:32 offset1:36
	v_add_u32_e32 v60, 0xd000, v133
	v_add_u32_e32 v61, 0xf000, v133
	s_waitcnt lgkmcnt(0)
	v_mfma_f32_16x16x32_bf16 v[162:165], v[170:173], v[62:65], v[162:165]
	ds_read2_b64 v[170:173], v60 offset0:64 offset1:68
	v_pk_mul_f32 v[42:43], v[42:43], v[40:41] op_sel_hi:[1,0]
	v_pk_mul_f32 v[48:49], v[48:49], v[40:41] op_sel_hi:[1,0]
	s_waitcnt lgkmcnt(0)
	v_mfma_f32_16x16x32_bf16 v[166:169], v[170:173], v[62:65], v[166:169]
	ds_read2_b64 v[170:173], v61 offset0:96 offset1:100
	v_cvt_pk_bf16_f32 v50, v50, v51
	v_cvt_pk_bf16_f32 v51, v52, v53
	v_cvt_pk_bf16_f32 v52, v54, v55
	v_cvt_pk_bf16_f32 v53, v56, v57
	v_add_u32_e32 v56, 0x9000, v134
	s_waitcnt lgkmcnt(0)
	v_mfma_f32_16x16x32_bf16 v[10:13], v[170:173], v[62:65], v[10:13]
	ds_read2_b64 v[62:65], v56 offset1:4
	v_add_u32_e32 v57, 0xb000, v134
	v_pk_mul_f32 v[46:47], v[46:47], v[40:41] op_sel_hi:[1,0]
	s_waitcnt lgkmcnt(0)
	v_mfma_f32_16x16x32_bf16 v[142:145], v[62:65], v[50:53], v[142:145]
	ds_read2_b64 v[62:65], v57 offset0:32 offset1:36
	v_add_u32_e32 v141, 0xd000, v135
	v_pk_mul_f32 v[16:17], v[16:17], v[40:41] op_sel_hi:[1,0]
	s_waitcnt lgkmcnt(0)
	v_mfma_f32_16x16x32_bf16 v[162:165], v[62:65], v[50:53], v[162:165]
	v_add_u32_e32 v62, 0xd000, v134
	ds_read2_b64 v[170:173], v62 offset0:64 offset1:68
	v_add_u32_e32 v63, 0xf000, v134
	v_add_u32_e32 v64, 0x9000, v135
	s_waitcnt lgkmcnt(0)
	v_mfma_f32_16x16x32_bf16 v[166:169], v[170:173], v[50:53], v[166:169]
	ds_read2_b64 v[170:173], v63 offset0:96 offset1:100
	v_cvt_pk_bf16_f32 v42, v42, v43
	v_cvt_pk_bf16_f32 v43, v44, v45
	v_cvt_pk_bf16_f32 v44, v46, v47
	v_cvt_pk_bf16_f32 v45, v48, v49
	ds_read2_b64 v[46:49], v64 offset1:4
	v_add_u32_e32 v65, 0xb000, v135
	s_waitcnt lgkmcnt(1)
	v_mfma_f32_16x16x32_bf16 v[10:13], v[170:173], v[50:53], v[10:13]
	ds_read2_b64 v[50:53], v65 offset0:32 offset1:36
	v_pk_mul_f32 v[14:15], v[14:15], v[40:41] op_sel_hi:[1,0]
	v_pk_mul_f32 v[38:39], v[38:39], v[40:41] op_sel_hi:[1,0]
	s_waitcnt lgkmcnt(1)
	v_mfma_f32_16x16x32_bf16 v[46:49], v[46:49], v[42:45], v[142:145]
	v_mul_f32_e64 v36, v36, v40
	v_mul_f32_e64 v37, v37, v40
	s_nop 0
	ds_read2_b64 v[142:145], v141 offset0:64 offset1:68
	s_waitcnt lgkmcnt(1)
	v_mfma_f32_16x16x32_bf16 v[50:53], v[50:53], v[42:45], v[162:165]
	s_waitcnt lgkmcnt(0)
	v_mfma_f32_16x16x32_bf16 v[162:165], v[142:145], v[42:45], v[166:169]
	v_add_u32_e32 v142, 0xf000, v135
	v_add_u32_e32 v143, 0x9000, v136
	s_nop 0
	ds_read2_b64 v[166:169], v142 offset0:96 offset1:100
	v_cvt_pk_bf16_f32 v14, v14, v15
	v_cvt_pk_bf16_f32 v15, v16, v17
	v_cvt_pk_bf16_f32 v16, v36, v37
	v_cvt_pk_bf16_f32 v17, v38, v39
	ds_read2_b64 v[36:39], v143 offset1:4
	v_add_u32_e32 v145, 0xd000, v136
	s_waitcnt lgkmcnt(1)
	v_mfma_f32_16x16x32_bf16 v[10:13], v[166:169], v[42:45], v[10:13]
	v_add_u32_e32 v144, 0xb000, v136
	ds_read2_b64 v[40:43], v144 offset0:32 offset1:36
	s_waitcnt lgkmcnt(1)
	v_mfma_f32_16x16x32_bf16 v[36:39], v[36:39], v[14:17], v[46:49]
	s_nop 2
	ds_read2_b64 v[44:47], v145 offset0:64 offset1:68
	s_waitcnt lgkmcnt(0)
	v_mfma_f32_16x16x32_bf16 v[44:47], v[44:47], v[14:17], v[162:165]
	s_nop 2
	v_add_u32_e32 v162, 0xf000, v136
	v_mfma_f32_16x16x32_bf16 v[40:43], v[40:43], v[14:17], v[50:53]
	s_nop 2
	ds_read2_b64 v[48:51], v162 offset0:96 offset1:100
	s_waitcnt lgkmcnt(0)
	v_mfma_f32_16x16x32_bf16 v[10:13], v[48:51], v[14:17], v[10:13]
	v_cvt_pk_bf16_f32 v14, v36, v37
	v_cvt_pk_bf16_f32 v15, v38, v39
	global_store_dwordx2 v[34:35], v[14:15], off offset:-64
	v_cvt_pk_bf16_f32 v14, v40, v41
	v_cvt_pk_bf16_f32 v15, v42, v43
	global_store_dwordx2 v[34:35], v[14:15], off offset:-32
	v_cvt_pk_bf16_f32 v14, v44, v45
	v_cvt_pk_bf16_f32 v15, v46, v47
	global_store_dwordx2 v[34:35], v[14:15], off
	v_cvt_pk_bf16_f32 v10, v10, v11
	v_cvt_pk_bf16_f32 v11, v12, v13
	s_nop 4
	global_store_dwordx2 v[34:35], v[10:11], off offset:32
	v_mov_b64_e32 v[12:13], v[8:9]
	v_lshl_add_u64 v[34:35], v[34:35], 0, s[94:95]
	v_mov_b64_e32 v[10:11], v[6:7]
	s_cbranch_scc0 .LBB0_124
	s_lshl_b32 s2, s23, 3
	s_add_i32 s2, s2, s19
	s_mov_b32 s3, s89
	s_lshl_b64 s[2:3], s[2:3], 2
	v_mov_b32_e32 v12, v22
	s_add_u32 s2, s48, s2
	s_addc_u32 s3, s49, s3
	v_lshl_add_u64 v[10:11], v[30:31], 1, v[24:25]
	v_cndmask_b32_e64 v16, v195, v12, s[38:39]
	global_load_dword v163, v1, s[2:3] offset:28
	v_add_u32_e32 v17, 0x80, v12
	ds_read_b128 v[12:15], v78
	ds_read_b128 v[30:33], v78 offset:64
	s_waitcnt lgkmcnt(1)
	v_mfma_f32_16x16x32_bf16 v[12:15], v[12:15], v[2:5], 0
	v_sub_u32_e32 v55, v17, v109
	s_or_b32 s88, s88, 0x380
	s_add_i32 s22, s22, s92
	s_waitcnt lgkmcnt(0)
	v_mfma_f32_16x16x32_bf16 v[12:15], v[30:33], v[6:9], v[12:15]
	v_sub_u32_e32 v30, v17, v79
	v_sub_u32_e32 v31, v16, v30
	v_or_b32_e32 v31, v31, v30
	v_and_b32_e32 v30, 0x7f, v30
	v_lshl_add_u32 v30, v30, 2, s97
	ds_read_b32 v30, v30
	v_ashrrev_i32_e32 v31, 31, v31
	v_and_b32_e32 v31, 0xff800000, v31
	s_xor_b64 s[42:43], s[42:43], s[44:45]
	s_cmpk_gt_i32 s22, 0xff
	s_waitcnt lgkmcnt(0)
	v_add_f32_e32 v12, v12, v30
	v_sub_u32_e32 v30, v17, v80
	v_add_f32_e32 v12, v12, v31
	v_sub_u32_e32 v31, v16, v30
	v_or_b32_e32 v31, v31, v30
	v_and_b32_e32 v30, 0x7f, v30
	v_lshl_add_u32 v30, v30, 2, s97
	ds_read_b32 v30, v30
	v_ashrrev_i32_e32 v31, 31, v31
	v_and_b32_e32 v31, 0xff800000, v31
	s_waitcnt lgkmcnt(0)
	v_add_f32_e32 v13, v13, v30
	v_add_f32_e32 v13, v13, v31
	v_sub_u32_e32 v31, v17, v81
	v_sub_u32_e32 v32, v16, v31
	v_or_b32_e32 v32, v32, v31
	v_and_b32_e32 v31, 0x7f, v31
	v_lshl_add_u32 v31, v31, 2, s97
	ds_read_b32 v31, v31
	v_ashrrev_i32_e32 v32, 31, v32
	v_and_b32_e32 v32, 0xff800000, v32
	v_max3_f32 v30, v12, s96, v13
	s_waitcnt lgkmcnt(0)
	v_add_f32_e32 v14, v14, v31
	v_sub_u32_e32 v31, v17, v82
	v_add_f32_e32 v14, v14, v32
	v_sub_u32_e32 v32, v16, v31
	v_or_b32_e32 v32, v32, v31
	v_and_b32_e32 v31, 0x7f, v31
	v_lshl_add_u32 v31, v31, 2, s97
	ds_read_b32 v31, v31
	v_ashrrev_i32_e32 v32, 31, v32
	v_and_b32_e32 v32, 0xff800000, v32
	s_waitcnt lgkmcnt(0)
	v_add_f32_e32 v15, v15, v31
	v_add_f32_e32 v15, v15, v32
	v_max3_f32 v38, v30, v14, v15
	ds_read_b128 v[30:33], v83
	ds_read_b128 v[34:37], v83 offset:64
	s_waitcnt lgkmcnt(1)
	v_mfma_f32_16x16x32_bf16 v[30:33], v[30:33], v[2:5], 0
	s_waitcnt lgkmcnt(0)
	v_mfma_f32_16x16x32_bf16 v[30:33], v[34:37], v[6:9], v[30:33]
	v_sub_u32_e32 v34, v17, v84
	v_sub_u32_e32 v35, v16, v34
	v_or_b32_e32 v35, v35, v34
	v_and_b32_e32 v34, 0x7f, v34
	v_lshl_add_u32 v34, v34, 2, s97
	ds_read_b32 v34, v34
	v_ashrrev_i32_e32 v35, 31, v35
	v_and_b32_e32 v35, 0xff800000, v35
	s_waitcnt lgkmcnt(0)
	v_add_f32_e32 v30, v30, v34
	v_sub_u32_e32 v34, v17, v85
	v_add_f32_e32 v30, v30, v35
	v_sub_u32_e32 v35, v16, v34
	v_or_b32_e32 v35, v35, v34
	v_and_b32_e32 v34, 0x7f, v34
	v_lshl_add_u32 v34, v34, 2, s97
	ds_read_b32 v34, v34
	v_ashrrev_i32_e32 v35, 31, v35
	v_and_b32_e32 v35, 0xff800000, v35
	s_waitcnt lgkmcnt(0)
	v_add_f32_e32 v31, v31, v34
	v_add_f32_e32 v31, v31, v35
	v_sub_u32_e32 v35, v17, v86
	v_sub_u32_e32 v36, v16, v35
	v_or_b32_e32 v36, v36, v35
	v_and_b32_e32 v35, 0x7f, v35
	v_lshl_add_u32 v35, v35, 2, s97
	ds_read_b32 v35, v35
	v_ashrrev_i32_e32 v36, 31, v36
	v_and_b32_e32 v36, 0xff800000, v36
	v_max3_f32 v34, v38, v30, v31
	s_waitcnt lgkmcnt(0)
	v_add_f32_e32 v32, v32, v35
	v_sub_u32_e32 v35, v17, v87
	v_add_f32_e32 v32, v32, v36
	v_sub_u32_e32 v36, v16, v35
	v_or_b32_e32 v36, v36, v35
	v_and_b32_e32 v35, 0x7f, v35
	v_lshl_add_u32 v35, v35, 2, s97
	ds_read_b32 v35, v35
	v_ashrrev_i32_e32 v36, 31, v36
	v_and_b32_e32 v36, 0xff800000, v36
	s_waitcnt lgkmcnt(0)
	v_add_f32_e32 v33, v33, v35
	v_add_f32_e32 v33, v33, v36
	v_max3_f32 v42, v34, v32, v33
	ds_read_b128 v[34:37], v88
	ds_read_b128 v[38:41], v88 offset:64
	s_waitcnt lgkmcnt(1)
	v_mfma_f32_16x16x32_bf16 v[34:37], v[34:37], v[2:5], 0
	s_waitcnt lgkmcnt(0)
	v_mfma_f32_16x16x32_bf16 v[34:37], v[38:41], v[6:9], v[34:37]
	v_sub_u32_e32 v38, v17, v89
	v_sub_u32_e32 v39, v16, v38
	v_or_b32_e32 v39, v39, v38
	v_and_b32_e32 v38, 0x7f, v38
	v_lshl_add_u32 v38, v38, 2, s97
	ds_read_b32 v38, v38
	v_ashrrev_i32_e32 v39, 31, v39
	v_and_b32_e32 v39, 0xff800000, v39
	s_waitcnt lgkmcnt(0)
	v_add_f32_e32 v34, v34, v38
	v_sub_u32_e32 v38, v17, v90
	v_add_f32_e32 v34, v34, v39
	v_sub_u32_e32 v39, v16, v38
	v_or_b32_e32 v39, v39, v38
	v_and_b32_e32 v38, 0x7f, v38
	v_lshl_add_u32 v38, v38, 2, s97
	ds_read_b32 v38, v38
	v_ashrrev_i32_e32 v39, 31, v39
	v_and_b32_e32 v39, 0xff800000, v39
	s_waitcnt lgkmcnt(0)
	v_add_f32_e32 v35, v35, v38
	v_add_f32_e32 v35, v35, v39
	v_sub_u32_e32 v39, v17, v91
	v_sub_u32_e32 v40, v16, v39
	v_or_b32_e32 v40, v40, v39
	v_and_b32_e32 v39, 0x7f, v39
	v_lshl_add_u32 v39, v39, 2, s97
	ds_read_b32 v39, v39
	v_ashrrev_i32_e32 v40, 31, v40
	v_and_b32_e32 v40, 0xff800000, v40
	v_max3_f32 v38, v42, v34, v35
	s_waitcnt lgkmcnt(0)
	v_add_f32_e32 v36, v36, v39
	v_sub_u32_e32 v39, v17, v92
	v_add_f32_e32 v36, v36, v40
	v_sub_u32_e32 v40, v16, v39
	v_or_b32_e32 v40, v40, v39
	v_and_b32_e32 v39, 0x7f, v39
	v_lshl_add_u32 v39, v39, 2, s97
	ds_read_b32 v39, v39
	v_ashrrev_i32_e32 v40, 31, v40
	v_and_b32_e32 v40, 0xff800000, v40
	s_waitcnt lgkmcnt(0)
	v_add_f32_e32 v37, v37, v39
	v_add_f32_e32 v37, v37, v40
	v_max3_f32 v46, v38, v36, v37
	ds_read_b128 v[38:41], v93
	ds_read_b128 v[42:45], v93 offset:64
	s_waitcnt lgkmcnt(1)
	v_mfma_f32_16x16x32_bf16 v[38:41], v[38:41], v[2:5], 0
	s_waitcnt lgkmcnt(0)
	v_mfma_f32_16x16x32_bf16 v[38:41], v[42:45], v[6:9], v[38:41]
	v_sub_u32_e32 v42, v17, v94
	v_sub_u32_e32 v43, v16, v42
	v_or_b32_e32 v43, v43, v42
	v_and_b32_e32 v42, 0x7f, v42
	v_lshl_add_u32 v42, v42, 2, s97
	ds_read_b32 v42, v42
	v_ashrrev_i32_e32 v43, 31, v43
	v_and_b32_e32 v43, 0xff800000, v43
	s_waitcnt lgkmcnt(0)
	v_add_f32_e32 v38, v38, v42
	v_sub_u32_e32 v42, v17, v95
	v_add_f32_e32 v38, v38, v43
	v_sub_u32_e32 v43, v16, v42
	v_or_b32_e32 v43, v43, v42
	v_and_b32_e32 v42, 0x7f, v42
	v_lshl_add_u32 v42, v42, 2, s97
	ds_read_b32 v42, v42
	v_ashrrev_i32_e32 v43, 31, v43
	v_and_b32_e32 v43, 0xff800000, v43
	s_waitcnt lgkmcnt(0)
	v_add_f32_e32 v39, v39, v42
	v_add_f32_e32 v39, v39, v43
	v_sub_u32_e32 v43, v17, v96
	v_sub_u32_e32 v44, v16, v43
	v_or_b32_e32 v44, v44, v43
	v_and_b32_e32 v43, 0x7f, v43
	v_lshl_add_u32 v43, v43, 2, s97
	ds_read_b32 v43, v43
	v_ashrrev_i32_e32 v44, 31, v44
	v_and_b32_e32 v44, 0xff800000, v44
	v_max3_f32 v42, v46, v38, v39
	s_waitcnt lgkmcnt(0)
	v_add_f32_e32 v40, v40, v43
	v_sub_u32_e32 v43, v17, v97
	v_add_f32_e32 v40, v40, v44
	v_sub_u32_e32 v44, v16, v43
	v_or_b32_e32 v44, v44, v43
	v_and_b32_e32 v43, 0x7f, v43
	v_lshl_add_u32 v43, v43, 2, s97
	ds_read_b32 v43, v43
	v_ashrrev_i32_e32 v44, 31, v44
	v_and_b32_e32 v44, 0xff800000, v44
	s_waitcnt lgkmcnt(0)
	v_add_f32_e32 v41, v41, v43
	v_add_f32_e32 v41, v41, v44
	v_max3_f32 v50, v42, v40, v41
	ds_read_b128 v[42:45], v98
	ds_read_b128 v[46:49], v98 offset:64
	s_waitcnt lgkmcnt(1)
	v_mfma_f32_16x16x32_bf16 v[42:45], v[42:45], v[2:5], 0
	s_waitcnt lgkmcnt(0)
	v_mfma_f32_16x16x32_bf16 v[42:45], v[46:49], v[6:9], v[42:45]
	v_sub_u32_e32 v46, v17, v99
	v_sub_u32_e32 v47, v16, v46
	v_or_b32_e32 v47, v47, v46
	v_and_b32_e32 v46, 0x7f, v46
	v_lshl_add_u32 v46, v46, 2, s97
	ds_read_b32 v46, v46
	v_ashrrev_i32_e32 v47, 31, v47
	v_and_b32_e32 v47, 0xff800000, v47
	s_waitcnt lgkmcnt(0)
	v_add_f32_e32 v42, v42, v46
	v_sub_u32_e32 v46, v17, v100
	v_add_f32_e32 v42, v42, v47
	v_sub_u32_e32 v47, v16, v46
	v_or_b32_e32 v47, v47, v46
	v_and_b32_e32 v46, 0x7f, v46
	v_lshl_add_u32 v46, v46, 2, s97
	ds_read_b32 v46, v46
	v_ashrrev_i32_e32 v47, 31, v47
	v_and_b32_e32 v47, 0xff800000, v47
	s_waitcnt lgkmcnt(0)
	v_add_f32_e32 v43, v43, v46
	v_add_f32_e32 v43, v43, v47
	v_sub_u32_e32 v47, v17, v101
	v_sub_u32_e32 v48, v16, v47
	v_or_b32_e32 v48, v48, v47
	v_and_b32_e32 v47, 0x7f, v47
	v_lshl_add_u32 v47, v47, 2, s97
	ds_read_b32 v47, v47
	v_ashrrev_i32_e32 v48, 31, v48
	v_and_b32_e32 v48, 0xff800000, v48
	v_max3_f32 v46, v50, v42, v43
	s_waitcnt lgkmcnt(0)
	v_add_f32_e32 v44, v44, v47
	v_sub_u32_e32 v47, v17, v102
	v_add_f32_e32 v44, v44, v48
	v_sub_u32_e32 v48, v16, v47
	v_or_b32_e32 v48, v48, v47
	v_and_b32_e32 v47, 0x7f, v47
	v_lshl_add_u32 v47, v47, 2, s97
	ds_read_b32 v47, v47
	v_ashrrev_i32_e32 v48, 31, v48
	v_and_b32_e32 v48, 0xff800000, v48
	s_waitcnt lgkmcnt(0)
	v_add_f32_e32 v45, v45, v47
	v_add_f32_e32 v45, v45, v48
	v_max3_f32 v54, v46, v44, v45
	ds_read_b128 v[46:49], v103
	ds_read_b128 v[50:53], v103 offset:64
	s_waitcnt lgkmcnt(1)
	v_mfma_f32_16x16x32_bf16 v[46:49], v[46:49], v[2:5], 0
	s_waitcnt lgkmcnt(0)
	v_mfma_f32_16x16x32_bf16 v[46:49], v[50:53], v[6:9], v[46:49]
	v_sub_u32_e32 v50, v17, v104
	v_sub_u32_e32 v51, v16, v50
	v_or_b32_e32 v51, v51, v50
	v_and_b32_e32 v50, 0x7f, v50
	v_lshl_add_u32 v50, v50, 2, s97
	ds_read_b32 v50, v50
	v_ashrrev_i32_e32 v51, 31, v51
	v_and_b32_e32 v51, 0xff800000, v51
	s_waitcnt lgkmcnt(0)
	v_add_f32_e32 v46, v46, v50
	v_sub_u32_e32 v50, v17, v105
	v_add_f32_e32 v46, v46, v51
	v_sub_u32_e32 v51, v16, v50
	v_or_b32_e32 v51, v51, v50
	v_and_b32_e32 v50, 0x7f, v50
	v_lshl_add_u32 v50, v50, 2, s97
	ds_read_b32 v50, v50
	v_ashrrev_i32_e32 v51, 31, v51
	v_and_b32_e32 v51, 0xff800000, v51
	s_waitcnt lgkmcnt(0)
	v_add_f32_e32 v47, v47, v50
	v_add_f32_e32 v47, v47, v51
	v_sub_u32_e32 v51, v17, v106
	v_sub_u32_e32 v52, v16, v51
	v_or_b32_e32 v52, v52, v51
	v_and_b32_e32 v51, 0x7f, v51
	v_lshl_add_u32 v51, v51, 2, s97
	ds_read_b32 v51, v51
	v_ashrrev_i32_e32 v52, 31, v52
	v_and_b32_e32 v52, 0xff800000, v52
	v_max3_f32 v50, v54, v46, v47
	s_waitcnt lgkmcnt(0)
	v_add_f32_e32 v48, v48, v51
	v_sub_u32_e32 v51, v17, v107
	v_add_f32_e32 v48, v48, v52
	v_sub_u32_e32 v52, v16, v51
	v_or_b32_e32 v52, v52, v51
	v_and_b32_e32 v51, 0x7f, v51
	v_lshl_add_u32 v51, v51, 2, s97
	ds_read_b32 v51, v51
	v_ashrrev_i32_e32 v52, 31, v52
	v_and_b32_e32 v52, 0xff800000, v52
	s_waitcnt lgkmcnt(0)
	v_add_f32_e32 v49, v49, v51
	v_add_f32_e32 v49, v49, v52
	v_max3_f32 v54, v50, v48, v49
	ds_read_b128 v[50:53], v108
	ds_read_b128 v[164:167], v108 offset:64
	s_waitcnt lgkmcnt(1)
	v_mfma_f32_16x16x32_bf16 v[50:53], v[50:53], v[2:5], 0
	s_waitcnt lgkmcnt(0)
	v_mfma_f32_16x16x32_bf16 v[50:53], v[164:167], v[6:9], v[50:53]
	v_sub_u32_e32 v164, v16, v55
	v_or_b32_e32 v164, v164, v55
	v_and_b32_e32 v55, 0x7f, v55
	v_lshl_add_u32 v55, v55, 2, s97
	ds_read_b32 v55, v55
	v_ashrrev_i32_e32 v164, 31, v164
	v_and_b32_e32 v164, 0xff800000, v164
	s_waitcnt lgkmcnt(0)
	v_add_f32_e32 v50, v50, v55
	v_sub_u32_e32 v55, v17, v110
	v_add_f32_e32 v50, v50, v164
	v_sub_u32_e32 v164, v16, v55
	v_or_b32_e32 v164, v164, v55
	v_and_b32_e32 v55, 0x7f, v55
	v_lshl_add_u32 v55, v55, 2, s97
	ds_read_b32 v55, v55
	v_ashrrev_i32_e32 v164, 31, v164
	v_and_b32_e32 v164, 0xff800000, v164
	s_waitcnt lgkmcnt(0)
	v_add_f32_e32 v51, v51, v55
	v_sub_u32_e32 v55, v17, v111
	v_add_f32_e32 v51, v51, v164
	v_sub_u32_e32 v164, v16, v55
	v_or_b32_e32 v164, v164, v55
	v_and_b32_e32 v55, 0x7f, v55
	v_lshl_add_u32 v55, v55, 2, s97
	ds_read_b32 v55, v55
	v_ashrrev_i32_e32 v164, 31, v164
	v_and_b32_e32 v164, 0xff800000, v164
	v_max3_f32 v54, v54, v50, v51
	s_waitcnt lgkmcnt(0)
	v_add_f32_e32 v52, v52, v55
	v_sub_u32_e32 v55, v17, v112
	v_add_f32_e32 v52, v52, v164
	v_sub_u32_e32 v164, v16, v55
	v_or_b32_e32 v164, v164, v55
	v_and_b32_e32 v55, 0x7f, v55
	v_lshl_add_u32 v55, v55, 2, s97
	ds_read_b32 v55, v55
	v_ashrrev_i32_e32 v164, 31, v164
	v_and_b32_e32 v164, 0xff800000, v164
	s_waitcnt lgkmcnt(0)
	v_add_f32_e32 v53, v53, v55
	v_add_f32_e32 v53, v53, v164
	ds_read_b128 v[164:167], v113
	ds_read_b128 v[168:171], v113 offset:64
	v_max3_f32 v172, v54, v52, v53
	v_sub_u32_e32 v54, v17, v114
	s_waitcnt lgkmcnt(1)
	v_mfma_f32_16x16x32_bf16 v[164:167], v[164:167], v[2:5], 0
	v_sub_u32_e32 v55, v16, v54
	v_or_b32_e32 v55, v55, v54
	v_and_b32_e32 v54, 0x7f, v54
	v_lshl_add_u32 v54, v54, 2, s97
	ds_read_b32 v54, v54
	s_waitcnt lgkmcnt(1)
	v_mfma_f32_16x16x32_bf16 v[164:167], v[168:171], v[6:9], v[164:167]
	v_ashrrev_i32_e32 v55, 31, v55
	v_and_b32_e32 v55, 0xff800000, v55
	s_waitcnt lgkmcnt(0)
	s_nop 4
	v_add_f32_e32 v54, v164, v54
	v_add_f32_e32 v54, v54, v55
	v_sub_u32_e32 v55, v17, v115
	v_sub_u32_e32 v164, v16, v55
	v_or_b32_e32 v164, v164, v55
	v_and_b32_e32 v55, 0x7f, v55
	v_lshl_add_u32 v55, v55, 2, s97
	ds_read_b32 v55, v55
	v_ashrrev_i32_e32 v164, 31, v164
	v_and_b32_e32 v164, 0xff800000, v164
	s_waitcnt lgkmcnt(0)
	v_add_f32_e32 v55, v165, v55
	v_add_f32_e32 v55, v55, v164
	v_sub_u32_e32 v164, v17, v116
	v_sub_u32_e32 v165, v16, v164
	v_or_b32_e32 v165, v165, v164
	v_and_b32_e32 v164, 0x7f, v164
	v_lshl_add_u32 v164, v164, 2, s97
	ds_read_b32 v164, v164
	v_ashrrev_i32_e32 v165, 31, v165
	v_and_b32_e32 v165, 0xff800000, v165
	v_max3_f32 v168, v172, v54, v55
	s_waitcnt lgkmcnt(0)
	v_add_f32_e32 v164, v166, v164
	v_add_f32_e32 v164, v164, v165
	v_sub_u32_e32 v165, v17, v117
	v_sub_u32_e32 v166, v16, v165
	v_or_b32_e32 v166, v166, v165
	v_and_b32_e32 v165, 0x7f, v165
	v_lshl_add_u32 v165, v165, 2, s97
	ds_read_b32 v165, v165
	v_ashrrev_i32_e32 v166, 31, v166
	v_and_b32_e32 v166, 0xff800000, v166
	s_waitcnt lgkmcnt(0)
	v_add_f32_e32 v165, v167, v165
	v_add_f32_e32 v165, v165, v166
	v_max3_f32 v174, v168, v164, v165
	ds_read_b128 v[166:169], v118
	ds_read_b128 v[170:173], v118 offset:64
	s_waitcnt lgkmcnt(1)
	v_mfma_f32_16x16x32_bf16 v[166:169], v[166:169], v[2:5], 0
	s_waitcnt lgkmcnt(0)
	v_mfma_f32_16x16x32_bf16 v[166:169], v[170:173], v[6:9], v[166:169]
	v_sub_u32_e32 v170, v17, v119
	v_sub_u32_e32 v171, v16, v170
	v_or_b32_e32 v171, v171, v170
	v_and_b32_e32 v170, 0x7f, v170
	v_lshl_add_u32 v170, v170, 2, s97
	ds_read_b32 v170, v170
	v_ashrrev_i32_e32 v171, 31, v171
	v_and_b32_e32 v171, 0xff800000, v171
	s_waitcnt lgkmcnt(0)
	v_add_f32_e32 v166, v166, v170
	v_sub_u32_e32 v170, v17, v120
	v_add_f32_e32 v166, v166, v171
	v_sub_u32_e32 v171, v16, v170
	v_or_b32_e32 v171, v171, v170
	v_and_b32_e32 v170, 0x7f, v170
	v_lshl_add_u32 v170, v170, 2, s97
	ds_read_b32 v170, v170
	v_ashrrev_i32_e32 v171, 31, v171
	v_and_b32_e32 v171, 0xff800000, v171
	s_waitcnt lgkmcnt(0)
	v_add_f32_e32 v167, v167, v170
	v_add_f32_e32 v167, v167, v171
	v_sub_u32_e32 v171, v17, v121
	v_sub_u32_e32 v172, v16, v171
	v_or_b32_e32 v172, v172, v171
	v_and_b32_e32 v171, 0x7f, v171
	v_lshl_add_u32 v171, v171, 2, s97
	ds_read_b32 v171, v171
	v_ashrrev_i32_e32 v172, 31, v172
	v_and_b32_e32 v172, 0xff800000, v172
	v_max3_f32 v170, v174, v166, v167
	s_waitcnt lgkmcnt(0)
	v_add_f32_e32 v168, v168, v171
	v_sub_u32_e32 v171, v17, v122
	v_add_f32_e32 v168, v168, v172
	v_sub_u32_e32 v172, v16, v171
	v_or_b32_e32 v172, v172, v171
	v_and_b32_e32 v171, 0x7f, v171
	v_lshl_add_u32 v171, v171, 2, s97
	ds_read_b32 v171, v171
	v_ashrrev_i32_e32 v172, 31, v172
	v_and_b32_e32 v172, 0xff800000, v172
	s_waitcnt lgkmcnt(0)
	v_add_f32_e32 v169, v169, v171
	v_add_f32_e32 v169, v169, v172
	v_max3_f32 v178, v170, v168, v169
	ds_read_b128 v[170:173], v123
	ds_read_b128 v[174:177], v123 offset:64
	s_waitcnt lgkmcnt(1)
	v_mfma_f32_16x16x32_bf16 v[2:5], v[170:173], v[2:5], 0
	s_waitcnt lgkmcnt(0)
	v_mfma_f32_16x16x32_bf16 v[2:5], v[174:177], v[6:9], v[2:5]
	v_sub_u32_e32 v6, v17, v124
	v_sub_u32_e32 v7, v16, v6
	v_or_b32_e32 v7, v7, v6
	v_and_b32_e32 v6, 0x7f, v6
	v_lshl_add_u32 v6, v6, 2, s97
	ds_read_b32 v6, v6
	v_ashrrev_i32_e32 v7, 31, v7
	v_and_b32_e32 v7, 0xff800000, v7
	s_waitcnt lgkmcnt(0)
	v_add_f32_e32 v2, v2, v6
	v_add_f32_e32 v170, v2, v7
	v_sub_u32_e32 v2, v17, v125
	v_sub_u32_e32 v6, v16, v2
	v_or_b32_e32 v6, v6, v2
	v_and_b32_e32 v2, 0x7f, v2
	v_lshl_add_u32 v2, v2, 2, s97
	ds_read_b32 v2, v2
	v_ashrrev_i32_e32 v6, 31, v6
	v_and_b32_e32 v6, 0xff800000, v6
	s_waitcnt lgkmcnt(0)
	v_add_f32_e32 v2, v3, v2
	v_sub_u32_e32 v3, v17, v126
	v_add_f32_e32 v171, v2, v6
	v_sub_u32_e32 v6, v16, v3
	v_or_b32_e32 v6, v6, v3
	v_and_b32_e32 v3, 0x7f, v3
	v_lshl_add_u32 v3, v3, 2, s97
	ds_read_b32 v3, v3
	v_ashrrev_i32_e32 v6, 31, v6
	v_and_b32_e32 v6, 0xff800000, v6
	v_max3_f32 v2, v178, v170, v171
	s_waitcnt lgkmcnt(0)
	v_add_f32_e32 v3, v4, v3
	v_add_f32_e32 v172, v3, v6
	v_sub_u32_e32 v3, v17, v127
	v_sub_u32_e32 v4, v16, v3
	v_or_b32_e32 v4, v4, v3
	v_and_b32_e32 v3, 0x7f, v3
	v_lshl_add_u32 v3, v3, 2, s97
	ds_read_b32 v3, v3
	v_ashrrev_i32_e32 v4, 31, v4
	v_and_b32_e32 v4, 0xff800000, v4
	s_waitcnt lgkmcnt(0)
	v_add_f32_e32 v3, v5, v3
	v_add_f32_e32 v173, v3, v4
	v_max3_f32 v2, v2, v172, v173
	ds_swizzle_b32 v3, v2 offset:swizzle(SWAP,16)
	s_waitcnt lgkmcnt(0)
	v_max_f32_e32 v3, v3, v3
	v_max_f32_e32 v2, v2, v3
	ds_bpermute_b32 v3, v19, v2
	s_waitcnt vmcnt(0) lgkmcnt(0)
	v_max3_f32 v174, v2, v3, v163
	v_sub_f32_e32 v2, v12, v174
	v_mul_f32_e32 v2, 0x3fb8aa3b, v2
	v_sub_f32_e32 v3, v13, v174
	v_exp_f32_e32 v2, v2
	v_mul_f32_e32 v3, 0x3fb8aa3b, v3
	v_exp_f32_e32 v3, v3
	v_sub_f32_e32 v7, v30, v174
	v_add_f32_e32 v4, 0, v2
	v_mul_f32_e32 v7, 0x3fb8aa3b, v7
	v_add_f32_e32 v5, v3, v4
	v_sub_f32_e32 v4, v14, v174
	v_mul_f32_e32 v4, 0x3fb8aa3b, v4
	v_exp_f32_e32 v4, v4
	v_exp_f32_e32 v8, v7
	v_sub_f32_e32 v7, v31, v174
	v_mul_f32_e32 v7, 0x3fb8aa3b, v7
	v_add_f32_e32 v6, v4, v5
	v_sub_f32_e32 v5, v15, v174
	v_mul_f32_e32 v5, 0x3fb8aa3b, v5
	v_exp_f32_e32 v5, v5
	v_exp_f32_e32 v9, v7
	v_sub_f32_e32 v7, v32, v174
	v_mul_f32_e32 v7, 0x3fb8aa3b, v7
	v_exp_f32_e32 v16, v7
	v_sub_f32_e32 v7, v33, v174
	v_mul_f32_e32 v7, 0x3fb8aa3b, v7
	v_add_f32_e32 v6, v5, v6
	v_exp_f32_e32 v17, v7
	v_add_f32_e32 v6, v8, v6
	v_add_f32_e32 v6, v9, v6
	v_add_f32_e32 v6, v16, v6
	v_add_f32_e32 v7, v17, v6
	v_sub_f32_e32 v6, v34, v174
	v_mul_f32_e32 v6, 0x3fb8aa3b, v6
	v_exp_f32_e32 v6, v6
	v_sub_f32_e32 v15, v38, v174
	v_mul_f32_e32 v15, 0x3fb8aa3b, v15
	v_exp_f32_e32 v30, v15
	v_add_f32_e32 v12, v6, v7
	v_sub_f32_e32 v7, v35, v174
	v_mul_f32_e32 v7, 0x3fb8aa3b, v7
	v_exp_f32_e32 v7, v7
	v_sub_f32_e32 v15, v39, v174
	v_mul_f32_e32 v15, 0x3fb8aa3b, v15
	v_exp_f32_e32 v31, v15
	v_add_f32_e32 v13, v7, v12
	v_sub_f32_e32 v12, v36, v174
	v_mul_f32_e32 v12, 0x3fb8aa3b, v12
	v_exp_f32_e32 v12, v12
	v_sub_f32_e32 v15, v40, v174
	v_mul_f32_e32 v15, 0x3fb8aa3b, v15
	v_exp_f32_e32 v36, v15
	v_add_f32_e32 v14, v12, v13
	v_sub_f32_e32 v13, v37, v174
	v_mul_f32_e32 v13, 0x3fb8aa3b, v13
	v_exp_f32_e32 v13, v13
	v_sub_f32_e32 v15, v41, v174
	v_mul_f32_e32 v15, 0x3fb8aa3b, v15
	v_exp_f32_e32 v37, v15
	v_add_f32_e32 v14, v13, v14
	v_add_f32_e32 v14, v30, v14
	v_add_f32_e32 v14, v31, v14
	v_add_f32_e32 v14, v36, v14
	v_add_f32_e32 v15, v37, v14
	v_sub_f32_e32 v14, v42, v174
	v_mul_f32_e32 v14, 0x3fb8aa3b, v14
	v_exp_f32_e32 v14, v14
	v_sub_f32_e32 v35, v46, v174
	v_mul_f32_e32 v35, 0x3fb8aa3b, v35
	v_exp_f32_e32 v38, v35
	v_add_f32_e32 v32, v14, v15
	v_sub_f32_e32 v15, v43, v174
	v_mul_f32_e32 v15, 0x3fb8aa3b, v15
	v_exp_f32_e32 v15, v15
	v_sub_f32_e32 v35, v47, v174
	v_mul_f32_e32 v35, 0x3fb8aa3b, v35
	v_exp_f32_e32 v39, v35
	v_add_f32_e32 v33, v15, v32
	v_sub_f32_e32 v32, v44, v174
	v_mul_f32_e32 v32, 0x3fb8aa3b, v32
	v_exp_f32_e32 v32, v32
	v_sub_f32_e32 v35, v48, v174
	v_mul_f32_e32 v35, 0x3fb8aa3b, v35
	v_exp_f32_e32 v44, v35
	v_add_f32_e32 v34, v32, v33
	v_sub_f32_e32 v33, v45, v174
	v_mul_f32_e32 v33, 0x3fb8aa3b, v33
	v_exp_f32_e32 v33, v33
	v_sub_f32_e32 v35, v49, v174
	v_mul_f32_e32 v35, 0x3fb8aa3b, v35
	v_exp_f32_e32 v45, v35
	v_add_f32_e32 v34, v33, v34
	v_add_f32_e32 v34, v38, v34
	v_add_f32_e32 v34, v39, v34
	v_add_f32_e32 v34, v44, v34
	v_add_f32_e32 v35, v45, v34
	v_sub_f32_e32 v34, v50, v174
	v_mul_f32_e32 v34, 0x3fb8aa3b, v34
	v_exp_f32_e32 v34, v34
	v_sub_f32_e32 v43, v54, v174
	v_mul_f32_e32 v43, 0x3fb8aa3b, v43
	v_exp_f32_e32 v46, v43
	v_add_f32_e32 v40, v34, v35
	v_sub_f32_e32 v35, v51, v174
	v_mul_f32_e32 v35, 0x3fb8aa3b, v35
	v_exp_f32_e32 v35, v35
	v_sub_f32_e32 v43, v55, v174
	v_mul_f32_e32 v43, 0x3fb8aa3b, v43
	v_exp_f32_e32 v47, v43
	v_add_f32_e32 v41, v35, v40
	v_sub_f32_e32 v40, v52, v174
	v_mul_f32_e32 v40, 0x3fb8aa3b, v40
	v_exp_f32_e32 v40, v40
	v_sub_f32_e32 v43, v164, v174
	v_mul_f32_e32 v43, 0x3fb8aa3b, v43
	v_exp_f32_e32 v50, v43
	v_add_f32_e32 v42, v40, v41
	v_sub_f32_e32 v41, v53, v174
	v_mul_f32_e32 v41, 0x3fb8aa3b, v41
	v_exp_f32_e32 v41, v41
	v_sub_f32_e32 v43, v165, v174
	v_mul_f32_e32 v43, 0x3fb8aa3b, v43
	v_exp_f32_e32 v51, v43
	v_add_f32_e32 v42, v41, v42
	v_add_f32_e32 v42, v46, v42
	v_add_f32_e32 v42, v47, v42
	v_add_f32_e32 v42, v50, v42
	v_add_f32_e32 v43, v51, v42
	v_sub_f32_e32 v42, v166, v174
	v_mul_f32_e32 v42, 0x3fb8aa3b, v42
	v_exp_f32_e32 v42, v42
	v_sub_f32_e32 v163, v163, v174
	v_mul_f32_e32 v163, 0x3fb8aa3b, v163
	v_exp_f32_e32 v163, v163
	v_add_f32_e32 v48, v42, v43
	v_sub_f32_e32 v43, v167, v174
	v_mul_f32_e32 v43, 0x3fb8aa3b, v43
	v_exp_f32_e32 v43, v43
	s_nop 0
	v_add_f32_e32 v49, v43, v48
	v_sub_f32_e32 v48, v168, v174
	v_mul_f32_e32 v48, 0x3fb8aa3b, v48
	v_exp_f32_e32 v48, v48
	s_nop 0
	v_add_f32_e32 v52, v48, v49
	v_sub_f32_e32 v49, v169, v174
	v_mul_f32_e32 v49, 0x3fb8aa3b, v49
	v_exp_f32_e32 v49, v49
	s_nop 0
	v_add_f32_e32 v53, v49, v52
	v_sub_f32_e32 v52, v170, v174
	v_mul_f32_e32 v52, 0x3fb8aa3b, v52
	v_exp_f32_e32 v52, v52
	s_nop 0
	v_add_f32_e32 v54, v52, v53
	v_sub_f32_e32 v53, v171, v174
	v_mul_f32_e32 v53, 0x3fb8aa3b, v53
	v_exp_f32_e32 v53, v53
	s_nop 0
	v_add_f32_e32 v55, v53, v54
	v_sub_f32_e32 v54, v172, v174
	v_mul_f32_e32 v54, 0x3fb8aa3b, v54
	v_exp_f32_e32 v54, v54
	s_nop 0
	v_add_f32_e32 v164, v54, v55
	v_sub_f32_e32 v55, v173, v174
	v_mul_f32_e32 v55, 0x3fb8aa3b, v55
	v_exp_f32_e32 v55, v55
	s_nop 0
	v_add_f32_e32 v164, v55, v164
	ds_swizzle_b32 v165, v164 offset:swizzle(SWAP,16)
	s_waitcnt lgkmcnt(0)
	v_add_f32_e32 v164, v164, v165
	ds_bpermute_b32 v165, v19, v164
	s_waitcnt lgkmcnt(0)
	v_add_f32_e32 v164, v164, v165
	v_add_f32_e32 v163, v163, v164
	v_div_scale_f32 v164, s[2:3], v163, v163, 1.0
	v_rcp_f32_e32 v165, v164
	s_nop 0
	v_fma_f32 v166, -v164, v165, 1.0
	v_fmac_f32_e32 v165, v166, v165
	v_div_scale_f32 v166, vcc, 1.0, v163, 1.0
	v_mul_f32_e32 v167, v166, v165
	v_fma_f32 v168, -v164, v167, v166
	v_fmac_f32_e32 v167, v168, v165
	v_fma_f32 v164, -v164, v167, v166
	v_div_fmas_f32 v164, v164, v165, v167
	v_div_fixup_f32 v180, v164, v163, 1.0
	v_pk_mul_f32 v[4:5], v[4:5], v[180:181] op_sel_hi:[1,0]
	v_pk_mul_f32 v[2:3], v[2:3], v[180:181] op_sel_hi:[1,0]
	v_pk_mul_f32 v[16:17], v[16:17], v[180:181] op_sel_hi:[1,0]
	v_pk_mul_f32 v[8:9], v[8:9], v[180:181] op_sel_hi:[1,0]
	v_cvt_pk_bf16_f32 v2, v2, v3
	v_cvt_pk_bf16_f32 v3, v4, v5
	v_pk_mul_f32 v[6:7], v[6:7], v[180:181] op_sel_hi:[1,0]
	v_cvt_pk_bf16_f32 v4, v8, v9
	v_cvt_pk_bf16_f32 v5, v16, v17
	ds_read2_b64 v[164:167], v137 offset1:4
	ds_read2_b64 v[168:171], v138 offset0:32 offset1:36
	ds_read2_b64 v[172:175], v139 offset0:64 offset1:68
	ds_read2_b64 v[176:179], v140 offset0:96 offset1:100
	v_pk_mul_f32 v[8:9], v[12:13], v[180:181] op_sel_hi:[1,0]
	s_waitcnt lgkmcnt(3)
	v_mfma_f32_16x16x32_bf16 v[164:167], v[164:167], v[2:5], 0
	v_mul_f32_e64 v12, v36, v180
	v_mul_f32_e64 v13, v37, v180
	v_pk_mul_f32 v[16:17], v[30:31], v[180:181] op_sel_hi:[1,0]
	v_cvt_pk_bf16_f32 v6, v6, v7
	s_waitcnt lgkmcnt(2)
	v_mfma_f32_16x16x32_bf16 v[168:171], v[168:171], v[2:5], 0
	v_cvt_pk_bf16_f32 v7, v8, v9
	v_cvt_pk_bf16_f32 v8, v16, v17
	v_cvt_pk_bf16_f32 v9, v12, v13
	s_waitcnt lgkmcnt(1)
	v_mfma_f32_16x16x32_bf16 v[172:175], v[172:175], v[2:5], 0
	v_mul_f32_e64 v12, v44, v180
	v_mul_f32_e64 v13, v45, v180
	v_pk_mul_f32 v[16:17], v[50:51], v[180:181] op_sel_hi:[1,0]
	s_waitcnt lgkmcnt(0)
	v_mfma_f32_16x16x32_bf16 v[2:5], v[176:179], v[2:5], 0
	ds_read2_b64 v[176:179], v58 offset1:4
	s_waitcnt lgkmcnt(0)
	v_mfma_f32_16x16x32_bf16 v[164:167], v[176:179], v[6:9], v[164:167]
	ds_read2_b64 v[176:179], v59 offset0:32 offset1:36
	s_waitcnt lgkmcnt(0)
	v_mfma_f32_16x16x32_bf16 v[168:171], v[176:179], v[6:9], v[168:171]
	ds_read2_b64 v[176:179], v60 offset0:64 offset1:68
	ds_read2_b64 v[58:61], v61 offset0:96 offset1:100
	s_waitcnt lgkmcnt(1)
	v_mfma_f32_16x16x32_bf16 v[172:175], v[176:179], v[6:9], v[172:175]
	s_waitcnt lgkmcnt(0)
	v_mfma_f32_16x16x32_bf16 v[2:5], v[58:61], v[6:9], v[2:5]
	v_mul_f32_e64 v8, v32, v180
	v_mul_f32_e64 v9, v33, v180
	v_pk_mul_f32 v[6:7], v[14:15], v[180:181] op_sel_hi:[1,0]
	v_pk_mul_f32 v[14:15], v[38:39], v[180:181] op_sel_hi:[1,0]
	v_cvt_pk_bf16_f32 v6, v6, v7
	v_cvt_pk_bf16_f32 v7, v8, v9
	s_nop 0
	v_cvt_pk_bf16_f32 v8, v14, v15
	v_cvt_pk_bf16_f32 v9, v12, v13
	ds_read2_b64 v[12:15], v56 offset1:4
	ds_read2_b64 v[30:33], v57 offset0:32 offset1:36
	ds_read2_b64 v[36:39], v62 offset0:64 offset1:68
	ds_read2_b64 v[56:59], v63 offset0:96 offset1:100
	s_waitcnt lgkmcnt(3)
	v_mfma_f32_16x16x32_bf16 v[12:15], v[12:15], v[6:9], v[164:167]
	s_waitcnt lgkmcnt(2)
	v_mfma_f32_16x16x32_bf16 v[30:33], v[30:33], v[6:9], v[168:171]
	s_waitcnt lgkmcnt(1)
	v_mfma_f32_16x16x32_bf16 v[36:39], v[36:39], v[6:9], v[172:175]
	s_waitcnt lgkmcnt(0)
	v_mfma_f32_16x16x32_bf16 v[2:5], v[56:59], v[6:9], v[2:5]
	v_mul_f32_e64 v8, v40, v180
	v_mul_f32_e64 v9, v41, v180
	v_pk_mul_f32 v[6:7], v[34:35], v[180:181] op_sel_hi:[1,0]
	v_pk_mul_f32 v[34:35], v[46:47], v[180:181] op_sel_hi:[1,0]
	v_cvt_pk_bf16_f32 v6, v6, v7
	v_cvt_pk_bf16_f32 v7, v8, v9
	s_nop 0
	v_cvt_pk_bf16_f32 v8, v34, v35
	v_cvt_pk_bf16_f32 v9, v16, v17
	ds_read2_b64 v[44:47], v64 offset1:4
	s_waitcnt lgkmcnt(0)
	v_mfma_f32_16x16x32_bf16 v[12:15], v[44:47], v[6:9], v[12:15]
	ds_read2_b64 v[44:47], v65 offset0:32 offset1:36
	v_pk_mul_f32 v[16:17], v[54:55], v[180:181] op_sel_hi:[1,0]
	s_waitcnt lgkmcnt(0)
	v_mfma_f32_16x16x32_bf16 v[30:33], v[44:47], v[6:9], v[30:33]
	ds_read2_b64 v[44:47], v141 offset0:64 offset1:68
	s_waitcnt lgkmcnt(0)
	v_mfma_f32_16x16x32_bf16 v[34:37], v[44:47], v[6:9], v[36:39]
	s_nop 2
	ds_read2_b64 v[38:41], v142 offset0:96 offset1:100
	s_waitcnt lgkmcnt(0)
	v_mfma_f32_16x16x32_bf16 v[2:5], v[38:41], v[6:9], v[2:5]
	v_mul_f32_e64 v8, v48, v180
	v_mul_f32_e64 v9, v49, v180
	v_pk_mul_f32 v[6:7], v[42:43], v[180:181] op_sel_hi:[1,0]
	v_pk_mul_f32 v[38:39], v[52:53], v[180:181] op_sel_hi:[1,0]
	v_cvt_pk_bf16_f32 v6, v6, v7
	v_cvt_pk_bf16_f32 v7, v8, v9
	s_nop 0
	v_cvt_pk_bf16_f32 v8, v38, v39
	v_cvt_pk_bf16_f32 v9, v16, v17
	ds_read2_b64 v[38:41], v143 offset1:4
	s_waitcnt lgkmcnt(0)
	v_mfma_f32_16x16x32_bf16 v[12:15], v[38:41], v[6:9], v[12:15]
	ds_read2_b64 v[38:41], v144 offset0:32 offset1:36
	s_waitcnt lgkmcnt(0)
	v_mfma_f32_16x16x32_bf16 v[30:33], v[38:41], v[6:9], v[30:33]
	ds_read2_b64 v[38:41], v145 offset0:64 offset1:68
	s_waitcnt lgkmcnt(0)
	v_mfma_f32_16x16x32_bf16 v[34:37], v[38:41], v[6:9], v[34:37]
	ds_read2_b64 v[38:41], v162 offset0:96 offset1:100
	s_waitcnt lgkmcnt(0)
	v_mfma_f32_16x16x32_bf16 v[2:5], v[38:41], v[6:9], v[2:5]
	v_lshl_add_u64 v[6:7], v[10:11], 0, s[88:89]
	v_cvt_pk_bf16_f32 v8, v12, v13
	v_cvt_pk_bf16_f32 v9, v14, v15
	global_store_dwordx2 v[6:7], v[8:9], off
	v_cvt_pk_bf16_f32 v8, v30, v31
	v_cvt_pk_bf16_f32 v9, v32, v33
	global_store_dwordx2 v[6:7], v[8:9], off offset:32
	v_cvt_pk_bf16_f32 v8, v34, v35
	v_cvt_pk_bf16_f32 v9, v36, v37
	global_store_dwordx2 v[6:7], v[8:9], off offset:64
	v_cvt_pk_bf16_f32 v2, v2, v3
	v_cvt_pk_bf16_f32 v3, v4, v5
	s_nop 3
	global_store_dwordx2 v[6:7], v[2:3], off offset:96
	s_cbranch_scc0 .LBB0_115
.LBB0_126:
	s_cmpk_lg_u32 s92, 0x100
	s_cbranch_scc1 .Lattn_s_generic
	s_mov_b64 s[54:55], exec
	s_waitcnt lgkmcnt(0)
	s_load_dwordx2 s[38:39], s[80:81], 0x20
	s_load_dwordx2 s[40:41], s[80:81], 0x28
	s_load_dwordx2 s[56:57], s[80:81], 0xd0
	s_lshr_b32 s45, s90, 1
	s_and_b32 s46, s90, 1
	v_readfirstlane_b32 s47, v204
	v_and_b32_e32 v0, 15, v204
	v_lshrrev_b32_e32 v2, 4, v204
	s_lshr_b32 s47, s47, 6
	s_lshl_b32 s44, s46, 3
	s_add_i32 s44, s44, s47
	s_lshl_b32 s2, s45, 16
	s_lshl_b32 s3, s46, 8
	s_add_i32 s2, s2, s3
	v_lshlrev_b32_e32 v3, 9, v2
	v_lshl_add_u32 v3, v0, 4, v3
	v_add_u32_e32 v3, s2, v3
	v_add_u32_e32 v4, 0x4000, v3
	v_add_u32_e32 v5, 0x8000, v3
	v_add_u32_e32 v6, 0xc000, v3
	s_waitcnt lgkmcnt(0)
	global_load_dwordx4 v[20:23], v3, s[38:39]
	global_load_dwordx4 v[24:27], v4, s[38:39]
	global_load_dwordx4 v[28:31], v5, s[38:39]
	global_load_dwordx4 v[32:35], v6, s[38:39]
	global_load_dwordx4 v[36:39], v3, s[40:41]
	global_load_dwordx4 v[40:43], v4, s[40:41]
	global_load_dwordx4 v[44:47], v5, s[40:41]
	global_load_dwordx4 v[48:51], v6, s[40:41]
	s_add_u32 s8, s10, 0x13140000
	s_addc_u32 s9, s11, 0
	s_lshl_b32 s2, s45, 11
	s_lshl_b32 s3, s46, 7
	s_add_i32 s2, s2, s3
	s_add_i32 s2, s2, 0x800000
	v_and_b32_e32 v7, 63, v204
	v_bfe_u32 v8, v204, 6, 2
	v_lshrrev_b32_e32 v9, 8, v204
	v_lshlrev_b32_e32 v10, 1, v7
	v_lshl_add_u32 v10, v8, 9, v10
	v_lshl_add_u32 v10, v9, 8, v10
	v_add_u32_e32 v10, s2, v10
	global_load_ushort v52, v10, s[8:9]
	s_add_u32 s42, s10, 0xb580000
	s_addc_u32 s43, s11, 0
	s_lshl_b32 s2, s45, 13
	s_lshl_b32 s3, s44, 7
	s_add_i32 s2, s2, s3
	s_add_i32 s22, s2, 0x2000000
	v_lshl_add_u32 v11, v7, 1, s22
	v_add_u32_e32 v12, 0x1000, v11
	global_load_ushort v56, v11, s[42:43]
	global_load_ushort v57, v11, s[42:43] offset:2048
	global_load_ushort v58, v12, s[42:43]
	global_load_ushort v59, v12, s[42:43] offset:2048
	s_lshl_b32 s2, s44, 2
	s_cmp_gt_u32 s82, 30
	s_cselect_b32 s3, 64, 0
	s_add_i32 s2, s2, s3
	s_load_dword s58, s[56:57], s2
	v_mul_u32_u24_e32 v13, 272, v2
	v_lshl_add_u32 v13, v0, 4, v13
	v_lshlrev_b32_e32 v14, 8, v2
	v_lshl_add_u32 v14, v0, 4, v14
	v_add_u32_e32 v14, 0x9000, v14
	s_barrier
	s_waitcnt vmcnt(12)
	ds_write_b128 v13, v[20:23]
	s_waitcnt vmcnt(11)
	ds_write_b128 v13, v[24:27] offset:8704
	s_waitcnt vmcnt(10)
	ds_write_b128 v13, v[28:31] offset:17408
	s_waitcnt vmcnt(9)
	ds_write_b128 v13, v[32:35] offset:26112
	s_waitcnt vmcnt(8)
	ds_write_b128 v14, v[36:39]
	s_waitcnt vmcnt(7)
	ds_write_b128 v14, v[40:43] offset:8192
	s_waitcnt vmcnt(6)
	ds_write_b128 v14, v[44:47] offset:16384
	s_waitcnt vmcnt(5)
	ds_write_b128 v14, v[48:51] offset:24576
	v_mul_u32_u24_e32 v15, 272, v8
	v_add_u32_e32 v15, 34816, v15
	v_lshlrev_b32_e32 v16, 8, v8
	v_add_u32_e32 v16, 69632, v16
	v_cmp_eq_u32_e32 vcc, 0, v9
	s_nop 1
	v_cndmask_b32_e32 v15, v16, v15, vcc
	v_lshl_add_u32 v15, v7, 2, v15
	s_waitcnt vmcnt(4)
	v_lshlrev_b32_e32 v52, 16, v52
	ds_write_b32 v15, v52
	s_lshl_b32 s3, s47, 12
	s_add_i32 s59, s3, 0x12000
	v_lshl_add_u32 v17, v7, 4, s59
	s_waitcnt vmcnt(0)
	v_lshlrev_b32_e32 v56, 16, v56
	v_lshlrev_b32_e32 v57, 16, v57
	v_lshlrev_b32_e32 v58, 16, v58
	v_lshlrev_b32_e32 v59, 16, v59
	ds_write_b128 v17, v[56:59]
	s_waitcnt lgkmcnt(0)
	s_barrier
	v_mul_u32_u24_e32 v19, 272, v7
	v_min_u32_e32 v2, 3, v7
	v_mul_u32_u24_e32 v2, 272, v2
	v_add_u32_e32 v2, 34816, v2
	v_mov_b32_e32 v3, s59
	v_mov_b32_e32 v20, 0
	v_mov_b32_e32 v21, 0
	v_mov_b32_e32 v22, 0
	v_mov_b32_e32 v23, 0
	v_mov_b32_e32 v24, 0
	v_mov_b32_e32 v25, 0
	v_mov_b32_e32 v26, 0
	v_mov_b32_e32 v27, 0
	v_mov_b32_e32 v28, 0
	v_mov_b32_e32 v29, 0
	v_mov_b32_e32 v30, 0
	v_mov_b32_e32 v31, 0
	ds_read_b128 v[32:35], v19 offset:0
	ds_read_b128 v[36:39], v19 offset:17408
	ds_read_b128 v[40:43], v2 offset:0
	ds_read_b128 v[56:59], v3 offset:0
	ds_read_b128 v[60:63], v3 offset:16
	ds_read_b128 v[64:67], v3 offset:32
	ds_read_b128 v[68:71], v3 offset:48
	ds_read_b128 v[44:47], v19 offset:16
	ds_read_b128 v[48:51], v19 offset:17424
	ds_read_b128 v[52:55], v2 offset:16
	s_waitcnt lgkmcnt(7)
	s_waitcnt lgkmcnt(6)
	v_fmac_f32_e32 v20, v56, v32
	v_fmac_f32_e32 v21, v57, v32
	v_fmac_f32_e32 v22, v58, v32
	v_fmac_f32_e32 v23, v59, v32
	v_fmac_f32_e32 v24, v56, v36
	v_fmac_f32_e32 v25, v57, v36
	v_fmac_f32_e32 v26, v58, v36
	v_fmac_f32_e32 v27, v59, v36
	v_fmac_f32_e32 v28, v56, v40
	v_fmac_f32_e32 v29, v57, v40
	v_fmac_f32_e32 v30, v58, v40
	v_fmac_f32_e32 v31, v59, v40
	ds_read_b128 v[56:59], v3 offset:64
	s_waitcnt lgkmcnt(6)
	v_fmac_f32_e32 v20, v60, v33
	v_fmac_f32_e32 v21, v61, v33
	v_fmac_f32_e32 v22, v62, v33
	v_fmac_f32_e32 v23, v63, v33
	v_fmac_f32_e32 v24, v60, v37
	v_fmac_f32_e32 v25, v61, v37
	v_fmac_f32_e32 v26, v62, v37
	v_fmac_f32_e32 v27, v63, v37
	v_fmac_f32_e32 v28, v60, v41
	v_fmac_f32_e32 v29, v61, v41
	v_fmac_f32_e32 v30, v62, v41
	v_fmac_f32_e32 v31, v63, v41
	ds_read_b128 v[60:63], v3 offset:80
	s_waitcnt lgkmcnt(6)
	v_fmac_f32_e32 v20, v64, v34
	v_fmac_f32_e32 v21, v65, v34
	v_fmac_f32_e32 v22, v66, v34
	v_fmac_f32_e32 v23, v67, v34
	v_fmac_f32_e32 v24, v64, v38
	v_fmac_f32_e32 v25, v65, v38
	v_fmac_f32_e32 v26, v66, v38
	v_fmac_f32_e32 v27, v67, v38
	v_fmac_f32_e32 v28, v64, v42
	v_fmac_f32_e32 v29, v65, v42
	v_fmac_f32_e32 v30, v66, v42
	v_fmac_f32_e32 v31, v67, v42
	ds_read_b128 v[64:67], v3 offset:96
	s_waitcnt lgkmcnt(6)
	v_fmac_f32_e32 v20, v68, v35
	v_fmac_f32_e32 v21, v69, v35
	v_fmac_f32_e32 v22, v70, v35
	v_fmac_f32_e32 v23, v71, v35
	v_fmac_f32_e32 v24, v68, v39
	v_fmac_f32_e32 v25, v69, v39
	v_fmac_f32_e32 v26, v70, v39
	v_fmac_f32_e32 v27, v71, v39
	v_fmac_f32_e32 v28, v68, v43
	v_fmac_f32_e32 v29, v69, v43
	v_fmac_f32_e32 v30, v70, v43
	v_fmac_f32_e32 v31, v71, v43
	ds_read_b128 v[68:71], v3 offset:112
	ds_read_b128 v[32:35], v19 offset:32
	ds_read_b128 v[36:39], v19 offset:17440
	ds_read_b128 v[40:43], v2 offset:32
	s_waitcnt lgkmcnt(7)
	s_waitcnt lgkmcnt(6)
	v_fmac_f32_e32 v20, v56, v44
	v_fmac_f32_e32 v21, v57, v44
	v_fmac_f32_e32 v22, v58, v44
	v_fmac_f32_e32 v23, v59, v44
	v_fmac_f32_e32 v24, v56, v48
	v_fmac_f32_e32 v25, v57, v48
	v_fmac_f32_e32 v26, v58, v48
	v_fmac_f32_e32 v27, v59, v48
	v_fmac_f32_e32 v28, v56, v52
	v_fmac_f32_e32 v29, v57, v52
	v_fmac_f32_e32 v30, v58, v52
	v_fmac_f32_e32 v31, v59, v52
	ds_read_b128 v[56:59], v3 offset:128
	s_waitcnt lgkmcnt(6)
	v_fmac_f32_e32 v20, v60, v45
	v_fmac_f32_e32 v21, v61, v45
	v_fmac_f32_e32 v22, v62, v45
	v_fmac_f32_e32 v23, v63, v45
	v_fmac_f32_e32 v24, v60, v49
	v_fmac_f32_e32 v25, v61, v49
	v_fmac_f32_e32 v26, v62, v49
	v_fmac_f32_e32 v27, v63, v49
	v_fmac_f32_e32 v28, v60, v53
	v_fmac_f32_e32 v29, v61, v53
	v_fmac_f32_e32 v30, v62, v53
	v_fmac_f32_e32 v31, v63, v53
	ds_read_b128 v[60:63], v3 offset:144
	s_waitcnt lgkmcnt(6)
	v_fmac_f32_e32 v20, v64, v46
	v_fmac_f32_e32 v21, v65, v46
	v_fmac_f32_e32 v22, v66, v46
	v_fmac_f32_e32 v23, v67, v46
	v_fmac_f32_e32 v24, v64, v50
	v_fmac_f32_e32 v25, v65, v50
	v_fmac_f32_e32 v26, v66, v50
	v_fmac_f32_e32 v27, v67, v50
	v_fmac_f32_e32 v28, v64, v54
	v_fmac_f32_e32 v29, v65, v54
	v_fmac_f32_e32 v30, v66, v54
	v_fmac_f32_e32 v31, v67, v54
	ds_read_b128 v[64:67], v3 offset:160
	s_waitcnt lgkmcnt(6)
	v_fmac_f32_e32 v20, v68, v47
	v_fmac_f32_e32 v21, v69, v47
	v_fmac_f32_e32 v22, v70, v47
	v_fmac_f32_e32 v23, v71, v47
	v_fmac_f32_e32 v24, v68, v51
	v_fmac_f32_e32 v25, v69, v51
	v_fmac_f32_e32 v26, v70, v51
	v_fmac_f32_e32 v27, v71, v51
	v_fmac_f32_e32 v28, v68, v55
	v_fmac_f32_e32 v29, v69, v55
	v_fmac_f32_e32 v30, v70, v55
	v_fmac_f32_e32 v31, v71, v55
	ds_read_b128 v[68:71], v3 offset:176
	ds_read_b128 v[44:47], v19 offset:48
	ds_read_b128 v[48:51], v19 offset:17456
	ds_read_b128 v[52:55], v2 offset:48
	s_waitcnt lgkmcnt(7)
	s_waitcnt lgkmcnt(6)
	v_fmac_f32_e32 v20, v56, v32
	v_fmac_f32_e32 v21, v57, v32
	v_fmac_f32_e32 v22, v58, v32
	v_fmac_f32_e32 v23, v59, v32
	v_fmac_f32_e32 v24, v56, v36
	v_fmac_f32_e32 v25, v57, v36
	v_fmac_f32_e32 v26, v58, v36
	v_fmac_f32_e32 v27, v59, v36
	v_fmac_f32_e32 v28, v56, v40
	v_fmac_f32_e32 v29, v57, v40
	v_fmac_f32_e32 v30, v58, v40
	v_fmac_f32_e32 v31, v59, v40
	ds_read_b128 v[56:59], v3 offset:192
	s_waitcnt lgkmcnt(6)
	v_fmac_f32_e32 v20, v60, v33
	v_fmac_f32_e32 v21, v61, v33
	v_fmac_f32_e32 v22, v62, v33
	v_fmac_f32_e32 v23, v63, v33
	v_fmac_f32_e32 v24, v60, v37
	v_fmac_f32_e32 v25, v61, v37
	v_fmac_f32_e32 v26, v62, v37
	v_fmac_f32_e32 v27, v63, v37
	v_fmac_f32_e32 v28, v60, v41
	v_fmac_f32_e32 v29, v61, v41
	v_fmac_f32_e32 v30, v62, v41
	v_fmac_f32_e32 v31, v63, v41
	ds_read_b128 v[60:63], v3 offset:208
	s_waitcnt lgkmcnt(6)
	v_fmac_f32_e32 v20, v64, v34
	v_fmac_f32_e32 v21, v65, v34
	v_fmac_f32_e32 v22, v66, v34
	v_fmac_f32_e32 v23, v67, v34
	v_fmac_f32_e32 v24, v64, v38
	v_fmac_f32_e32 v25, v65, v38
	v_fmac_f32_e32 v26, v66, v38
	v_fmac_f32_e32 v27, v67, v38
	v_fmac_f32_e32 v28, v64, v42
	v_fmac_f32_e32 v29, v65, v42
	v_fmac_f32_e32 v30, v66, v42
	v_fmac_f32_e32 v31, v67, v42
	ds_read_b128 v[64:67], v3 offset:224
	s_waitcnt lgkmcnt(6)
	v_fmac_f32_e32 v20, v68, v35
	v_fmac_f32_e32 v21, v69, v35
	v_fmac_f32_e32 v22, v70, v35
	v_fmac_f32_e32 v23, v71, v35
	v_fmac_f32_e32 v24, v68, v39
	v_fmac_f32_e32 v25, v69, v39
	v_fmac_f32_e32 v26, v70, v39
	v_fmac_f32_e32 v27, v71, v39
	v_fmac_f32_e32 v28, v68, v43
	v_fmac_f32_e32 v29, v69, v43
	v_fmac_f32_e32 v30, v70, v43
	v_fmac_f32_e32 v31, v71, v43
	ds_read_b128 v[68:71], v3 offset:240
	ds_read_b128 v[32:35], v19 offset:64
	ds_read_b128 v[36:39], v19 offset:17472
	ds_read_b128 v[40:43], v2 offset:64
	s_waitcnt lgkmcnt(7)
	s_waitcnt lgkmcnt(6)
	v_fmac_f32_e32 v20, v56, v44
	v_fmac_f32_e32 v21, v57, v44
	v_fmac_f32_e32 v22, v58, v44
	v_fmac_f32_e32 v23, v59, v44
	v_fmac_f32_e32 v24, v56, v48
	v_fmac_f32_e32 v25, v57, v48
	v_fmac_f32_e32 v26, v58, v48
	v_fmac_f32_e32 v27, v59, v48
	v_fmac_f32_e32 v28, v56, v52
	v_fmac_f32_e32 v29, v57, v52
	v_fmac_f32_e32 v30, v58, v52
	v_fmac_f32_e32 v31, v59, v52
	ds_read_b128 v[56:59], v3 offset:256
	s_waitcnt lgkmcnt(6)
	v_fmac_f32_e32 v20, v60, v45
	v_fmac_f32_e32 v21, v61, v45
	v_fmac_f32_e32 v22, v62, v45
	v_fmac_f32_e32 v23, v63, v45
	v_fmac_f32_e32 v24, v60, v49
	v_fmac_f32_e32 v25, v61, v49
	v_fmac_f32_e32 v26, v62, v49
	v_fmac_f32_e32 v27, v63, v49
	v_fmac_f32_e32 v28, v60, v53
	v_fmac_f32_e32 v29, v61, v53
	v_fmac_f32_e32 v30, v62, v53
	v_fmac_f32_e32 v31, v63, v53
	ds_read_b128 v[60:63], v3 offset:272
	s_waitcnt lgkmcnt(6)
	v_fmac_f32_e32 v20, v64, v46
	v_fmac_f32_e32 v21, v65, v46
	v_fmac_f32_e32 v22, v66, v46
	v_fmac_f32_e32 v23, v67, v46
	v_fmac_f32_e32 v24, v64, v50
	v_fmac_f32_e32 v25, v65, v50
	v_fmac_f32_e32 v26, v66, v50
	v_fmac_f32_e32 v27, v67, v50
	v_fmac_f32_e32 v28, v64, v54
	v_fmac_f32_e32 v29, v65, v54
	v_fmac_f32_e32 v30, v66, v54
	v_fmac_f32_e32 v31, v67, v54
	ds_read_b128 v[64:67], v3 offset:288
	s_waitcnt lgkmcnt(6)
	v_fmac_f32_e32 v20, v68, v47
	v_fmac_f32_e32 v21, v69, v47
	v_fmac_f32_e32 v22, v70, v47
	v_fmac_f32_e32 v23, v71, v47
	v_fmac_f32_e32 v24, v68, v51
	v_fmac_f32_e32 v25, v69, v51
	v_fmac_f32_e32 v26, v70, v51
	v_fmac_f32_e32 v27, v71, v51
	v_fmac_f32_e32 v28, v68, v55
	v_fmac_f32_e32 v29, v69, v55
	v_fmac_f32_e32 v30, v70, v55
	v_fmac_f32_e32 v31, v71, v55
	ds_read_b128 v[68:71], v3 offset:304
	ds_read_b128 v[44:47], v19 offset:80
	ds_read_b128 v[48:51], v19 offset:17488
	ds_read_b128 v[52:55], v2 offset:80
	s_waitcnt lgkmcnt(7)
	s_waitcnt lgkmcnt(6)
	v_fmac_f32_e32 v20, v56, v32
	v_fmac_f32_e32 v21, v57, v32
	v_fmac_f32_e32 v22, v58, v32
	v_fmac_f32_e32 v23, v59, v32
	v_fmac_f32_e32 v24, v56, v36
	v_fmac_f32_e32 v25, v57, v36
	v_fmac_f32_e32 v26, v58, v36
	v_fmac_f32_e32 v27, v59, v36
	v_fmac_f32_e32 v28, v56, v40
	v_fmac_f32_e32 v29, v57, v40
	v_fmac_f32_e32 v30, v58, v40
	v_fmac_f32_e32 v31, v59, v40
	ds_read_b128 v[56:59], v3 offset:320
	s_waitcnt lgkmcnt(6)
	v_fmac_f32_e32 v20, v60, v33
	v_fmac_f32_e32 v21, v61, v33
	v_fmac_f32_e32 v22, v62, v33
	v_fmac_f32_e32 v23, v63, v33
	v_fmac_f32_e32 v24, v60, v37
	v_fmac_f32_e32 v25, v61, v37
	v_fmac_f32_e32 v26, v62, v37
	v_fmac_f32_e32 v27, v63, v37
	v_fmac_f32_e32 v28, v60, v41
	v_fmac_f32_e32 v29, v61, v41
	v_fmac_f32_e32 v30, v62, v41
	v_fmac_f32_e32 v31, v63, v41
	ds_read_b128 v[60:63], v3 offset:336
	s_waitcnt lgkmcnt(6)
	v_fmac_f32_e32 v20, v64, v34
	v_fmac_f32_e32 v21, v65, v34
	v_fmac_f32_e32 v22, v66, v34
	v_fmac_f32_e32 v23, v67, v34
	v_fmac_f32_e32 v24, v64, v38
	v_fmac_f32_e32 v25, v65, v38
	v_fmac_f32_e32 v26, v66, v38
	v_fmac_f32_e32 v27, v67, v38
	v_fmac_f32_e32 v28, v64, v42
	v_fmac_f32_e32 v29, v65, v42
	v_fmac_f32_e32 v30, v66, v42
	v_fmac_f32_e32 v31, v67, v42
	ds_read_b128 v[64:67], v3 offset:352
	s_waitcnt lgkmcnt(6)
	v_fmac_f32_e32 v20, v68, v35
	v_fmac_f32_e32 v21, v69, v35
	v_fmac_f32_e32 v22, v70, v35
	v_fmac_f32_e32 v23, v71, v35
	v_fmac_f32_e32 v24, v68, v39
	v_fmac_f32_e32 v25, v69, v39
	v_fmac_f32_e32 v26, v70, v39
	v_fmac_f32_e32 v27, v71, v39
	v_fmac_f32_e32 v28, v68, v43
	v_fmac_f32_e32 v29, v69, v43
	v_fmac_f32_e32 v30, v70, v43
	v_fmac_f32_e32 v31, v71, v43
	ds_read_b128 v[68:71], v3 offset:368
	ds_read_b128 v[32:35], v19 offset:96
	ds_read_b128 v[36:39], v19 offset:17504
	ds_read_b128 v[40:43], v2 offset:96
	s_waitcnt lgkmcnt(7)
	s_waitcnt lgkmcnt(6)
	v_fmac_f32_e32 v20, v56, v44
	v_fmac_f32_e32 v21, v57, v44
	v_fmac_f32_e32 v22, v58, v44
	v_fmac_f32_e32 v23, v59, v44
	v_fmac_f32_e32 v24, v56, v48
	v_fmac_f32_e32 v25, v57, v48
	v_fmac_f32_e32 v26, v58, v48
	v_fmac_f32_e32 v27, v59, v48
	v_fmac_f32_e32 v28, v56, v52
	v_fmac_f32_e32 v29, v57, v52
	v_fmac_f32_e32 v30, v58, v52
	v_fmac_f32_e32 v31, v59, v52
	ds_read_b128 v[56:59], v3 offset:384
	s_waitcnt lgkmcnt(6)
	v_fmac_f32_e32 v20, v60, v45
	v_fmac_f32_e32 v21, v61, v45
	v_fmac_f32_e32 v22, v62, v45
	v_fmac_f32_e32 v23, v63, v45
	v_fmac_f32_e32 v24, v60, v49
	v_fmac_f32_e32 v25, v61, v49
	v_fmac_f32_e32 v26, v62, v49
	v_fmac_f32_e32 v27, v63, v49
	v_fmac_f32_e32 v28, v60, v53
	v_fmac_f32_e32 v29, v61, v53
	v_fmac_f32_e32 v30, v62, v53
	v_fmac_f32_e32 v31, v63, v53
	ds_read_b128 v[60:63], v3 offset:400
	s_waitcnt lgkmcnt(6)
	v_fmac_f32_e32 v20, v64, v46
	v_fmac_f32_e32 v21, v65, v46
	v_fmac_f32_e32 v22, v66, v46
	v_fmac_f32_e32 v23, v67, v46
	v_fmac_f32_e32 v24, v64, v50
	v_fmac_f32_e32 v25, v65, v50
	v_fmac_f32_e32 v26, v66, v50
	v_fmac_f32_e32 v27, v67, v50
	v_fmac_f32_e32 v28, v64, v54
	v_fmac_f32_e32 v29, v65, v54
	v_fmac_f32_e32 v30, v66, v54
	v_fmac_f32_e32 v31, v67, v54
	ds_read_b128 v[64:67], v3 offset:416
	s_waitcnt lgkmcnt(6)
	v_fmac_f32_e32 v20, v68, v47
	v_fmac_f32_e32 v21, v69, v47
	v_fmac_f32_e32 v22, v70, v47
	v_fmac_f32_e32 v23, v71, v47
	v_fmac_f32_e32 v24, v68, v51
	v_fmac_f32_e32 v25, v69, v51
	v_fmac_f32_e32 v26, v70, v51
	v_fmac_f32_e32 v27, v71, v51
	v_fmac_f32_e32 v28, v68, v55
	v_fmac_f32_e32 v29, v69, v55
	v_fmac_f32_e32 v30, v70, v55
	v_fmac_f32_e32 v31, v71, v55
	ds_read_b128 v[68:71], v3 offset:432
	ds_read_b128 v[44:47], v19 offset:112
	ds_read_b128 v[48:51], v19 offset:17520
	ds_read_b128 v[52:55], v2 offset:112
	s_waitcnt lgkmcnt(7)
	s_waitcnt lgkmcnt(6)
	v_fmac_f32_e32 v20, v56, v32
	v_fmac_f32_e32 v21, v57, v32
	v_fmac_f32_e32 v22, v58, v32
	v_fmac_f32_e32 v23, v59, v32
	v_fmac_f32_e32 v24, v56, v36
	v_fmac_f32_e32 v25, v57, v36
	v_fmac_f32_e32 v26, v58, v36
	v_fmac_f32_e32 v27, v59, v36
	v_fmac_f32_e32 v28, v56, v40
	v_fmac_f32_e32 v29, v57, v40
	v_fmac_f32_e32 v30, v58, v40
	v_fmac_f32_e32 v31, v59, v40
	ds_read_b128 v[56:59], v3 offset:448
	s_waitcnt lgkmcnt(6)
	v_fmac_f32_e32 v20, v60, v33
	v_fmac_f32_e32 v21, v61, v33
	v_fmac_f32_e32 v22, v62, v33
	v_fmac_f32_e32 v23, v63, v33
	v_fmac_f32_e32 v24, v60, v37
	v_fmac_f32_e32 v25, v61, v37
	v_fmac_f32_e32 v26, v62, v37
	v_fmac_f32_e32 v27, v63, v37
	v_fmac_f32_e32 v28, v60, v41
	v_fmac_f32_e32 v29, v61, v41
	v_fmac_f32_e32 v30, v62, v41
	v_fmac_f32_e32 v31, v63, v41
	ds_read_b128 v[60:63], v3 offset:464
	s_waitcnt lgkmcnt(6)
	v_fmac_f32_e32 v20, v64, v34
	v_fmac_f32_e32 v21, v65, v34
	v_fmac_f32_e32 v22, v66, v34
	v_fmac_f32_e32 v23, v67, v34
	v_fmac_f32_e32 v24, v64, v38
	v_fmac_f32_e32 v25, v65, v38
	v_fmac_f32_e32 v26, v66, v38
	v_fmac_f32_e32 v27, v67, v38
	v_fmac_f32_e32 v28, v64, v42
	v_fmac_f32_e32 v29, v65, v42
	v_fmac_f32_e32 v30, v66, v42
	v_fmac_f32_e32 v31, v67, v42
	ds_read_b128 v[64:67], v3 offset:480
	s_waitcnt lgkmcnt(6)
	v_fmac_f32_e32 v20, v68, v35
	v_fmac_f32_e32 v21, v69, v35
	v_fmac_f32_e32 v22, v70, v35
	v_fmac_f32_e32 v23, v71, v35
	v_fmac_f32_e32 v24, v68, v39
	v_fmac_f32_e32 v25, v69, v39
	v_fmac_f32_e32 v26, v70, v39
	v_fmac_f32_e32 v27, v71, v39
	v_fmac_f32_e32 v28, v68, v43
	v_fmac_f32_e32 v29, v69, v43
	v_fmac_f32_e32 v30, v70, v43
	v_fmac_f32_e32 v31, v71, v43
	ds_read_b128 v[68:71], v3 offset:496
	ds_read_b128 v[32:35], v19 offset:128
	ds_read_b128 v[36:39], v19 offset:17536
	ds_read_b128 v[40:43], v2 offset:128
	s_waitcnt lgkmcnt(7)
	s_waitcnt lgkmcnt(6)
	v_fmac_f32_e32 v20, v56, v44
	v_fmac_f32_e32 v21, v57, v44
	v_fmac_f32_e32 v22, v58, v44
	v_fmac_f32_e32 v23, v59, v44
	v_fmac_f32_e32 v24, v56, v48
	v_fmac_f32_e32 v25, v57, v48
	v_fmac_f32_e32 v26, v58, v48
	v_fmac_f32_e32 v27, v59, v48
	v_fmac_f32_e32 v28, v56, v52
	v_fmac_f32_e32 v29, v57, v52
	v_fmac_f32_e32 v30, v58, v52
	v_fmac_f32_e32 v31, v59, v52
	ds_read_b128 v[56:59], v3 offset:512
	s_waitcnt lgkmcnt(6)
	v_fmac_f32_e32 v20, v60, v45
	v_fmac_f32_e32 v21, v61, v45
	v_fmac_f32_e32 v22, v62, v45
	v_fmac_f32_e32 v23, v63, v45
	v_fmac_f32_e32 v24, v60, v49
	v_fmac_f32_e32 v25, v61, v49
	v_fmac_f32_e32 v26, v62, v49
	v_fmac_f32_e32 v27, v63, v49
	v_fmac_f32_e32 v28, v60, v53
	v_fmac_f32_e32 v29, v61, v53
	v_fmac_f32_e32 v30, v62, v53
	v_fmac_f32_e32 v31, v63, v53
	ds_read_b128 v[60:63], v3 offset:528
	s_waitcnt lgkmcnt(6)
	v_fmac_f32_e32 v20, v64, v46
	v_fmac_f32_e32 v21, v65, v46
	v_fmac_f32_e32 v22, v66, v46
	v_fmac_f32_e32 v23, v67, v46
	v_fmac_f32_e32 v24, v64, v50
	v_fmac_f32_e32 v25, v65, v50
	v_fmac_f32_e32 v26, v66, v50
	v_fmac_f32_e32 v27, v67, v50
	v_fmac_f32_e32 v28, v64, v54
	v_fmac_f32_e32 v29, v65, v54
	v_fmac_f32_e32 v30, v66, v54
	v_fmac_f32_e32 v31, v67, v54
	ds_read_b128 v[64:67], v3 offset:544
	s_waitcnt lgkmcnt(6)
	v_fmac_f32_e32 v20, v68, v47
	v_fmac_f32_e32 v21, v69, v47
	v_fmac_f32_e32 v22, v70, v47
	v_fmac_f32_e32 v23, v71, v47
	v_fmac_f32_e32 v24, v68, v51
	v_fmac_f32_e32 v25, v69, v51
	v_fmac_f32_e32 v26, v70, v51
	v_fmac_f32_e32 v27, v71, v51
	v_fmac_f32_e32 v28, v68, v55
	v_fmac_f32_e32 v29, v69, v55
	v_fmac_f32_e32 v30, v70, v55
	v_fmac_f32_e32 v31, v71, v55
	ds_read_b128 v[68:71], v3 offset:560
	ds_read_b128 v[44:47], v19 offset:144
	ds_read_b128 v[48:51], v19 offset:17552
	ds_read_b128 v[52:55], v2 offset:144
	s_waitcnt lgkmcnt(7)
	s_waitcnt lgkmcnt(6)
	v_fmac_f32_e32 v20, v56, v32
	v_fmac_f32_e32 v21, v57, v32
	v_fmac_f32_e32 v22, v58, v32
	v_fmac_f32_e32 v23, v59, v32
	v_fmac_f32_e32 v24, v56, v36
	v_fmac_f32_e32 v25, v57, v36
	v_fmac_f32_e32 v26, v58, v36
	v_fmac_f32_e32 v27, v59, v36
	v_fmac_f32_e32 v28, v56, v40
	v_fmac_f32_e32 v29, v57, v40
	v_fmac_f32_e32 v30, v58, v40
	v_fmac_f32_e32 v31, v59, v40
	ds_read_b128 v[56:59], v3 offset:576
	s_waitcnt lgkmcnt(6)
	v_fmac_f32_e32 v20, v60, v33
	v_fmac_f32_e32 v21, v61, v33
	v_fmac_f32_e32 v22, v62, v33
	v_fmac_f32_e32 v23, v63, v33
	v_fmac_f32_e32 v24, v60, v37
	v_fmac_f32_e32 v25, v61, v37
	v_fmac_f32_e32 v26, v62, v37
	v_fmac_f32_e32 v27, v63, v37
	v_fmac_f32_e32 v28, v60, v41
	v_fmac_f32_e32 v29, v61, v41
	v_fmac_f32_e32 v30, v62, v41
	v_fmac_f32_e32 v31, v63, v41
	ds_read_b128 v[60:63], v3 offset:592
	s_waitcnt lgkmcnt(6)
	v_fmac_f32_e32 v20, v64, v34
	v_fmac_f32_e32 v21, v65, v34
	v_fmac_f32_e32 v22, v66, v34
	v_fmac_f32_e32 v23, v67, v34
	v_fmac_f32_e32 v24, v64, v38
	v_fmac_f32_e32 v25, v65, v38
	v_fmac_f32_e32 v26, v66, v38
	v_fmac_f32_e32 v27, v67, v38
	v_fmac_f32_e32 v28, v64, v42
	v_fmac_f32_e32 v29, v65, v42
	v_fmac_f32_e32 v30, v66, v42
	v_fmac_f32_e32 v31, v67, v42
	ds_read_b128 v[64:67], v3 offset:608
	s_waitcnt lgkmcnt(6)
	v_fmac_f32_e32 v20, v68, v35
	v_fmac_f32_e32 v21, v69, v35
	v_fmac_f32_e32 v22, v70, v35
	v_fmac_f32_e32 v23, v71, v35
	v_fmac_f32_e32 v24, v68, v39
	v_fmac_f32_e32 v25, v69, v39
	v_fmac_f32_e32 v26, v70, v39
	v_fmac_f32_e32 v27, v71, v39
	v_fmac_f32_e32 v28, v68, v43
	v_fmac_f32_e32 v29, v69, v43
	v_fmac_f32_e32 v30, v70, v43
	v_fmac_f32_e32 v31, v71, v43
	ds_read_b128 v[68:71], v3 offset:624
	ds_read_b128 v[32:35], v19 offset:160
	ds_read_b128 v[36:39], v19 offset:17568
	ds_read_b128 v[40:43], v2 offset:160
	s_waitcnt lgkmcnt(7)
	s_waitcnt lgkmcnt(6)
	v_fmac_f32_e32 v20, v56, v44
	v_fmac_f32_e32 v21, v57, v44
	v_fmac_f32_e32 v22, v58, v44
	v_fmac_f32_e32 v23, v59, v44
	v_fmac_f32_e32 v24, v56, v48
	v_fmac_f32_e32 v25, v57, v48
	v_fmac_f32_e32 v26, v58, v48
	v_fmac_f32_e32 v27, v59, v48
	v_fmac_f32_e32 v28, v56, v52
	v_fmac_f32_e32 v29, v57, v52
	v_fmac_f32_e32 v30, v58, v52
	v_fmac_f32_e32 v31, v59, v52
	ds_read_b128 v[56:59], v3 offset:640
	s_waitcnt lgkmcnt(6)
	v_fmac_f32_e32 v20, v60, v45
	v_fmac_f32_e32 v21, v61, v45
	v_fmac_f32_e32 v22, v62, v45
	v_fmac_f32_e32 v23, v63, v45
	v_fmac_f32_e32 v24, v60, v49
	v_fmac_f32_e32 v25, v61, v49
	v_fmac_f32_e32 v26, v62, v49
	v_fmac_f32_e32 v27, v63, v49
	v_fmac_f32_e32 v28, v60, v53
	v_fmac_f32_e32 v29, v61, v53
	v_fmac_f32_e32 v30, v62, v53
	v_fmac_f32_e32 v31, v63, v53
	ds_read_b128 v[60:63], v3 offset:656
	s_waitcnt lgkmcnt(6)
	v_fmac_f32_e32 v20, v64, v46
	v_fmac_f32_e32 v21, v65, v46
	v_fmac_f32_e32 v22, v66, v46
	v_fmac_f32_e32 v23, v67, v46
	v_fmac_f32_e32 v24, v64, v50
	v_fmac_f32_e32 v25, v65, v50
	v_fmac_f32_e32 v26, v66, v50
	v_fmac_f32_e32 v27, v67, v50
	v_fmac_f32_e32 v28, v64, v54
	v_fmac_f32_e32 v29, v65, v54
	v_fmac_f32_e32 v30, v66, v54
	v_fmac_f32_e32 v31, v67, v54
	ds_read_b128 v[64:67], v3 offset:672
	s_waitcnt lgkmcnt(6)
	v_fmac_f32_e32 v20, v68, v47
	v_fmac_f32_e32 v21, v69, v47
	v_fmac_f32_e32 v22, v70, v47
	v_fmac_f32_e32 v23, v71, v47
	v_fmac_f32_e32 v24, v68, v51
	v_fmac_f32_e32 v25, v69, v51
	v_fmac_f32_e32 v26, v70, v51
	v_fmac_f32_e32 v27, v71, v51
	v_fmac_f32_e32 v28, v68, v55
	v_fmac_f32_e32 v29, v69, v55
	v_fmac_f32_e32 v30, v70, v55
	v_fmac_f32_e32 v31, v71, v55
	ds_read_b128 v[68:71], v3 offset:688
	ds_read_b128 v[44:47], v19 offset:176
	ds_read_b128 v[48:51], v19 offset:17584
	ds_read_b128 v[52:55], v2 offset:176
	s_waitcnt lgkmcnt(7)
	s_waitcnt lgkmcnt(6)
	v_fmac_f32_e32 v20, v56, v32
	v_fmac_f32_e32 v21, v57, v32
	v_fmac_f32_e32 v22, v58, v32
	v_fmac_f32_e32 v23, v59, v32
	v_fmac_f32_e32 v24, v56, v36
	v_fmac_f32_e32 v25, v57, v36
	v_fmac_f32_e32 v26, v58, v36
	v_fmac_f32_e32 v27, v59, v36
	v_fmac_f32_e32 v28, v56, v40
	v_fmac_f32_e32 v29, v57, v40
	v_fmac_f32_e32 v30, v58, v40
	v_fmac_f32_e32 v31, v59, v40
	ds_read_b128 v[56:59], v3 offset:704
	s_waitcnt lgkmcnt(6)
	v_fmac_f32_e32 v20, v60, v33
	v_fmac_f32_e32 v21, v61, v33
	v_fmac_f32_e32 v22, v62, v33
	v_fmac_f32_e32 v23, v63, v33
	v_fmac_f32_e32 v24, v60, v37
	v_fmac_f32_e32 v25, v61, v37
	v_fmac_f32_e32 v26, v62, v37
	v_fmac_f32_e32 v27, v63, v37
	v_fmac_f32_e32 v28, v60, v41
	v_fmac_f32_e32 v29, v61, v41
	v_fmac_f32_e32 v30, v62, v41
	v_fmac_f32_e32 v31, v63, v41
	ds_read_b128 v[60:63], v3 offset:720
	s_waitcnt lgkmcnt(6)
	v_fmac_f32_e32 v20, v64, v34
	v_fmac_f32_e32 v21, v65, v34
	v_fmac_f32_e32 v22, v66, v34
	v_fmac_f32_e32 v23, v67, v34
	v_fmac_f32_e32 v24, v64, v38
	v_fmac_f32_e32 v25, v65, v38
	v_fmac_f32_e32 v26, v66, v38
	v_fmac_f32_e32 v27, v67, v38
	v_fmac_f32_e32 v28, v64, v42
	v_fmac_f32_e32 v29, v65, v42
	v_fmac_f32_e32 v30, v66, v42
	v_fmac_f32_e32 v31, v67, v42
	ds_read_b128 v[64:67], v3 offset:736
	s_waitcnt lgkmcnt(6)
	v_fmac_f32_e32 v20, v68, v35
	v_fmac_f32_e32 v21, v69, v35
	v_fmac_f32_e32 v22, v70, v35
	v_fmac_f32_e32 v23, v71, v35
	v_fmac_f32_e32 v24, v68, v39
	v_fmac_f32_e32 v25, v69, v39
	v_fmac_f32_e32 v26, v70, v39
	v_fmac_f32_e32 v27, v71, v39
	v_fmac_f32_e32 v28, v68, v43
	v_fmac_f32_e32 v29, v69, v43
	v_fmac_f32_e32 v30, v70, v43
	v_fmac_f32_e32 v31, v71, v43
	ds_read_b128 v[68:71], v3 offset:752
	ds_read_b128 v[32:35], v19 offset:192
	ds_read_b128 v[36:39], v19 offset:17600
	ds_read_b128 v[40:43], v2 offset:192
	s_waitcnt lgkmcnt(7)
	s_waitcnt lgkmcnt(6)
	v_fmac_f32_e32 v20, v56, v44
	v_fmac_f32_e32 v21, v57, v44
	v_fmac_f32_e32 v22, v58, v44
	v_fmac_f32_e32 v23, v59, v44
	v_fmac_f32_e32 v24, v56, v48
	v_fmac_f32_e32 v25, v57, v48
	v_fmac_f32_e32 v26, v58, v48
	v_fmac_f32_e32 v27, v59, v48
	v_fmac_f32_e32 v28, v56, v52
	v_fmac_f32_e32 v29, v57, v52
	v_fmac_f32_e32 v30, v58, v52
	v_fmac_f32_e32 v31, v59, v52
	ds_read_b128 v[56:59], v3 offset:768
	s_waitcnt lgkmcnt(6)
	v_fmac_f32_e32 v20, v60, v45
	v_fmac_f32_e32 v21, v61, v45
	v_fmac_f32_e32 v22, v62, v45
	v_fmac_f32_e32 v23, v63, v45
	v_fmac_f32_e32 v24, v60, v49
	v_fmac_f32_e32 v25, v61, v49
	v_fmac_f32_e32 v26, v62, v49
	v_fmac_f32_e32 v27, v63, v49
	v_fmac_f32_e32 v28, v60, v53
	v_fmac_f32_e32 v29, v61, v53
	v_fmac_f32_e32 v30, v62, v53
	v_fmac_f32_e32 v31, v63, v53
	ds_read_b128 v[60:63], v3 offset:784
	s_waitcnt lgkmcnt(6)
	v_fmac_f32_e32 v20, v64, v46
	v_fmac_f32_e32 v21, v65, v46
	v_fmac_f32_e32 v22, v66, v46
	v_fmac_f32_e32 v23, v67, v46
	v_fmac_f32_e32 v24, v64, v50
	v_fmac_f32_e32 v25, v65, v50
	v_fmac_f32_e32 v26, v66, v50
	v_fmac_f32_e32 v27, v67, v50
	v_fmac_f32_e32 v28, v64, v54
	v_fmac_f32_e32 v29, v65, v54
	v_fmac_f32_e32 v30, v66, v54
	v_fmac_f32_e32 v31, v67, v54
	ds_read_b128 v[64:67], v3 offset:800
	s_waitcnt lgkmcnt(6)
	v_fmac_f32_e32 v20, v68, v47
	v_fmac_f32_e32 v21, v69, v47
	v_fmac_f32_e32 v22, v70, v47
	v_fmac_f32_e32 v23, v71, v47
	v_fmac_f32_e32 v24, v68, v51
	v_fmac_f32_e32 v25, v69, v51
	v_fmac_f32_e32 v26, v70, v51
	v_fmac_f32_e32 v27, v71, v51
	v_fmac_f32_e32 v28, v68, v55
	v_fmac_f32_e32 v29, v69, v55
	v_fmac_f32_e32 v30, v70, v55
	v_fmac_f32_e32 v31, v71, v55
	ds_read_b128 v[68:71], v3 offset:816
	ds_read_b128 v[44:47], v19 offset:208
	ds_read_b128 v[48:51], v19 offset:17616
	ds_read_b128 v[52:55], v2 offset:208
	s_waitcnt lgkmcnt(7)
	s_waitcnt lgkmcnt(6)
	v_fmac_f32_e32 v20, v56, v32
	v_fmac_f32_e32 v21, v57, v32
	v_fmac_f32_e32 v22, v58, v32
	v_fmac_f32_e32 v23, v59, v32
	v_fmac_f32_e32 v24, v56, v36
	v_fmac_f32_e32 v25, v57, v36
	v_fmac_f32_e32 v26, v58, v36
	v_fmac_f32_e32 v27, v59, v36
	v_fmac_f32_e32 v28, v56, v40
	v_fmac_f32_e32 v29, v57, v40
	v_fmac_f32_e32 v30, v58, v40
	v_fmac_f32_e32 v31, v59, v40
	ds_read_b128 v[56:59], v3 offset:832
	s_waitcnt lgkmcnt(6)
	v_fmac_f32_e32 v20, v60, v33
	v_fmac_f32_e32 v21, v61, v33
	v_fmac_f32_e32 v22, v62, v33
	v_fmac_f32_e32 v23, v63, v33
	v_fmac_f32_e32 v24, v60, v37
	v_fmac_f32_e32 v25, v61, v37
	v_fmac_f32_e32 v26, v62, v37
	v_fmac_f32_e32 v27, v63, v37
	v_fmac_f32_e32 v28, v60, v41
	v_fmac_f32_e32 v29, v61, v41
	v_fmac_f32_e32 v30, v62, v41
	v_fmac_f32_e32 v31, v63, v41
	ds_read_b128 v[60:63], v3 offset:848
	s_waitcnt lgkmcnt(6)
	v_fmac_f32_e32 v20, v64, v34
	v_fmac_f32_e32 v21, v65, v34
	v_fmac_f32_e32 v22, v66, v34
	v_fmac_f32_e32 v23, v67, v34
	v_fmac_f32_e32 v24, v64, v38
	v_fmac_f32_e32 v25, v65, v38
	v_fmac_f32_e32 v26, v66, v38
	v_fmac_f32_e32 v27, v67, v38
	v_fmac_f32_e32 v28, v64, v42
	v_fmac_f32_e32 v29, v65, v42
	v_fmac_f32_e32 v30, v66, v42
	v_fmac_f32_e32 v31, v67, v42
	ds_read_b128 v[64:67], v3 offset:864
	s_waitcnt lgkmcnt(6)
	v_fmac_f32_e32 v20, v68, v35
	v_fmac_f32_e32 v21, v69, v35
	v_fmac_f32_e32 v22, v70, v35
	v_fmac_f32_e32 v23, v71, v35
	v_fmac_f32_e32 v24, v68, v39
	v_fmac_f32_e32 v25, v69, v39
	v_fmac_f32_e32 v26, v70, v39
	v_fmac_f32_e32 v27, v71, v39
	v_fmac_f32_e32 v28, v68, v43
	v_fmac_f32_e32 v29, v69, v43
	v_fmac_f32_e32 v30, v70, v43
	v_fmac_f32_e32 v31, v71, v43
	ds_read_b128 v[68:71], v3 offset:880
	ds_read_b128 v[32:35], v19 offset:224
	ds_read_b128 v[36:39], v19 offset:17632
	ds_read_b128 v[40:43], v2 offset:224
	s_waitcnt lgkmcnt(7)
	s_waitcnt lgkmcnt(6)
	v_fmac_f32_e32 v20, v56, v44
	v_fmac_f32_e32 v21, v57, v44
	v_fmac_f32_e32 v22, v58, v44
	v_fmac_f32_e32 v23, v59, v44
	v_fmac_f32_e32 v24, v56, v48
	v_fmac_f32_e32 v25, v57, v48
	v_fmac_f32_e32 v26, v58, v48
	v_fmac_f32_e32 v27, v59, v48
	v_fmac_f32_e32 v28, v56, v52
	v_fmac_f32_e32 v29, v57, v52
	v_fmac_f32_e32 v30, v58, v52
	v_fmac_f32_e32 v31, v59, v52
	ds_read_b128 v[56:59], v3 offset:896
	s_waitcnt lgkmcnt(6)
	v_fmac_f32_e32 v20, v60, v45
	v_fmac_f32_e32 v21, v61, v45
	v_fmac_f32_e32 v22, v62, v45
	v_fmac_f32_e32 v23, v63, v45
	v_fmac_f32_e32 v24, v60, v49
	v_fmac_f32_e32 v25, v61, v49
	v_fmac_f32_e32 v26, v62, v49
	v_fmac_f32_e32 v27, v63, v49
	v_fmac_f32_e32 v28, v60, v53
	v_fmac_f32_e32 v29, v61, v53
	v_fmac_f32_e32 v30, v62, v53
	v_fmac_f32_e32 v31, v63, v53
	ds_read_b128 v[60:63], v3 offset:912
	s_waitcnt lgkmcnt(6)
	v_fmac_f32_e32 v20, v64, v46
	v_fmac_f32_e32 v21, v65, v46
	v_fmac_f32_e32 v22, v66, v46
	v_fmac_f32_e32 v23, v67, v46
	v_fmac_f32_e32 v24, v64, v50
	v_fmac_f32_e32 v25, v65, v50
	v_fmac_f32_e32 v26, v66, v50
	v_fmac_f32_e32 v27, v67, v50
	v_fmac_f32_e32 v28, v64, v54
	v_fmac_f32_e32 v29, v65, v54
	v_fmac_f32_e32 v30, v66, v54
	v_fmac_f32_e32 v31, v67, v54
	ds_read_b128 v[64:67], v3 offset:928
	s_waitcnt lgkmcnt(6)
	v_fmac_f32_e32 v20, v68, v47
	v_fmac_f32_e32 v21, v69, v47
	v_fmac_f32_e32 v22, v70, v47
	v_fmac_f32_e32 v23, v71, v47
	v_fmac_f32_e32 v24, v68, v51
	v_fmac_f32_e32 v25, v69, v51
	v_fmac_f32_e32 v26, v70, v51
	v_fmac_f32_e32 v27, v71, v51
	v_fmac_f32_e32 v28, v68, v55
	v_fmac_f32_e32 v29, v69, v55
	v_fmac_f32_e32 v30, v70, v55
	v_fmac_f32_e32 v31, v71, v55
	ds_read_b128 v[68:71], v3 offset:944
	ds_read_b128 v[44:47], v19 offset:240
	ds_read_b128 v[48:51], v19 offset:17648
	ds_read_b128 v[52:55], v2 offset:240
	s_waitcnt lgkmcnt(7)
	s_waitcnt lgkmcnt(6)
	v_fmac_f32_e32 v20, v56, v32
	v_fmac_f32_e32 v21, v57, v32
	v_fmac_f32_e32 v22, v58, v32
	v_fmac_f32_e32 v23, v59, v32
	v_fmac_f32_e32 v24, v56, v36
	v_fmac_f32_e32 v25, v57, v36
	v_fmac_f32_e32 v26, v58, v36
	v_fmac_f32_e32 v27, v59, v36
	v_fmac_f32_e32 v28, v56, v40
	v_fmac_f32_e32 v29, v57, v40
	v_fmac_f32_e32 v30, v58, v40
	v_fmac_f32_e32 v31, v59, v40
	ds_read_b128 v[56:59], v3 offset:960
	s_waitcnt lgkmcnt(6)
	v_fmac_f32_e32 v20, v60, v33
	v_fmac_f32_e32 v21, v61, v33
	v_fmac_f32_e32 v22, v62, v33
	v_fmac_f32_e32 v23, v63, v33
	v_fmac_f32_e32 v24, v60, v37
	v_fmac_f32_e32 v25, v61, v37
	v_fmac_f32_e32 v26, v62, v37
	v_fmac_f32_e32 v27, v63, v37
	v_fmac_f32_e32 v28, v60, v41
	v_fmac_f32_e32 v29, v61, v41
	v_fmac_f32_e32 v30, v62, v41
	v_fmac_f32_e32 v31, v63, v41
	ds_read_b128 v[60:63], v3 offset:976
	s_waitcnt lgkmcnt(6)
	v_fmac_f32_e32 v20, v64, v34
	v_fmac_f32_e32 v21, v65, v34
	v_fmac_f32_e32 v22, v66, v34
	v_fmac_f32_e32 v23, v67, v34
	v_fmac_f32_e32 v24, v64, v38
	v_fmac_f32_e32 v25, v65, v38
	v_fmac_f32_e32 v26, v66, v38
	v_fmac_f32_e32 v27, v67, v38
	v_fmac_f32_e32 v28, v64, v42
	v_fmac_f32_e32 v29, v65, v42
	v_fmac_f32_e32 v30, v66, v42
	v_fmac_f32_e32 v31, v67, v42
	ds_read_b128 v[64:67], v3 offset:992
	s_waitcnt lgkmcnt(6)
	v_fmac_f32_e32 v20, v68, v35
	v_fmac_f32_e32 v21, v69, v35
	v_fmac_f32_e32 v22, v70, v35
	v_fmac_f32_e32 v23, v71, v35
	v_fmac_f32_e32 v24, v68, v39
	v_fmac_f32_e32 v25, v69, v39
	v_fmac_f32_e32 v26, v70, v39
	v_fmac_f32_e32 v27, v71, v39
	v_fmac_f32_e32 v28, v68, v43
	v_fmac_f32_e32 v29, v69, v43
	v_fmac_f32_e32 v30, v70, v43
	v_fmac_f32_e32 v31, v71, v43
	ds_read_b128 v[68:71], v3 offset:1008
	s_waitcnt lgkmcnt(4)
	s_waitcnt lgkmcnt(3)
	v_fmac_f32_e32 v20, v56, v44
	v_fmac_f32_e32 v21, v57, v44
	v_fmac_f32_e32 v22, v58, v44
	v_fmac_f32_e32 v23, v59, v44
	v_fmac_f32_e32 v24, v56, v48
	v_fmac_f32_e32 v25, v57, v48
	v_fmac_f32_e32 v26, v58, v48
	v_fmac_f32_e32 v27, v59, v48
	v_fmac_f32_e32 v28, v56, v52
	v_fmac_f32_e32 v29, v57, v52
	v_fmac_f32_e32 v30, v58, v52
	v_fmac_f32_e32 v31, v59, v52
	s_waitcnt lgkmcnt(2)
	v_fmac_f32_e32 v20, v60, v45
	v_fmac_f32_e32 v21, v61, v45
	v_fmac_f32_e32 v22, v62, v45
	v_fmac_f32_e32 v23, v63, v45
	v_fmac_f32_e32 v24, v60, v49
	v_fmac_f32_e32 v25, v61, v49
	v_fmac_f32_e32 v26, v62, v49
	v_fmac_f32_e32 v27, v63, v49
	v_fmac_f32_e32 v28, v60, v53
	v_fmac_f32_e32 v29, v61, v53
	v_fmac_f32_e32 v30, v62, v53
	v_fmac_f32_e32 v31, v63, v53
	s_waitcnt lgkmcnt(1)
	v_fmac_f32_e32 v20, v64, v46
	v_fmac_f32_e32 v21, v65, v46
	v_fmac_f32_e32 v22, v66, v46
	v_fmac_f32_e32 v23, v67, v46
	v_fmac_f32_e32 v24, v64, v50
	v_fmac_f32_e32 v25, v65, v50
	v_fmac_f32_e32 v26, v66, v50
	v_fmac_f32_e32 v27, v67, v50
	v_fmac_f32_e32 v28, v64, v54
	v_fmac_f32_e32 v29, v65, v54
	v_fmac_f32_e32 v30, v66, v54
	v_fmac_f32_e32 v31, v67, v54
	s_waitcnt lgkmcnt(0)
	v_fmac_f32_e32 v20, v68, v47
	v_fmac_f32_e32 v21, v69, v47
	v_fmac_f32_e32 v22, v70, v47
	v_fmac_f32_e32 v23, v71, v47
	v_fmac_f32_e32 v24, v68, v51
	v_fmac_f32_e32 v25, v69, v51
	v_fmac_f32_e32 v26, v70, v51
	v_fmac_f32_e32 v27, v71, v51
	v_fmac_f32_e32 v28, v68, v55
	v_fmac_f32_e32 v29, v69, v55
	v_fmac_f32_e32 v30, v70, v55
	v_fmac_f32_e32 v31, v71, v55
	s_add_u32 s8, s10, 0x14180000
	s_addc_u32 s9, s11, 0
	s_lshl_b32 s2, s44, 9
	s_add_u32 s8, s8, s2
	s_addc_u32 s9, s9, 0
	v_sub_u32_e32 v44, 128, v7
	v_and_b32_e32 v44, 0x7f, v44
	v_lshlrev_b32_e32 v44, 2, v44
	global_load_dword v32, v44, s[8:9]
	v_sub_u32_e32 v44, 129, v7
	v_and_b32_e32 v44, 0x7f, v44
	v_lshlrev_b32_e32 v44, 2, v44
	global_load_dword v33, v44, s[8:9]
	v_sub_u32_e32 v44, 130, v7
	v_and_b32_e32 v44, 0x7f, v44
	v_lshlrev_b32_e32 v44, 2, v44
	global_load_dword v34, v44, s[8:9]
	v_sub_u32_e32 v44, 131, v7
	v_and_b32_e32 v44, 0x7f, v44
	v_lshlrev_b32_e32 v44, 2, v44
	global_load_dword v35, v44, s[8:9]
	v_sub_u32_e32 v44, 64, v7
	v_and_b32_e32 v44, 0x7f, v44
	v_lshlrev_b32_e32 v44, 2, v44
	global_load_dword v36, v44, s[8:9]
	v_sub_u32_e32 v44, 65, v7
	v_and_b32_e32 v44, 0x7f, v44
	v_lshlrev_b32_e32 v44, 2, v44
	global_load_dword v37, v44, s[8:9]
	v_sub_u32_e32 v44, 66, v7
	v_and_b32_e32 v44, 0x7f, v44
	v_lshlrev_b32_e32 v44, 2, v44
	global_load_dword v38, v44, s[8:9]
	v_sub_u32_e32 v44, 67, v7
	v_and_b32_e32 v44, 0x7f, v44
	v_lshlrev_b32_e32 v44, 2, v44
	global_load_dword v39, v44, s[8:9]
	v_sub_u32_e32 v44, 0, v7
	v_and_b32_e32 v44, 0x7f, v44
	v_lshlrev_b32_e32 v44, 2, v44
	global_load_dword v40, v44, s[8:9]
	v_sub_u32_e32 v44, 1, v7
	v_and_b32_e32 v44, 0x7f, v44
	v_lshlrev_b32_e32 v44, 2, v44
	global_load_dword v41, v44, s[8:9]
	v_sub_u32_e32 v44, 2, v7
	v_and_b32_e32 v44, 0x7f, v44
	v_lshlrev_b32_e32 v44, 2, v44
	global_load_dword v42, v44, s[8:9]
	v_sub_u32_e32 v44, 3, v7
	v_and_b32_e32 v44, 0x7f, v44
	v_lshlrev_b32_e32 v44, 2, v44
	global_load_dword v43, v44, s[8:9]
	s_waitcnt vmcnt(0)
	v_add_f32_e32 v20, v20, v32
	v_add_f32_e32 v21, v21, v33
	v_add_f32_e32 v22, v22, v34
	v_add_f32_e32 v23, v23, v35
	v_add_f32_e32 v24, v24, v36
	v_add_f32_e32 v25, v25, v37
	v_add_f32_e32 v26, v26, v38
	v_add_f32_e32 v27, v27, v39
	v_add_f32_e32 v28, v28, v40
	v_add_f32_e32 v29, v29, v41
	v_add_f32_e32 v30, v30, v42
	v_add_f32_e32 v31, v31, v43
	v_mov_b32_e32 v45, 0xff800000
	v_cmp_lt_u32_e32 vcc, 0, v7
	s_nop 1
	v_cndmask_b32_e32 v20, v45, v20, vcc
	v_cmp_ge_u32_e32 vcc, 0, v7
	s_nop 1
	v_cndmask_b32_e32 v28, v45, v28, vcc
	v_cmp_lt_u32_e32 vcc, 1, v7
	s_nop 1
	v_cndmask_b32_e32 v21, v45, v21, vcc
	v_cmp_ge_u32_e32 vcc, 1, v7
	s_nop 1
	v_cndmask_b32_e32 v29, v45, v29, vcc
	v_cmp_lt_u32_e32 vcc, 2, v7
	s_nop 1
	v_cndmask_b32_e32 v22, v45, v22, vcc
	v_cmp_ge_u32_e32 vcc, 2, v7
	s_nop 1
	v_cndmask_b32_e32 v30, v45, v30, vcc
	v_cmp_lt_u32_e32 vcc, 3, v7
	s_nop 1
	v_cndmask_b32_e32 v23, v45, v23, vcc
	v_cmp_ge_u32_e32 vcc, 3, v7
	s_nop 1
	v_cndmask_b32_e32 v31, v45, v31, vcc
	v_max3_f32 v46, v20, v24, v28
	v_max3_f32 v47, v21, v25, v29
	v_max3_f32 v48, v22, v26, v30
	v_max3_f32 v49, v23, v27, v31
	v_xor_b32_e32 v54, 32, v7
	v_lshlrev_b32_e32 v54, 2, v54
	ds_swizzle_b32 v50, v46 offset:0x41f
	ds_swizzle_b32 v51, v47 offset:0x41f
	ds_swizzle_b32 v52, v48 offset:0x41f
	ds_swizzle_b32 v53, v49 offset:0x41f
	s_waitcnt lgkmcnt(0)
	v_max_f32_e32 v46, v46, v50
	v_max_f32_e32 v47, v47, v51
	v_max_f32_e32 v48, v48, v52
	v_max_f32_e32 v49, v49, v53
	ds_swizzle_b32 v50, v46 offset:0x81f
	ds_swizzle_b32 v51, v47 offset:0x81f
	ds_swizzle_b32 v52, v48 offset:0x81f
	ds_swizzle_b32 v53, v49 offset:0x81f
	s_waitcnt lgkmcnt(0)
	v_max_f32_e32 v46, v46, v50
	v_max_f32_e32 v47, v47, v51
	v_max_f32_e32 v48, v48, v52
	v_max_f32_e32 v49, v49, v53
	ds_swizzle_b32 v50, v46 offset:0x101f
	ds_swizzle_b32 v51, v47 offset:0x101f
	ds_swizzle_b32 v52, v48 offset:0x101f
	ds_swizzle_b32 v53, v49 offset:0x101f
	s_waitcnt lgkmcnt(0)
	v_max_f32_e32 v46, v46, v50
	v_max_f32_e32 v47, v47, v51
	v_max_f32_e32 v48, v48, v52
	v_max_f32_e32 v49, v49, v53
	ds_swizzle_b32 v50, v46 offset:0x201f
	ds_swizzle_b32 v51, v47 offset:0x201f
	ds_swizzle_b32 v52, v48 offset:0x201f
	ds_swizzle_b32 v53, v49 offset:0x201f
	s_waitcnt lgkmcnt(0)
	v_max_f32_e32 v46, v46, v50
	v_max_f32_e32 v47, v47, v51
	v_max_f32_e32 v48, v48, v52
	v_max_f32_e32 v49, v49, v53
	ds_swizzle_b32 v50, v46 offset:0x401f
	ds_swizzle_b32 v51, v47 offset:0x401f
	ds_swizzle_b32 v52, v48 offset:0x401f
	ds_swizzle_b32 v53, v49 offset:0x401f
	s_waitcnt lgkmcnt(0)
	v_max_f32_e32 v46, v46, v50
	v_max_f32_e32 v47, v47, v51
	v_max_f32_e32 v48, v48, v52
	v_max_f32_e32 v49, v49, v53
	ds_bpermute_b32 v50, v54, v46
	ds_bpermute_b32 v51, v54, v47
	ds_bpermute_b32 v52, v54, v48
	ds_bpermute_b32 v53, v54, v49
	s_waitcnt lgkmcnt(0)
	v_max_f32_e32 v46, v46, v50
	v_max_f32_e32 v47, v47, v51
	v_max_f32_e32 v48, v48, v52
	v_max_f32_e32 v49, v49, v53
	s_waitcnt lgkmcnt(0)
	v_max_f32_e32 v46, s58, v46
	v_max_f32_e32 v47, s58, v47
	v_max_f32_e32 v48, s58, v48
	v_max_f32_e32 v49, s58, v49
	v_mov_b32_e32 v55, 0x3fb8aa3b
	v_sub_f32_e32 v20, v20, v46
	v_sub_f32_e32 v21, v21, v47
	v_sub_f32_e32 v22, v22, v48
	v_sub_f32_e32 v23, v23, v49
	v_sub_f32_e32 v24, v24, v46
	v_sub_f32_e32 v25, v25, v47
	v_sub_f32_e32 v26, v26, v48
	v_sub_f32_e32 v27, v27, v49
	v_sub_f32_e32 v28, v28, v46
	v_sub_f32_e32 v29, v29, v47
	v_sub_f32_e32 v30, v30, v48
	v_sub_f32_e32 v31, v31, v49
	v_mul_f32_e32 v20, v55, v20
	v_mul_f32_e32 v21, v55, v21
	v_mul_f32_e32 v22, v55, v22
	v_mul_f32_e32 v23, v55, v23
	v_mul_f32_e32 v24, v55, v24
	v_mul_f32_e32 v25, v55, v25
	v_mul_f32_e32 v26, v55, v26
	v_mul_f32_e32 v27, v55, v27
	v_mul_f32_e32 v28, v55, v28
	v_mul_f32_e32 v29, v55, v29
	v_mul_f32_e32 v30, v55, v30
	v_mul_f32_e32 v31, v55, v31
	v_exp_f32_e32 v20, v20
	v_exp_f32_e32 v21, v21
	v_exp_f32_e32 v22, v22
	v_exp_f32_e32 v23, v23
	v_exp_f32_e32 v24, v24
	v_exp_f32_e32 v25, v25
	v_exp_f32_e32 v26, v26
	v_exp_f32_e32 v27, v27
	v_exp_f32_e32 v28, v28
	v_exp_f32_e32 v29, v29
	v_exp_f32_e32 v30, v30
	v_exp_f32_e32 v31, v31
	s_nop 1
	v_add_f32_e32 v56, v20, v24
	v_add_f32_e32 v57, v21, v25
	v_add_f32_e32 v58, v22, v26
	v_add_f32_e32 v59, v23, v27
	v_add_f32_e32 v56, v56, v28
	v_add_f32_e32 v57, v57, v29
	v_add_f32_e32 v58, v58, v30
	v_add_f32_e32 v59, v59, v31
	ds_swizzle_b32 v50, v56 offset:0x41f
	ds_swizzle_b32 v51, v57 offset:0x41f
	ds_swizzle_b32 v52, v58 offset:0x41f
	ds_swizzle_b32 v53, v59 offset:0x41f
	s_waitcnt lgkmcnt(0)
	v_add_f32_e32 v56, v56, v50
	v_add_f32_e32 v57, v57, v51
	v_add_f32_e32 v58, v58, v52
	v_add_f32_e32 v59, v59, v53
	ds_swizzle_b32 v50, v56 offset:0x81f
	ds_swizzle_b32 v51, v57 offset:0x81f
	ds_swizzle_b32 v52, v58 offset:0x81f
	ds_swizzle_b32 v53, v59 offset:0x81f
	s_waitcnt lgkmcnt(0)
	v_add_f32_e32 v56, v56, v50
	v_add_f32_e32 v57, v57, v51
	v_add_f32_e32 v58, v58, v52
	v_add_f32_e32 v59, v59, v53
	ds_swizzle_b32 v50, v56 offset:0x101f
	ds_swizzle_b32 v51, v57 offset:0x101f
	ds_swizzle_b32 v52, v58 offset:0x101f
	ds_swizzle_b32 v53, v59 offset:0x101f
	s_waitcnt lgkmcnt(0)
	v_add_f32_e32 v56, v56, v50
	v_add_f32_e32 v57, v57, v51
	v_add_f32_e32 v58, v58, v52
	v_add_f32_e32 v59, v59, v53
	ds_swizzle_b32 v50, v56 offset:0x201f
	ds_swizzle_b32 v51, v57 offset:0x201f
	ds_swizzle_b32 v52, v58 offset:0x201f
	ds_swizzle_b32 v53, v59 offset:0x201f
	s_waitcnt lgkmcnt(0)
	v_add_f32_e32 v56, v56, v50
	v_add_f32_e32 v57, v57, v51
	v_add_f32_e32 v58, v58, v52
	v_add_f32_e32 v59, v59, v53
	ds_swizzle_b32 v50, v56 offset:0x401f
	ds_swizzle_b32 v51, v57 offset:0x401f
	ds_swizzle_b32 v52, v58 offset:0x401f
	ds_swizzle_b32 v53, v59 offset:0x401f
	s_waitcnt lgkmcnt(0)
	v_add_f32_e32 v56, v56, v50
	v_add_f32_e32 v57, v57, v51
	v_add_f32_e32 v58, v58, v52
	v_add_f32_e32 v59, v59, v53
	ds_bpermute_b32 v50, v54, v56
	ds_bpermute_b32 v51, v54, v57
	ds_bpermute_b32 v52, v54, v58
	ds_bpermute_b32 v53, v54, v59
	s_waitcnt lgkmcnt(0)
	v_add_f32_e32 v56, v56, v50
	v_add_f32_e32 v57, v57, v51
	v_add_f32_e32 v58, v58, v52
	v_add_f32_e32 v59, v59, v53
	v_sub_f32_e32 v60, s58, v46
	v_sub_f32_e32 v61, s58, v47
	v_sub_f32_e32 v62, s58, v48
	v_sub_f32_e32 v63, s58, v49
	v_mul_f32_e32 v60, v55, v60
	v_mul_f32_e32 v61, v55, v61
	v_mul_f32_e32 v62, v55, v62
	v_mul_f32_e32 v63, v55, v63
	v_exp_f32_e32 v60, v60
	v_exp_f32_e32 v61, v61
	v_exp_f32_e32 v62, v62
	v_exp_f32_e32 v63, v63
	s_nop 1
	v_add_f32_e32 v56, v56, v60
	v_add_f32_e32 v57, v57, v61
	v_add_f32_e32 v58, v58, v62
	v_add_f32_e32 v59, v59, v63
	v_rcp_f32_e32 v60, v56
	v_rcp_f32_e32 v61, v57
	v_rcp_f32_e32 v62, v58
	v_rcp_f32_e32 v63, v59
	s_nop 1
	v_fma_f32 v50, -v56, v60, 1.0
	v_fma_f32 v51, -v57, v61, 1.0
	v_fma_f32 v52, -v58, v62, 1.0
	v_fma_f32 v53, -v59, v63, 1.0
	v_fma_f32 v60, v50, v60, v60
	v_fma_f32 v61, v51, v61, v61
	v_fma_f32 v62, v52, v62, v62
	v_fma_f32 v63, v53, v63, v63
	v_mul_f32_e32 v20, v20, v60
	v_mul_f32_e32 v21, v21, v61
	v_mul_f32_e32 v22, v22, v62
	v_mul_f32_e32 v23, v23, v63
	v_mul_f32_e32 v24, v24, v60
	v_mul_f32_e32 v25, v25, v61
	v_mul_f32_e32 v26, v26, v62
	v_mul_f32_e32 v27, v27, v63
	v_mul_f32_e32 v28, v28, v60
	v_mul_f32_e32 v29, v29, v61
	v_mul_f32_e32 v30, v30, v62
	v_mul_f32_e32 v31, v31, v63
	v_add_u32_e32 v17, 0x400, v17
	ds_write_b128 v17, v[20:23]
	ds_write_b128 v17, v[24:27] offset:1024
	ds_write_b128 v17, v[28:31] offset:2048
	s_waitcnt lgkmcnt(0)
	v_lshlrev_b32_e32 v19, 2, v7
	v_add_u32_e32 v19, 0x9000, v19
	s_add_i32 s2, s59, 0x400
	v_mov_b32_e32 v3, s2
	v_mov_b32_e32 v4, 0
	v_mov_b32_e32 v5, 0
	v_mov_b32_e32 v6, 0
	v_mov_b32_e32 v8, 0
	ds_read_b128 v[20:23], v3 offset:0
	ds_read_b32 v32, v19 offset:0
	ds_read_b128 v[24:27], v3 offset:16
	ds_read_b32 v33, v19 offset:256
	ds_read_b128 v[28:31], v3 offset:32
	ds_read_b32 v34, v19 offset:512
	ds_read_b128 v[36:39], v3 offset:48
	ds_read_b32 v48, v19 offset:768
	ds_read_b128 v[40:43], v3 offset:64
	ds_read_b32 v49, v19 offset:1024
	ds_read_b128 v[44:47], v3 offset:80
	ds_read_b32 v50, v19 offset:1280
	s_waitcnt lgkmcnt(10)
	v_fmac_f32_e32 v4, v20, v32
	v_fmac_f32_e32 v5, v21, v32
	v_fmac_f32_e32 v6, v22, v32
	v_fmac_f32_e32 v8, v23, v32
	s_waitcnt lgkmcnt(8)
	v_fmac_f32_e32 v4, v24, v33
	v_fmac_f32_e32 v5, v25, v33
	v_fmac_f32_e32 v6, v26, v33
	v_fmac_f32_e32 v8, v27, v33
	s_waitcnt lgkmcnt(6)
	v_fmac_f32_e32 v4, v28, v34
	v_fmac_f32_e32 v5, v29, v34
	v_fmac_f32_e32 v6, v30, v34
	v_fmac_f32_e32 v8, v31, v34
	ds_read_b128 v[20:23], v3 offset:96
	ds_read_b32 v32, v19 offset:1536
	ds_read_b128 v[24:27], v3 offset:112
	ds_read_b32 v33, v19 offset:1792
	ds_read_b128 v[28:31], v3 offset:128
	ds_read_b32 v34, v19 offset:2048
	s_waitcnt lgkmcnt(10)
	v_fmac_f32_e32 v4, v36, v48
	v_fmac_f32_e32 v5, v37, v48
	v_fmac_f32_e32 v6, v38, v48
	v_fmac_f32_e32 v8, v39, v48
	s_waitcnt lgkmcnt(8)
	v_fmac_f32_e32 v4, v40, v49
	v_fmac_f32_e32 v5, v41, v49
	v_fmac_f32_e32 v6, v42, v49
	v_fmac_f32_e32 v8, v43, v49
	s_waitcnt lgkmcnt(6)
	v_fmac_f32_e32 v4, v44, v50
	v_fmac_f32_e32 v5, v45, v50
	v_fmac_f32_e32 v6, v46, v50
	v_fmac_f32_e32 v8, v47, v50
	ds_read_b128 v[36:39], v3 offset:144
	ds_read_b32 v48, v19 offset:2304
	ds_read_b128 v[40:43], v3 offset:160
	ds_read_b32 v49, v19 offset:2560
	ds_read_b128 v[44:47], v3 offset:176
	ds_read_b32 v50, v19 offset:2816
	s_waitcnt lgkmcnt(10)
	v_fmac_f32_e32 v4, v20, v32
	v_fmac_f32_e32 v5, v21, v32
	v_fmac_f32_e32 v6, v22, v32
	v_fmac_f32_e32 v8, v23, v32
	s_waitcnt lgkmcnt(8)
	v_fmac_f32_e32 v4, v24, v33
	v_fmac_f32_e32 v5, v25, v33
	v_fmac_f32_e32 v6, v26, v33
	v_fmac_f32_e32 v8, v27, v33
	s_waitcnt lgkmcnt(6)
	v_fmac_f32_e32 v4, v28, v34
	v_fmac_f32_e32 v5, v29, v34
	v_fmac_f32_e32 v6, v30, v34
	v_fmac_f32_e32 v8, v31, v34
	ds_read_b128 v[20:23], v3 offset:192
	ds_read_b32 v32, v19 offset:3072
	ds_read_b128 v[24:27], v3 offset:208
	ds_read_b32 v33, v19 offset:3328
	ds_read_b128 v[28:31], v3 offset:224
	ds_read_b32 v34, v19 offset:3584
	s_waitcnt lgkmcnt(10)
	v_fmac_f32_e32 v4, v36, v48
	v_fmac_f32_e32 v5, v37, v48
	v_fmac_f32_e32 v6, v38, v48
	v_fmac_f32_e32 v8, v39, v48
	s_waitcnt lgkmcnt(8)
	v_fmac_f32_e32 v4, v40, v49
	v_fmac_f32_e32 v5, v41, v49
	v_fmac_f32_e32 v6, v42, v49
	v_fmac_f32_e32 v8, v43, v49
	s_waitcnt lgkmcnt(6)
	v_fmac_f32_e32 v4, v44, v50
	v_fmac_f32_e32 v5, v45, v50
	v_fmac_f32_e32 v6, v46, v50
	v_fmac_f32_e32 v8, v47, v50
	ds_read_b128 v[36:39], v3 offset:240
	ds_read_b32 v48, v19 offset:3840
	ds_read_b128 v[40:43], v3 offset:256
	ds_read_b32 v49, v19 offset:4096
	ds_read_b128 v[44:47], v3 offset:272
	ds_read_b32 v50, v19 offset:4352
	s_waitcnt lgkmcnt(10)
	v_fmac_f32_e32 v4, v20, v32
	v_fmac_f32_e32 v5, v21, v32
	v_fmac_f32_e32 v6, v22, v32
	v_fmac_f32_e32 v8, v23, v32
	s_waitcnt lgkmcnt(8)
	v_fmac_f32_e32 v4, v24, v33
	v_fmac_f32_e32 v5, v25, v33
	v_fmac_f32_e32 v6, v26, v33
	v_fmac_f32_e32 v8, v27, v33
	s_waitcnt lgkmcnt(6)
	v_fmac_f32_e32 v4, v28, v34
	v_fmac_f32_e32 v5, v29, v34
	v_fmac_f32_e32 v6, v30, v34
	v_fmac_f32_e32 v8, v31, v34
	ds_read_b128 v[20:23], v3 offset:288
	ds_read_b32 v32, v19 offset:4608
	ds_read_b128 v[24:27], v3 offset:304
	ds_read_b32 v33, v19 offset:4864
	ds_read_b128 v[28:31], v3 offset:320
	ds_read_b32 v34, v19 offset:5120
	s_waitcnt lgkmcnt(10)
	v_fmac_f32_e32 v4, v36, v48
	v_fmac_f32_e32 v5, v37, v48
	v_fmac_f32_e32 v6, v38, v48
	v_fmac_f32_e32 v8, v39, v48
	s_waitcnt lgkmcnt(8)
	v_fmac_f32_e32 v4, v40, v49
	v_fmac_f32_e32 v5, v41, v49
	v_fmac_f32_e32 v6, v42, v49
	v_fmac_f32_e32 v8, v43, v49
	s_waitcnt lgkmcnt(6)
	v_fmac_f32_e32 v4, v44, v50
	v_fmac_f32_e32 v5, v45, v50
	v_fmac_f32_e32 v6, v46, v50
	v_fmac_f32_e32 v8, v47, v50
	ds_read_b128 v[36:39], v3 offset:336
	ds_read_b32 v48, v19 offset:5376
	ds_read_b128 v[40:43], v3 offset:352
	ds_read_b32 v49, v19 offset:5632
	ds_read_b128 v[44:47], v3 offset:368
	ds_read_b32 v50, v19 offset:5888
	s_waitcnt lgkmcnt(10)
	v_fmac_f32_e32 v4, v20, v32
	v_fmac_f32_e32 v5, v21, v32
	v_fmac_f32_e32 v6, v22, v32
	v_fmac_f32_e32 v8, v23, v32
	s_waitcnt lgkmcnt(8)
	v_fmac_f32_e32 v4, v24, v33
	v_fmac_f32_e32 v5, v25, v33
	v_fmac_f32_e32 v6, v26, v33
	v_fmac_f32_e32 v8, v27, v33
	s_waitcnt lgkmcnt(6)
	v_fmac_f32_e32 v4, v28, v34
	v_fmac_f32_e32 v5, v29, v34
	v_fmac_f32_e32 v6, v30, v34
	v_fmac_f32_e32 v8, v31, v34
	ds_read_b128 v[20:23], v3 offset:384
	ds_read_b32 v32, v19 offset:6144
	ds_read_b128 v[24:27], v3 offset:400
	ds_read_b32 v33, v19 offset:6400
	ds_read_b128 v[28:31], v3 offset:416
	ds_read_b32 v34, v19 offset:6656
	s_waitcnt lgkmcnt(10)
	v_fmac_f32_e32 v4, v36, v48
	v_fmac_f32_e32 v5, v37, v48
	v_fmac_f32_e32 v6, v38, v48
	v_fmac_f32_e32 v8, v39, v48
	s_waitcnt lgkmcnt(8)
	v_fmac_f32_e32 v4, v40, v49
	v_fmac_f32_e32 v5, v41, v49
	v_fmac_f32_e32 v6, v42, v49
	v_fmac_f32_e32 v8, v43, v49
	s_waitcnt lgkmcnt(6)
	v_fmac_f32_e32 v4, v44, v50
	v_fmac_f32_e32 v5, v45, v50
	v_fmac_f32_e32 v6, v46, v50
	v_fmac_f32_e32 v8, v47, v50
	ds_read_b128 v[36:39], v3 offset:432
	ds_read_b32 v48, v19 offset:6912
	ds_read_b128 v[40:43], v3 offset:448
	ds_read_b32 v49, v19 offset:7168
	ds_read_b128 v[44:47], v3 offset:464
	ds_read_b32 v50, v19 offset:7424
	s_waitcnt lgkmcnt(10)
	v_fmac_f32_e32 v4, v20, v32
	v_fmac_f32_e32 v5, v21, v32
	v_fmac_f32_e32 v6, v22, v32
	v_fmac_f32_e32 v8, v23, v32
	s_waitcnt lgkmcnt(8)
	v_fmac_f32_e32 v4, v24, v33
	v_fmac_f32_e32 v5, v25, v33
	v_fmac_f32_e32 v6, v26, v33
	v_fmac_f32_e32 v8, v27, v33
	s_waitcnt lgkmcnt(6)
	v_fmac_f32_e32 v4, v28, v34
	v_fmac_f32_e32 v5, v29, v34
	v_fmac_f32_e32 v6, v30, v34
	v_fmac_f32_e32 v8, v31, v34
	ds_read_b128 v[20:23], v3 offset:480
	ds_read_b32 v32, v19 offset:7680
	ds_read_b128 v[24:27], v3 offset:496
	ds_read_b32 v33, v19 offset:7936
	ds_read_b128 v[28:31], v3 offset:512
	ds_read_b32 v34, v19 offset:8192
	s_waitcnt lgkmcnt(10)
	v_fmac_f32_e32 v4, v36, v48
	v_fmac_f32_e32 v5, v37, v48
	v_fmac_f32_e32 v6, v38, v48
	v_fmac_f32_e32 v8, v39, v48
	s_waitcnt lgkmcnt(8)
	v_fmac_f32_e32 v4, v40, v49
	v_fmac_f32_e32 v5, v41, v49
	v_fmac_f32_e32 v6, v42, v49
	v_fmac_f32_e32 v8, v43, v49
	s_waitcnt lgkmcnt(6)
	v_fmac_f32_e32 v4, v44, v50
	v_fmac_f32_e32 v5, v45, v50
	v_fmac_f32_e32 v6, v46, v50
	v_fmac_f32_e32 v8, v47, v50
	ds_read_b128 v[36:39], v3 offset:528
	ds_read_b32 v48, v19 offset:8448
	ds_read_b128 v[40:43], v3 offset:544
	ds_read_b32 v49, v19 offset:8704
	ds_read_b128 v[44:47], v3 offset:560
	ds_read_b32 v50, v19 offset:8960
	s_waitcnt lgkmcnt(10)
	v_fmac_f32_e32 v4, v20, v32
	v_fmac_f32_e32 v5, v21, v32
	v_fmac_f32_e32 v6, v22, v32
	v_fmac_f32_e32 v8, v23, v32
	s_waitcnt lgkmcnt(8)
	v_fmac_f32_e32 v4, v24, v33
	v_fmac_f32_e32 v5, v25, v33
	v_fmac_f32_e32 v6, v26, v33
	v_fmac_f32_e32 v8, v27, v33
	s_waitcnt lgkmcnt(6)
	v_fmac_f32_e32 v4, v28, v34
	v_fmac_f32_e32 v5, v29, v34
	v_fmac_f32_e32 v6, v30, v34
	v_fmac_f32_e32 v8, v31, v34
	ds_read_b128 v[20:23], v3 offset:576
	ds_read_b32 v32, v19 offset:9216
	ds_read_b128 v[24:27], v3 offset:592
	ds_read_b32 v33, v19 offset:9472
	ds_read_b128 v[28:31], v3 offset:608
	ds_read_b32 v34, v19 offset:9728
	s_waitcnt lgkmcnt(10)
	v_fmac_f32_e32 v4, v36, v48
	v_fmac_f32_e32 v5, v37, v48
	v_fmac_f32_e32 v6, v38, v48
	v_fmac_f32_e32 v8, v39, v48
	s_waitcnt lgkmcnt(8)
	v_fmac_f32_e32 v4, v40, v49
	v_fmac_f32_e32 v5, v41, v49
	v_fmac_f32_e32 v6, v42, v49
	v_fmac_f32_e32 v8, v43, v49
	s_waitcnt lgkmcnt(6)
	v_fmac_f32_e32 v4, v44, v50
	v_fmac_f32_e32 v5, v45, v50
	v_fmac_f32_e32 v6, v46, v50
	v_fmac_f32_e32 v8, v47, v50
	ds_read_b128 v[36:39], v3 offset:624
	ds_read_b32 v48, v19 offset:9984
	ds_read_b128 v[40:43], v3 offset:640
	ds_read_b32 v49, v19 offset:10240
	ds_read_b128 v[44:47], v3 offset:656
	ds_read_b32 v50, v19 offset:10496
	s_waitcnt lgkmcnt(10)
	v_fmac_f32_e32 v4, v20, v32
	v_fmac_f32_e32 v5, v21, v32
	v_fmac_f32_e32 v6, v22, v32
	v_fmac_f32_e32 v8, v23, v32
	s_waitcnt lgkmcnt(8)
	v_fmac_f32_e32 v4, v24, v33
	v_fmac_f32_e32 v5, v25, v33
	v_fmac_f32_e32 v6, v26, v33
	v_fmac_f32_e32 v8, v27, v33
	s_waitcnt lgkmcnt(6)
	v_fmac_f32_e32 v4, v28, v34
	v_fmac_f32_e32 v5, v29, v34
	v_fmac_f32_e32 v6, v30, v34
	v_fmac_f32_e32 v8, v31, v34
	ds_read_b128 v[20:23], v3 offset:672
	ds_read_b32 v32, v19 offset:10752
	ds_read_b128 v[24:27], v3 offset:688
	ds_read_b32 v33, v19 offset:11008
	ds_read_b128 v[28:31], v3 offset:704
	ds_read_b32 v34, v19 offset:11264
	s_waitcnt lgkmcnt(10)
	v_fmac_f32_e32 v4, v36, v48
	v_fmac_f32_e32 v5, v37, v48
	v_fmac_f32_e32 v6, v38, v48
	v_fmac_f32_e32 v8, v39, v48
	s_waitcnt lgkmcnt(8)
	v_fmac_f32_e32 v4, v40, v49
	v_fmac_f32_e32 v5, v41, v49
	v_fmac_f32_e32 v6, v42, v49
	v_fmac_f32_e32 v8, v43, v49
	s_waitcnt lgkmcnt(6)
	v_fmac_f32_e32 v4, v44, v50
	v_fmac_f32_e32 v5, v45, v50
	v_fmac_f32_e32 v6, v46, v50
	v_fmac_f32_e32 v8, v47, v50
	ds_read_b128 v[36:39], v3 offset:720
	ds_read_b32 v48, v19 offset:11520
	ds_read_b128 v[40:43], v3 offset:736
	ds_read_b32 v49, v19 offset:11776
	ds_read_b128 v[44:47], v3 offset:752
	ds_read_b32 v50, v19 offset:12032
	s_waitcnt lgkmcnt(10)
	v_fmac_f32_e32 v4, v20, v32
	v_fmac_f32_e32 v5, v21, v32
	v_fmac_f32_e32 v6, v22, v32
	v_fmac_f32_e32 v8, v23, v32
	s_waitcnt lgkmcnt(8)
	v_fmac_f32_e32 v4, v24, v33
	v_fmac_f32_e32 v5, v25, v33
	v_fmac_f32_e32 v6, v26, v33
	v_fmac_f32_e32 v8, v27, v33
	s_waitcnt lgkmcnt(6)
	v_fmac_f32_e32 v4, v28, v34
	v_fmac_f32_e32 v5, v29, v34
	v_fmac_f32_e32 v6, v30, v34
	v_fmac_f32_e32 v8, v31, v34
	ds_read_b128 v[20:23], v3 offset:768
	ds_read_b32 v32, v19 offset:12288
	ds_read_b128 v[24:27], v3 offset:784
	ds_read_b32 v33, v19 offset:12544
	ds_read_b128 v[28:31], v3 offset:800
	ds_read_b32 v34, v19 offset:12800
	s_waitcnt lgkmcnt(10)
	v_fmac_f32_e32 v4, v36, v48
	v_fmac_f32_e32 v5, v37, v48
	v_fmac_f32_e32 v6, v38, v48
	v_fmac_f32_e32 v8, v39, v48
	s_waitcnt lgkmcnt(8)
	v_fmac_f32_e32 v4, v40, v49
	v_fmac_f32_e32 v5, v41, v49
	v_fmac_f32_e32 v6, v42, v49
	v_fmac_f32_e32 v8, v43, v49
	s_waitcnt lgkmcnt(6)
	v_fmac_f32_e32 v4, v44, v50
	v_fmac_f32_e32 v5, v45, v50
	v_fmac_f32_e32 v6, v46, v50
	v_fmac_f32_e32 v8, v47, v50
	ds_read_b128 v[36:39], v3 offset:816
	ds_read_b32 v48, v19 offset:13056
	ds_read_b128 v[40:43], v3 offset:832
	ds_read_b32 v49, v19 offset:13312
	ds_read_b128 v[44:47], v3 offset:848
	ds_read_b32 v50, v19 offset:13568
	s_waitcnt lgkmcnt(10)
	v_fmac_f32_e32 v4, v20, v32
	v_fmac_f32_e32 v5, v21, v32
	v_fmac_f32_e32 v6, v22, v32
	v_fmac_f32_e32 v8, v23, v32
	s_waitcnt lgkmcnt(8)
	v_fmac_f32_e32 v4, v24, v33
	v_fmac_f32_e32 v5, v25, v33
	v_fmac_f32_e32 v6, v26, v33
	v_fmac_f32_e32 v8, v27, v33
	s_waitcnt lgkmcnt(6)
	v_fmac_f32_e32 v4, v28, v34
	v_fmac_f32_e32 v5, v29, v34
	v_fmac_f32_e32 v6, v30, v34
	v_fmac_f32_e32 v8, v31, v34
	ds_read_b128 v[20:23], v3 offset:864
	ds_read_b32 v32, v19 offset:13824
	ds_read_b128 v[24:27], v3 offset:880
	ds_read_b32 v33, v19 offset:14080
	ds_read_b128 v[28:31], v3 offset:896
	ds_read_b32 v34, v19 offset:14336
	s_waitcnt lgkmcnt(10)
	v_fmac_f32_e32 v4, v36, v48
	v_fmac_f32_e32 v5, v37, v48
	v_fmac_f32_e32 v6, v38, v48
	v_fmac_f32_e32 v8, v39, v48
	s_waitcnt lgkmcnt(8)
	v_fmac_f32_e32 v4, v40, v49
	v_fmac_f32_e32 v5, v41, v49
	v_fmac_f32_e32 v6, v42, v49
	v_fmac_f32_e32 v8, v43, v49
	s_waitcnt lgkmcnt(6)
	v_fmac_f32_e32 v4, v44, v50
	v_fmac_f32_e32 v5, v45, v50
	v_fmac_f32_e32 v6, v46, v50
	v_fmac_f32_e32 v8, v47, v50
	ds_read_b128 v[36:39], v3 offset:912
	ds_read_b32 v48, v19 offset:14592
	ds_read_b128 v[40:43], v3 offset:928
	ds_read_b32 v49, v19 offset:14848
	ds_read_b128 v[44:47], v3 offset:944
	ds_read_b32 v50, v19 offset:15104
	s_waitcnt lgkmcnt(10)
	v_fmac_f32_e32 v4, v20, v32
	v_fmac_f32_e32 v5, v21, v32
	v_fmac_f32_e32 v6, v22, v32
	v_fmac_f32_e32 v8, v23, v32
	s_waitcnt lgkmcnt(8)
	v_fmac_f32_e32 v4, v24, v33
	v_fmac_f32_e32 v5, v25, v33
	v_fmac_f32_e32 v6, v26, v33
	v_fmac_f32_e32 v8, v27, v33
	s_waitcnt lgkmcnt(6)
	v_fmac_f32_e32 v4, v28, v34
	v_fmac_f32_e32 v5, v29, v34
	v_fmac_f32_e32 v6, v30, v34
	v_fmac_f32_e32 v8, v31, v34
	ds_read_b128 v[20:23], v3 offset:960
	ds_read_b32 v32, v19 offset:15360
	ds_read_b128 v[24:27], v3 offset:976
	ds_read_b32 v33, v19 offset:15616
	ds_read_b128 v[28:31], v3 offset:992
	ds_read_b32 v34, v19 offset:15872
	s_waitcnt lgkmcnt(10)
	v_fmac_f32_e32 v4, v36, v48
	v_fmac_f32_e32 v5, v37, v48
	v_fmac_f32_e32 v6, v38, v48
	v_fmac_f32_e32 v8, v39, v48
	s_waitcnt lgkmcnt(8)
	v_fmac_f32_e32 v4, v40, v49
	v_fmac_f32_e32 v5, v41, v49
	v_fmac_f32_e32 v6, v42, v49
	v_fmac_f32_e32 v8, v43, v49
	s_waitcnt lgkmcnt(6)
	v_fmac_f32_e32 v4, v44, v50
	v_fmac_f32_e32 v5, v45, v50
	v_fmac_f32_e32 v6, v46, v50
	v_fmac_f32_e32 v8, v47, v50
	ds_read_b128 v[36:39], v3 offset:1008
	ds_read_b32 v48, v19 offset:16128
	ds_read_b128 v[40:43], v3 offset:1024
	ds_read_b32 v49, v19 offset:16384
	ds_read_b128 v[44:47], v3 offset:1040
	ds_read_b32 v50, v19 offset:16640
	s_waitcnt lgkmcnt(10)
	v_fmac_f32_e32 v4, v20, v32
	v_fmac_f32_e32 v5, v21, v32
	v_fmac_f32_e32 v6, v22, v32
	v_fmac_f32_e32 v8, v23, v32
	s_waitcnt lgkmcnt(8)
	v_fmac_f32_e32 v4, v24, v33
	v_fmac_f32_e32 v5, v25, v33
	v_fmac_f32_e32 v6, v26, v33
	v_fmac_f32_e32 v8, v27, v33
	s_waitcnt lgkmcnt(6)
	v_fmac_f32_e32 v4, v28, v34
	v_fmac_f32_e32 v5, v29, v34
	v_fmac_f32_e32 v6, v30, v34
	v_fmac_f32_e32 v8, v31, v34
	ds_read_b128 v[20:23], v3 offset:1056
	ds_read_b32 v32, v19 offset:16896
	ds_read_b128 v[24:27], v3 offset:1072
	ds_read_b32 v33, v19 offset:17152
	ds_read_b128 v[28:31], v3 offset:1088
	ds_read_b32 v34, v19 offset:17408
	s_waitcnt lgkmcnt(10)
	v_fmac_f32_e32 v4, v36, v48
	v_fmac_f32_e32 v5, v37, v48
	v_fmac_f32_e32 v6, v38, v48
	v_fmac_f32_e32 v8, v39, v48
	s_waitcnt lgkmcnt(8)
	v_fmac_f32_e32 v4, v40, v49
	v_fmac_f32_e32 v5, v41, v49
	v_fmac_f32_e32 v6, v42, v49
	v_fmac_f32_e32 v8, v43, v49
	s_waitcnt lgkmcnt(6)
	v_fmac_f32_e32 v4, v44, v50
	v_fmac_f32_e32 v5, v45, v50
	v_fmac_f32_e32 v6, v46, v50
	v_fmac_f32_e32 v8, v47, v50
	ds_read_b128 v[36:39], v3 offset:1104
	ds_read_b32 v48, v19 offset:17664
	ds_read_b128 v[40:43], v3 offset:1120
	ds_read_b32 v49, v19 offset:17920
	ds_read_b128 v[44:47], v3 offset:1136
	ds_read_b32 v50, v19 offset:18176
	s_waitcnt lgkmcnt(10)
	v_fmac_f32_e32 v4, v20, v32
	v_fmac_f32_e32 v5, v21, v32
	v_fmac_f32_e32 v6, v22, v32
	v_fmac_f32_e32 v8, v23, v32
	s_waitcnt lgkmcnt(8)
	v_fmac_f32_e32 v4, v24, v33
	v_fmac_f32_e32 v5, v25, v33
	v_fmac_f32_e32 v6, v26, v33
	v_fmac_f32_e32 v8, v27, v33
	s_waitcnt lgkmcnt(6)
	v_fmac_f32_e32 v4, v28, v34
	v_fmac_f32_e32 v5, v29, v34
	v_fmac_f32_e32 v6, v30, v34
	v_fmac_f32_e32 v8, v31, v34
	ds_read_b128 v[20:23], v3 offset:1152
	ds_read_b32 v32, v19 offset:18432
	ds_read_b128 v[24:27], v3 offset:1168
	ds_read_b32 v33, v19 offset:18688
	ds_read_b128 v[28:31], v3 offset:1184
	ds_read_b32 v34, v19 offset:18944
	s_waitcnt lgkmcnt(10)
	v_fmac_f32_e32 v4, v36, v48
	v_fmac_f32_e32 v5, v37, v48
	v_fmac_f32_e32 v6, v38, v48
	v_fmac_f32_e32 v8, v39, v48
	s_waitcnt lgkmcnt(8)
	v_fmac_f32_e32 v4, v40, v49
	v_fmac_f32_e32 v5, v41, v49
	v_fmac_f32_e32 v6, v42, v49
	v_fmac_f32_e32 v8, v43, v49
	s_waitcnt lgkmcnt(6)
	v_fmac_f32_e32 v4, v44, v50
	v_fmac_f32_e32 v5, v45, v50
	v_fmac_f32_e32 v6, v46, v50
	v_fmac_f32_e32 v8, v47, v50
	ds_read_b128 v[36:39], v3 offset:1200
	ds_read_b32 v48, v19 offset:19200
	ds_read_b128 v[40:43], v3 offset:1216
	ds_read_b32 v49, v19 offset:19456
	ds_read_b128 v[44:47], v3 offset:1232
	ds_read_b32 v50, v19 offset:19712
	s_waitcnt lgkmcnt(10)
	v_fmac_f32_e32 v4, v20, v32
	v_fmac_f32_e32 v5, v21, v32
	v_fmac_f32_e32 v6, v22, v32
	v_fmac_f32_e32 v8, v23, v32
	s_waitcnt lgkmcnt(8)
	v_fmac_f32_e32 v4, v24, v33
	v_fmac_f32_e32 v5, v25, v33
	v_fmac_f32_e32 v6, v26, v33
	v_fmac_f32_e32 v8, v27, v33
	s_waitcnt lgkmcnt(6)
	v_fmac_f32_e32 v4, v28, v34
	v_fmac_f32_e32 v5, v29, v34
	v_fmac_f32_e32 v6, v30, v34
	v_fmac_f32_e32 v8, v31, v34
	ds_read_b128 v[20:23], v3 offset:1248
	ds_read_b32 v32, v19 offset:19968
	ds_read_b128 v[24:27], v3 offset:1264
	ds_read_b32 v33, v19 offset:20224
	ds_read_b128 v[28:31], v3 offset:1280
	ds_read_b32 v34, v19 offset:20480
	s_waitcnt lgkmcnt(10)
	v_fmac_f32_e32 v4, v36, v48
	v_fmac_f32_e32 v5, v37, v48
	v_fmac_f32_e32 v6, v38, v48
	v_fmac_f32_e32 v8, v39, v48
	s_waitcnt lgkmcnt(8)
	v_fmac_f32_e32 v4, v40, v49
	v_fmac_f32_e32 v5, v41, v49
	v_fmac_f32_e32 v6, v42, v49
	v_fmac_f32_e32 v8, v43, v49
	s_waitcnt lgkmcnt(6)
	v_fmac_f32_e32 v4, v44, v50
	v_fmac_f32_e32 v5, v45, v50
	v_fmac_f32_e32 v6, v46, v50
	v_fmac_f32_e32 v8, v47, v50
	ds_read_b128 v[36:39], v3 offset:1296
	ds_read_b32 v48, v19 offset:20736
	ds_read_b128 v[40:43], v3 offset:1312
	ds_read_b32 v49, v19 offset:20992
	ds_read_b128 v[44:47], v3 offset:1328
	ds_read_b32 v50, v19 offset:21248
	s_waitcnt lgkmcnt(10)
	v_fmac_f32_e32 v4, v20, v32
	v_fmac_f32_e32 v5, v21, v32
	v_fmac_f32_e32 v6, v22, v32
	v_fmac_f32_e32 v8, v23, v32
	s_waitcnt lgkmcnt(8)
	v_fmac_f32_e32 v4, v24, v33
	v_fmac_f32_e32 v5, v25, v33
	v_fmac_f32_e32 v6, v26, v33
	v_fmac_f32_e32 v8, v27, v33
	s_waitcnt lgkmcnt(6)
	v_fmac_f32_e32 v4, v28, v34
	v_fmac_f32_e32 v5, v29, v34
	v_fmac_f32_e32 v6, v30, v34
	v_fmac_f32_e32 v8, v31, v34
	ds_read_b128 v[20:23], v3 offset:1344
	ds_read_b32 v32, v19 offset:21504
	ds_read_b128 v[24:27], v3 offset:1360
	ds_read_b32 v33, v19 offset:21760
	ds_read_b128 v[28:31], v3 offset:1376
	ds_read_b32 v34, v19 offset:22016
	s_waitcnt lgkmcnt(10)
	v_fmac_f32_e32 v4, v36, v48
	v_fmac_f32_e32 v5, v37, v48
	v_fmac_f32_e32 v6, v38, v48
	v_fmac_f32_e32 v8, v39, v48
	s_waitcnt lgkmcnt(8)
	v_fmac_f32_e32 v4, v40, v49
	v_fmac_f32_e32 v5, v41, v49
	v_fmac_f32_e32 v6, v42, v49
	v_fmac_f32_e32 v8, v43, v49
	s_waitcnt lgkmcnt(6)
	v_fmac_f32_e32 v4, v44, v50
	v_fmac_f32_e32 v5, v45, v50
	v_fmac_f32_e32 v6, v46, v50
	v_fmac_f32_e32 v8, v47, v50
	ds_read_b128 v[36:39], v3 offset:1392
	ds_read_b32 v48, v19 offset:22272
	ds_read_b128 v[40:43], v3 offset:1408
	ds_read_b32 v49, v19 offset:22528
	ds_read_b128 v[44:47], v3 offset:1424
	ds_read_b32 v50, v19 offset:22784
	s_waitcnt lgkmcnt(10)
	v_fmac_f32_e32 v4, v20, v32
	v_fmac_f32_e32 v5, v21, v32
	v_fmac_f32_e32 v6, v22, v32
	v_fmac_f32_e32 v8, v23, v32
	s_waitcnt lgkmcnt(8)
	v_fmac_f32_e32 v4, v24, v33
	v_fmac_f32_e32 v5, v25, v33
	v_fmac_f32_e32 v6, v26, v33
	v_fmac_f32_e32 v8, v27, v33
	s_waitcnt lgkmcnt(6)
	v_fmac_f32_e32 v4, v28, v34
	v_fmac_f32_e32 v5, v29, v34
	v_fmac_f32_e32 v6, v30, v34
	v_fmac_f32_e32 v8, v31, v34
	ds_read_b128 v[20:23], v3 offset:1440
	ds_read_b32 v32, v19 offset:23040
	ds_read_b128 v[24:27], v3 offset:1456
	ds_read_b32 v33, v19 offset:23296
	ds_read_b128 v[28:31], v3 offset:1472
	ds_read_b32 v34, v19 offset:23552
	s_waitcnt lgkmcnt(10)
	v_fmac_f32_e32 v4, v36, v48
	v_fmac_f32_e32 v5, v37, v48
	v_fmac_f32_e32 v6, v38, v48
	v_fmac_f32_e32 v8, v39, v48
	s_waitcnt lgkmcnt(8)
	v_fmac_f32_e32 v4, v40, v49
	v_fmac_f32_e32 v5, v41, v49
	v_fmac_f32_e32 v6, v42, v49
	v_fmac_f32_e32 v8, v43, v49
	s_waitcnt lgkmcnt(6)
	v_fmac_f32_e32 v4, v44, v50
	v_fmac_f32_e32 v5, v45, v50
	v_fmac_f32_e32 v6, v46, v50
	v_fmac_f32_e32 v8, v47, v50
	ds_read_b128 v[36:39], v3 offset:1488
	ds_read_b32 v48, v19 offset:23808
	ds_read_b128 v[40:43], v3 offset:1504
	ds_read_b32 v49, v19 offset:24064
	ds_read_b128 v[44:47], v3 offset:1520
	ds_read_b32 v50, v19 offset:24320
	s_waitcnt lgkmcnt(10)
	v_fmac_f32_e32 v4, v20, v32
	v_fmac_f32_e32 v5, v21, v32
	v_fmac_f32_e32 v6, v22, v32
	v_fmac_f32_e32 v8, v23, v32
	s_waitcnt lgkmcnt(8)
	v_fmac_f32_e32 v4, v24, v33
	v_fmac_f32_e32 v5, v25, v33
	v_fmac_f32_e32 v6, v26, v33
	v_fmac_f32_e32 v8, v27, v33
	s_waitcnt lgkmcnt(6)
	v_fmac_f32_e32 v4, v28, v34
	v_fmac_f32_e32 v5, v29, v34
	v_fmac_f32_e32 v6, v30, v34
	v_fmac_f32_e32 v8, v31, v34
	ds_read_b128 v[20:23], v3 offset:1536
	ds_read_b32 v32, v19 offset:24576
	ds_read_b128 v[24:27], v3 offset:1552
	ds_read_b32 v33, v19 offset:24832
	ds_read_b128 v[28:31], v3 offset:1568
	ds_read_b32 v34, v19 offset:25088
	s_waitcnt lgkmcnt(10)
	v_fmac_f32_e32 v4, v36, v48
	v_fmac_f32_e32 v5, v37, v48
	v_fmac_f32_e32 v6, v38, v48
	v_fmac_f32_e32 v8, v39, v48
	s_waitcnt lgkmcnt(8)
	v_fmac_f32_e32 v4, v40, v49
	v_fmac_f32_e32 v5, v41, v49
	v_fmac_f32_e32 v6, v42, v49
	v_fmac_f32_e32 v8, v43, v49
	s_waitcnt lgkmcnt(6)
	v_fmac_f32_e32 v4, v44, v50
	v_fmac_f32_e32 v5, v45, v50
	v_fmac_f32_e32 v6, v46, v50
	v_fmac_f32_e32 v8, v47, v50
	ds_read_b128 v[36:39], v3 offset:1584
	ds_read_b32 v48, v19 offset:25344
	ds_read_b128 v[40:43], v3 offset:1600
	ds_read_b32 v49, v19 offset:25600
	ds_read_b128 v[44:47], v3 offset:1616
	ds_read_b32 v50, v19 offset:25856
	s_waitcnt lgkmcnt(10)
	v_fmac_f32_e32 v4, v20, v32
	v_fmac_f32_e32 v5, v21, v32
	v_fmac_f32_e32 v6, v22, v32
	v_fmac_f32_e32 v8, v23, v32
	s_waitcnt lgkmcnt(8)
	v_fmac_f32_e32 v4, v24, v33
	v_fmac_f32_e32 v5, v25, v33
	v_fmac_f32_e32 v6, v26, v33
	v_fmac_f32_e32 v8, v27, v33
	s_waitcnt lgkmcnt(6)
	v_fmac_f32_e32 v4, v28, v34
	v_fmac_f32_e32 v5, v29, v34
	v_fmac_f32_e32 v6, v30, v34
	v_fmac_f32_e32 v8, v31, v34
	ds_read_b128 v[20:23], v3 offset:1632
	ds_read_b32 v32, v19 offset:26112
	ds_read_b128 v[24:27], v3 offset:1648
	ds_read_b32 v33, v19 offset:26368
	ds_read_b128 v[28:31], v3 offset:1664
	ds_read_b32 v34, v19 offset:26624
	s_waitcnt lgkmcnt(10)
	v_fmac_f32_e32 v4, v36, v48
	v_fmac_f32_e32 v5, v37, v48
	v_fmac_f32_e32 v6, v38, v48
	v_fmac_f32_e32 v8, v39, v48
	s_waitcnt lgkmcnt(8)
	v_fmac_f32_e32 v4, v40, v49
	v_fmac_f32_e32 v5, v41, v49
	v_fmac_f32_e32 v6, v42, v49
	v_fmac_f32_e32 v8, v43, v49
	s_waitcnt lgkmcnt(6)
	v_fmac_f32_e32 v4, v44, v50
	v_fmac_f32_e32 v5, v45, v50
	v_fmac_f32_e32 v6, v46, v50
	v_fmac_f32_e32 v8, v47, v50
	ds_read_b128 v[36:39], v3 offset:1680
	ds_read_b32 v48, v19 offset:26880
	ds_read_b128 v[40:43], v3 offset:1696
	ds_read_b32 v49, v19 offset:27136
	ds_read_b128 v[44:47], v3 offset:1712
	ds_read_b32 v50, v19 offset:27392
	s_waitcnt lgkmcnt(10)
	v_fmac_f32_e32 v4, v20, v32
	v_fmac_f32_e32 v5, v21, v32
	v_fmac_f32_e32 v6, v22, v32
	v_fmac_f32_e32 v8, v23, v32
	s_waitcnt lgkmcnt(8)
	v_fmac_f32_e32 v4, v24, v33
	v_fmac_f32_e32 v5, v25, v33
	v_fmac_f32_e32 v6, v26, v33
	v_fmac_f32_e32 v8, v27, v33
	s_waitcnt lgkmcnt(6)
	v_fmac_f32_e32 v4, v28, v34
	v_fmac_f32_e32 v5, v29, v34
	v_fmac_f32_e32 v6, v30, v34
	v_fmac_f32_e32 v8, v31, v34
	ds_read_b128 v[20:23], v3 offset:1728
	ds_read_b32 v32, v19 offset:27648
	ds_read_b128 v[24:27], v3 offset:1744
	ds_read_b32 v33, v19 offset:27904
	ds_read_b128 v[28:31], v3 offset:1760
	ds_read_b32 v34, v19 offset:28160
	s_waitcnt lgkmcnt(10)
	v_fmac_f32_e32 v4, v36, v48
	v_fmac_f32_e32 v5, v37, v48
	v_fmac_f32_e32 v6, v38, v48
	v_fmac_f32_e32 v8, v39, v48
	s_waitcnt lgkmcnt(8)
	v_fmac_f32_e32 v4, v40, v49
	v_fmac_f32_e32 v5, v41, v49
	v_fmac_f32_e32 v6, v42, v49
	v_fmac_f32_e32 v8, v43, v49
	s_waitcnt lgkmcnt(6)
	v_fmac_f32_e32 v4, v44, v50
	v_fmac_f32_e32 v5, v45, v50
	v_fmac_f32_e32 v6, v46, v50
	v_fmac_f32_e32 v8, v47, v50
	ds_read_b128 v[36:39], v3 offset:1776
	ds_read_b32 v48, v19 offset:28416
	ds_read_b128 v[40:43], v3 offset:1792
	ds_read_b32 v49, v19 offset:28672
	ds_read_b128 v[44:47], v3 offset:1808
	ds_read_b32 v50, v19 offset:28928
	s_waitcnt lgkmcnt(10)
	v_fmac_f32_e32 v4, v20, v32
	v_fmac_f32_e32 v5, v21, v32
	v_fmac_f32_e32 v6, v22, v32
	v_fmac_f32_e32 v8, v23, v32
	s_waitcnt lgkmcnt(8)
	v_fmac_f32_e32 v4, v24, v33
	v_fmac_f32_e32 v5, v25, v33
	v_fmac_f32_e32 v6, v26, v33
	v_fmac_f32_e32 v8, v27, v33
	s_waitcnt lgkmcnt(6)
	v_fmac_f32_e32 v4, v28, v34
	v_fmac_f32_e32 v5, v29, v34
	v_fmac_f32_e32 v6, v30, v34
	v_fmac_f32_e32 v8, v31, v34
	ds_read_b128 v[20:23], v3 offset:1824
	ds_read_b32 v32, v19 offset:29184
	ds_read_b128 v[24:27], v3 offset:1840
	ds_read_b32 v33, v19 offset:29440
	ds_read_b128 v[28:31], v3 offset:1856
	ds_read_b32 v34, v19 offset:29696
	s_waitcnt lgkmcnt(10)
	v_fmac_f32_e32 v4, v36, v48
	v_fmac_f32_e32 v5, v37, v48
	v_fmac_f32_e32 v6, v38, v48
	v_fmac_f32_e32 v8, v39, v48
	s_waitcnt lgkmcnt(8)
	v_fmac_f32_e32 v4, v40, v49
	v_fmac_f32_e32 v5, v41, v49
	v_fmac_f32_e32 v6, v42, v49
	v_fmac_f32_e32 v8, v43, v49
	s_waitcnt lgkmcnt(6)
	v_fmac_f32_e32 v4, v44, v50
	v_fmac_f32_e32 v5, v45, v50
	v_fmac_f32_e32 v6, v46, v50
	v_fmac_f32_e32 v8, v47, v50
	ds_read_b128 v[36:39], v3 offset:1872
	ds_read_b32 v48, v19 offset:29952
	ds_read_b128 v[40:43], v3 offset:1888
	ds_read_b32 v49, v19 offset:30208
	ds_read_b128 v[44:47], v3 offset:1904
	ds_read_b32 v50, v19 offset:30464
	s_waitcnt lgkmcnt(10)
	v_fmac_f32_e32 v4, v20, v32
	v_fmac_f32_e32 v5, v21, v32
	v_fmac_f32_e32 v6, v22, v32
	v_fmac_f32_e32 v8, v23, v32
	s_waitcnt lgkmcnt(8)
	v_fmac_f32_e32 v4, v24, v33
	v_fmac_f32_e32 v5, v25, v33
	v_fmac_f32_e32 v6, v26, v33
	v_fmac_f32_e32 v8, v27, v33
	s_waitcnt lgkmcnt(6)
	v_fmac_f32_e32 v4, v28, v34
	v_fmac_f32_e32 v5, v29, v34
	v_fmac_f32_e32 v6, v30, v34
	v_fmac_f32_e32 v8, v31, v34
	ds_read_b128 v[20:23], v3 offset:1920
	ds_read_b32 v32, v19 offset:30720
	ds_read_b128 v[24:27], v3 offset:1936
	ds_read_b32 v33, v19 offset:30976
	ds_read_b128 v[28:31], v3 offset:1952
	ds_read_b32 v34, v19 offset:31232
	s_waitcnt lgkmcnt(10)
	v_fmac_f32_e32 v4, v36, v48
	v_fmac_f32_e32 v5, v37, v48
	v_fmac_f32_e32 v6, v38, v48
	v_fmac_f32_e32 v8, v39, v48
	s_waitcnt lgkmcnt(8)
	v_fmac_f32_e32 v4, v40, v49
	v_fmac_f32_e32 v5, v41, v49
	v_fmac_f32_e32 v6, v42, v49
	v_fmac_f32_e32 v8, v43, v49
	s_waitcnt lgkmcnt(6)
	v_fmac_f32_e32 v4, v44, v50
	v_fmac_f32_e32 v5, v45, v50
	v_fmac_f32_e32 v6, v46, v50
	v_fmac_f32_e32 v8, v47, v50
	ds_read_b128 v[36:39], v3 offset:1968
	ds_read_b32 v48, v19 offset:31488
	ds_read_b128 v[40:43], v3 offset:1984
	ds_read_b32 v49, v19 offset:31744
	ds_read_b128 v[44:47], v3 offset:2000
	ds_read_b32 v50, v19 offset:32000
	s_waitcnt lgkmcnt(10)
	v_fmac_f32_e32 v4, v20, v32
	v_fmac_f32_e32 v5, v21, v32
	v_fmac_f32_e32 v6, v22, v32
	v_fmac_f32_e32 v8, v23, v32
	s_waitcnt lgkmcnt(8)
	v_fmac_f32_e32 v4, v24, v33
	v_fmac_f32_e32 v5, v25, v33
	v_fmac_f32_e32 v6, v26, v33
	v_fmac_f32_e32 v8, v27, v33
	s_waitcnt lgkmcnt(6)
	v_fmac_f32_e32 v4, v28, v34
	v_fmac_f32_e32 v5, v29, v34
	v_fmac_f32_e32 v6, v30, v34
	v_fmac_f32_e32 v8, v31, v34
	ds_read_b128 v[20:23], v3 offset:2016
	ds_read_b32 v32, v19 offset:32256
	ds_read_b128 v[24:27], v3 offset:2032
	ds_read_b32 v33, v19 offset:32512
	ds_read_b128 v[28:31], v3 offset:2048
	ds_read_b32 v34, v19 offset:32768
	s_waitcnt lgkmcnt(10)
	v_fmac_f32_e32 v4, v36, v48
	v_fmac_f32_e32 v5, v37, v48
	v_fmac_f32_e32 v6, v38, v48
	v_fmac_f32_e32 v8, v39, v48
	s_waitcnt lgkmcnt(8)
	v_fmac_f32_e32 v4, v40, v49
	v_fmac_f32_e32 v5, v41, v49
	v_fmac_f32_e32 v6, v42, v49
	v_fmac_f32_e32 v8, v43, v49
	s_waitcnt lgkmcnt(6)
	v_fmac_f32_e32 v4, v44, v50
	v_fmac_f32_e32 v5, v45, v50
	v_fmac_f32_e32 v6, v46, v50
	v_fmac_f32_e32 v8, v47, v50
	ds_read_b128 v[36:39], v3 offset:2064
	ds_read_b32 v48, v19 offset:33024
	ds_read_b128 v[40:43], v3 offset:2080
	ds_read_b32 v49, v19 offset:33280
	ds_read_b128 v[44:47], v3 offset:2096
	ds_read_b32 v50, v19 offset:33536
	s_waitcnt lgkmcnt(10)
	v_fmac_f32_e32 v4, v20, v32
	v_fmac_f32_e32 v5, v21, v32
	v_fmac_f32_e32 v6, v22, v32
	v_fmac_f32_e32 v8, v23, v32
	s_waitcnt lgkmcnt(8)
	v_fmac_f32_e32 v4, v24, v33
	v_fmac_f32_e32 v5, v25, v33
	v_fmac_f32_e32 v6, v26, v33
	v_fmac_f32_e32 v8, v27, v33
	s_waitcnt lgkmcnt(6)
	v_fmac_f32_e32 v4, v28, v34
	v_fmac_f32_e32 v5, v29, v34
	v_fmac_f32_e32 v6, v30, v34
	v_fmac_f32_e32 v8, v31, v34
	s_waitcnt lgkmcnt(4)
	v_fmac_f32_e32 v4, v36, v48
	v_fmac_f32_e32 v5, v37, v48
	v_fmac_f32_e32 v6, v38, v48
	v_fmac_f32_e32 v8, v39, v48
	s_waitcnt lgkmcnt(2)
	v_fmac_f32_e32 v4, v40, v49
	v_fmac_f32_e32 v5, v41, v49
	v_fmac_f32_e32 v6, v42, v49
	v_fmac_f32_e32 v8, v43, v49
	s_waitcnt lgkmcnt(0)
	v_fmac_f32_e32 v4, v44, v50
	v_fmac_f32_e32 v5, v45, v50
	v_fmac_f32_e32 v6, v46, v50
	v_fmac_f32_e32 v8, v47, v50
	s_add_u32 s42, s10, 0xd680000
	s_addc_u32 s43, s11, 0
	v_cvt_pk_bf16_f32 v4, v4, v4
	v_cvt_pk_bf16_f32 v5, v5, v5
	v_cvt_pk_bf16_f32 v6, v6, v6
	v_cvt_pk_bf16_f32 v8, v8, v8
	s_nop 0
	global_store_short v11, v4, s[42:43]
	global_store_short v11, v5, s[42:43] offset:2048
	global_store_short v12, v6, s[42:43]
	global_store_short v12, v8, s[42:43] offset:2048
	s_branch .LBB0_162
